# v20 + nt hint on prep phase f32 loads (weights, x) and on LN1 per-token loads (residual x, mixer output)
# speedup vs baseline: 1.0130x; 1.0062x over previous
.LBB0_22:
	s_or_b64 exec, exec, s[2:3]
	s_load_dwordx16 s[60:75], s[0:1], 0x80
	v_mov_b32_e32 v30, v128
	s_cmpk_gt_i32 s24, 0x27f
	s_cbranch_scc1 .LBB0_25
	v_ashrrev_i32_e32 v1, 4, v30
	s_movk_i32 s2, 0xa00
	v_add_u32_e32 v2, 16, v1
	v_mad_i64_i32 v[22:23], s[0:1], v2, s2, 0
	v_add_u32_e32 v2, 32, v1
	v_mad_i64_i32 v[24:25], s[0:1], v2, s2, 0
	v_add_u32_e32 v2, 48, v1
	v_mad_i64_i32 v[20:21], s[0:1], v1, s2, 0
	v_mad_i64_i32 v[26:27], s[0:1], v2, s2, 0
	s_mul_hi_i32 s0, s24, 0x66666667
	s_lshr_b32 s1, s0, 31
	s_ashr_i32 s0, s0, 8
	s_add_i32 s0, s0, s1
	s_mul_i32 s2, s0, 0xa00000
	s_mul_hi_i32 s1, s0, 0xa00000
	s_add_u32 s2, s40, s2
	s_mulk_i32 s0, 0xfd80
	s_addc_u32 s1, s41, s1
	s_add_i32 s0, s0, s24
	s_mul_hi_i32 s3, s0, 0x66666667
	s_lshr_b32 s4, s3, 31
	s_ashr_i32 s3, s3, 4
	s_add_i32 s3, s3, s4
	s_lshl_b32 s4, s3, 6
	s_mul_i32 s5, s3, 0xa0000
	s_mul_hi_i32 s4, s4, 0x2800
	s_add_u32 s2, s2, s5
	s_addc_u32 s4, s1, s4
	s_mul_i32 s1, s3, 0xffffffd8
	s_add_i32 s1, s1, s0
	s_lshl_b32 s0, s1, 6
	s_ashr_i32 s1, s0, 31
	s_lshl_b64 s[0:1], s[0:1], 2
	v_and_b32_e32 v28, 15, v30
	s_add_u32 s0, s2, s0
	v_mov_b32_e32 v19, 0
	s_addc_u32 s1, s4, s1
	v_lshlrev_b32_e32 v18, 4, v28
	v_lshl_add_u64 v[10:11], s[0:1], 0, v[18:19]
	v_lshl_add_u64 v[2:3], v[26:27], 2, v[10:11]
	v_lshl_add_u64 v[6:7], v[24:25], 2, v[10:11]
	v_lshl_add_u64 v[12:13], v[22:23], 2, v[10:11]
	v_lshl_add_u64 v[14:15], v[20:21], 2, v[10:11]
	global_load_dwordx4 v[2:5], v[2:3], off nt
	s_nop 0
	global_load_dwordx4 v[6:9], v[6:7], off nt
	s_nop 0
	global_load_dwordx4 v[10:13], v[12:13], off nt
	s_nop 0
	global_load_dwordx4 v[14:17], v[14:15], off nt
	v_lshlrev_b32_e32 v18, 2, v28
	v_mul_u32_u24_e32 v28, 0x120, v28
	v_lshlrev_b32_e32 v28, 1, v28
	v_lshl_add_u32 v1, v1, 1, v28
	v_lshlrev_b32_e32 v28, 3, v30
	v_and_b32_e32 v32, 56, v28
	v_lshlrev_b32_e32 v36, 1, v32
	v_ashrrev_i32_e32 v34, 3, v30
	s_movk_i32 s2, 0x90
	v_mad_u64_u32 v[28:29], s[0:1], v34, s2, v[36:37]
	v_add_u32_e32 v29, 0x100, v30
	v_ashrrev_i32_e32 v29, 3, v29
	v_mad_u64_u32 v[30:31], s[0:1], v29, s2, v[36:37]
	v_lshlrev_b32_e32 v18, 2, v18
	v_lshlrev_b32_e32 v32, 1, v32
	v_mov_b32_e32 v33, v19
	s_mov_b32 s0, s24
.LBB0_24:
	s_mul_hi_i32 s1, s0, 0x66666667
	s_lshr_b32 s2, s1, 31
	s_ashr_i32 s1, s1, 8
	s_add_i32 s1, s1, s2
	s_mul_i32 s2, s1, 0xfffffd80
	s_add_i32 s2, s0, s2
	s_mul_hi_i32 s2, s2, 0x66666667
	s_lshr_b32 s3, s2, 31
	s_ashr_i32 s2, s2, 4
	s_add_i32 s4, s0, s90
	s_add_i32 s5, s2, s3
	s_cmpk_lt_u32 s4, 0x280
	s_cselect_b32 s2, s4, s0
	s_mul_hi_i32 s3, s2, 0x66666667
	s_lshr_b32 s6, s3, 31
	s_ashr_i32 s3, s3, 8
	s_add_i32 s3, s3, s6
	s_mul_i32 s6, s3, 0xfffffd80
	s_add_i32 s6, s6, s2
	s_mul_hi_i32 s2, s6, 0x66666667
	s_lshr_b32 s8, s2, 31
	s_ashr_i32 s2, s2, 4
	s_add_i32 s2, s2, s8
	s_mul_i32 s8, s2, 0xffffffd8
	s_mul_hi_i32 s7, s3, 0xa00000
	s_mul_i32 s3, s3, 0xa00000
	s_add_i32 s8, s8, s6
	s_add_u32 s3, s40, s3
	s_mul_i32 s9, s2, 0xa0000
	s_addc_u32 s6, s41, s7
	s_lshl_b32 s2, s2, 6
	s_mul_hi_i32 s2, s2, 0x2800
	s_add_u32 s7, s3, s9
	s_addc_u32 s6, s6, s2
	s_lshl_b32 s2, s8, 6
	s_ashr_i32 s3, s2, 31
	s_lshl_b64 s[2:3], s[2:3], 2
	s_add_u32 s2, s7, s2
	s_addc_u32 s3, s6, s3
	v_lshl_add_u64 v[36:37], s[2:3], 0, v[18:19]
	v_lshl_add_u64 v[38:39], v[20:21], 2, v[36:37]
	v_lshl_add_u64 v[40:41], v[22:23], 2, v[36:37]
	v_lshl_add_u64 v[44:45], v[24:25], 2, v[36:37]
	v_lshl_add_u64 v[48:49], v[26:27], 2, v[36:37]
	global_load_dwordx4 v[36:39], v[38:39], off nt
	s_nop 0
	global_load_dwordx4 v[40:43], v[40:41], off nt
	s_nop 0
	global_load_dwordx4 v[44:47], v[44:45], off nt
	s_nop 0
	global_load_dwordx4 v[48:51], v[48:49], off nt
	s_mul_i32 s2, s1, 0x280
	s_mul_i32 s6, s5, 0xffffffd8
	s_sub_i32 s2, s6, s2
	s_mul_hi_i32 s3, s1, 0x500000
	s_mul_i32 s1, s1, 0x500000
	s_add_i32 s2, s0, s2
	s_add_u32 s1, s88, s1
	s_addc_u32 s6, s89, s3
	s_lshl_b32 s7, s2, 6
	s_lshl_b32 s2, s5, 6
	s_waitcnt vmcnt(4)
	v_cvt_pk_bf16_f32 v14, v14, s0
	v_cvt_pk_bf16_f32 v6, v6, s0
	v_cvt_pk_bf16_f32 v7, v7, s0
	v_cvt_pk_bf16_f32 v8, v8, s0
	v_cvt_pk_bf16_f32 v9, v9, s0
	v_cvt_pk_bf16_f32 v2, v2, s0
	v_cvt_pk_bf16_f32 v3, v3, s0
	v_cvt_pk_bf16_f32 v4, v4, s0
	v_cvt_pk_bf16_f32 v5, v5, s0
	s_ashr_i32 s3, s2, 31
	v_cvt_pk_bf16_f32 v15, v15, s0
	v_cvt_pk_bf16_f32 v16, v16, s0
	v_cvt_pk_bf16_f32 v17, v17, s0
	v_cvt_pk_bf16_f32 v10, v10, s0
	v_cvt_pk_bf16_f32 v11, v11, s0
	v_cvt_pk_bf16_f32 v12, v12, s0
	v_cvt_pk_bf16_f32 v13, v13, s0
	s_waitcnt lgkmcnt(0)
	s_barrier
	ds_write_b16 v1, v14
	ds_write_b16 v1, v15 offset:144
	ds_write_b16 v1, v16 offset:288
	ds_write_b16 v1, v17 offset:432
	ds_write_b16 v1, v10 offset:32
	ds_write_b16 v1, v11 offset:176
	ds_write_b16 v1, v12 offset:320
	ds_write_b16 v1, v13 offset:464
	ds_write_b16 v1, v6 offset:64
	ds_write_b16 v1, v7 offset:208
	ds_write_b16 v1, v8 offset:352
	ds_write_b16 v1, v9 offset:496
	ds_write_b16 v1, v2 offset:96
	ds_write_b16 v1, v3 offset:240
	ds_write_b16 v1, v4 offset:384
	ds_write_b16 v1, v5 offset:528
	s_waitcnt lgkmcnt(0)
	s_barrier
	ds_read_b128 v[2:5], v28
	ds_read_b128 v[6:9], v30
	s_lshl_b64 s[2:3], s[2:3], 1
	v_add_u32_e32 v10, s7, v34
	v_add_u32_e32 v12, s7, v29
	s_add_u32 s2, s1, s2
	v_ashrrev_i32_e32 v11, 31, v10
	v_ashrrev_i32_e32 v13, 31, v12
	s_addc_u32 s3, s6, s3
	v_lshlrev_b64 v[10:11], 11, v[10:11]
	v_lshlrev_b64 v[12:13], 11, v[12:13]
	v_lshl_add_u64 v[14:15], s[2:3], 0, v[32:33]
	v_lshl_add_u64 v[10:11], v[14:15], 0, v[10:11]
	v_lshl_add_u64 v[12:13], v[14:15], 0, v[12:13]
	s_mov_b32 s0, s4
	s_cmpk_lt_i32 s4, 0x280
	s_waitcnt lgkmcnt(1)
	global_store_dwordx4 v[10:11], v[2:5], off sc0 sc1
	s_waitcnt lgkmcnt(0)
	global_store_dwordx4 v[12:13], v[6:9], off sc0 sc1
	s_waitcnt vmcnt(5)
	v_mov_b64_e32 v[14:15], v[36:37]
	v_mov_b64_e32 v[16:17], v[38:39]
	s_waitcnt vmcnt(4)
	v_mov_b64_e32 v[10:11], v[40:41]
	v_mov_b64_e32 v[12:13], v[42:43]
	s_waitcnt vmcnt(3)
	v_mov_b64_e32 v[6:7], v[44:45]
	v_mov_b64_e32 v[8:9], v[46:47]
	s_waitcnt vmcnt(2)
	v_mov_b64_e32 v[2:3], v[48:49]
	v_mov_b64_e32 v[4:5], v[50:51]
	s_cbranch_scc1 .LBB0_24
.LBB0_25:
	s_add_u32 s10, s88, 0x500000
	s_addc_u32 s11, s89, 0
	v_mov_b32_e32 v30, v128
	s_cmpk_gt_i32 s24, 0x7f
	s_cbranch_scc1 .LBB0_28
	s_ashr_i32 s0, s24, 31
	s_lshr_b32 s0, s0, 25
	s_add_i32 s2, s24, s0
	s_ashr_i32 s0, s2, 7
	s_ashr_i32 s1, s0, 31
	v_readlane_b32 s44, v237, 5
	s_lshl_b64 s[0:1], s[0:1], 21
	v_readlane_b32 s52, v237, 13
	v_readlane_b32 s53, v237, 14
	s_add_u32 s3, s52, s0
	s_addc_u32 s4, s53, s1
	s_and_b32 s0, s2, 0xffffff80
	s_sub_i32 s2, s24, s0
	s_ashr_i32 s0, s2, 31
	s_lshr_b32 s0, s0, 28
	s_add_i32 s0, s2, s0
	s_ashr_i32 s5, s0, 4
	s_lshl_b32 s0, s5, 6
	s_ashr_i32 s1, s0, 31
	s_lshl_b64 s[0:1], s[0:1], 12
	s_add_u32 s3, s3, s0
	s_addc_u32 s4, s4, s1
	s_lshl_b32 s0, s5, 10
	s_lshl_b32 s1, s2, 6
	s_sub_i32 s0, s1, s0
	s_ashr_i32 s1, s0, 31
	v_ashrrev_i32_e32 v28, 4, v30
	s_lshl_b64 s[0:1], s[0:1], 2
	v_and_b32_e32 v1, 15, v30
	v_add_u32_e32 v22, 16, v28
	v_add_u32_e32 v24, 32, v28
	v_add_u32_e32 v26, 48, v28
	s_add_u32 s0, s3, s0
	v_mov_b32_e32 v19, 0
	v_ashrrev_i32_e32 v29, 31, v28
	v_ashrrev_i32_e32 v23, 31, v22
	v_ashrrev_i32_e32 v25, 31, v24
	v_ashrrev_i32_e32 v27, 31, v26
	s_addc_u32 s1, s4, s1
	v_lshlrev_b32_e32 v18, 4, v1
	v_lshl_add_u64 v[10:11], s[0:1], 0, v[18:19]
	v_lshlrev_b64 v[2:3], 12, v[26:27]
	v_lshlrev_b64 v[4:5], 12, v[24:25]
	v_lshlrev_b64 v[12:13], 12, v[22:23]
	v_lshlrev_b64 v[14:15], 12, v[28:29]
	v_lshl_add_u64 v[2:3], v[10:11], 0, v[2:3]
	v_lshl_add_u64 v[6:7], v[10:11], 0, v[4:5]
	v_lshl_add_u64 v[12:13], v[10:11], 0, v[12:13]
	v_lshl_add_u64 v[14:15], v[10:11], 0, v[14:15]
	global_load_dwordx4 v[2:5], v[2:3], off nt
	s_nop 0
	global_load_dwordx4 v[6:9], v[6:7], off nt
	s_nop 0
	global_load_dwordx4 v[10:13], v[12:13], off nt
	s_nop 0
	global_load_dwordx4 v[14:17], v[14:15], off nt
	v_lshlrev_b32_e32 v18, 2, v1
	v_mul_u32_u24_e32 v1, 0x120, v1
	v_lshlrev_b32_e32 v1, 1, v1
	v_lshlrev_b64 v[20:21], 10, v[28:29]
	v_lshl_add_u32 v1, v28, 1, v1
	v_lshlrev_b32_e32 v28, 3, v30
	v_and_b32_e32 v32, 56, v28
	v_lshlrev_b32_e32 v36, 1, v32
	v_ashrrev_i32_e32 v34, 3, v30
	s_movk_i32 s2, 0x90
	v_mad_u64_u32 v[28:29], s[0:1], v34, s2, v[36:37]
	v_add_u32_e32 v29, 0x100, v30
	v_ashrrev_i32_e32 v29, 3, v29
	v_mad_u64_u32 v[30:31], s[0:1], v29, s2, v[36:37]
	v_lshlrev_b64 v[22:23], 10, v[22:23]
	v_lshlrev_b64 v[24:25], 10, v[24:25]
	v_lshlrev_b64 v[26:27], 10, v[26:27]
	v_and_b32_e32 v31, 31, v34
	v_and_b32_e32 v35, 31, v29
	s_lshl_b32 s2, s24, 6
	s_lshl_b32 s3, s90, 6
	v_lshlrev_b32_e32 v18, 2, v18
	v_lshlrev_b32_e32 v32, 1, v32
	v_mov_b32_e32 v33, v19
	s_movk_i32 s4, 0x200
	v_mov_b32_e32 v36, 0xfffffe00
	s_mov_b32 s6, s24
	v_readlane_b32 s45, v237, 6
	v_readlane_b32 s46, v237, 7
	v_readlane_b32 s47, v237, 8
	v_readlane_b32 s48, v237, 9
	v_readlane_b32 s49, v237, 10
	v_readlane_b32 s50, v237, 11
	v_readlane_b32 s51, v237, 12
	v_readlane_b32 s54, v237, 15
	v_readlane_b32 s55, v237, 16
	v_readlane_b32 s56, v237, 17
	v_readlane_b32 s57, v237, 18
	v_readlane_b32 s58, v237, 19
	v_readlane_b32 s59, v237, 20
.LBB0_27:
	s_ashr_i32 s0, s6, 31
	s_waitcnt vmcnt(0)
	v_cvt_pk_bf16_f32 v37, v14, s0
	v_cvt_pk_bf16_f32 v42, v15, s0
	v_cvt_pk_bf16_f32 v43, v16, s0
	v_cvt_pk_bf16_f32 v44, v17, s0
	v_cvt_pk_bf16_f32 v45, v10, s0
	v_cvt_pk_bf16_f32 v46, v11, s0
	v_cvt_pk_bf16_f32 v47, v12, s0
	v_cvt_pk_bf16_f32 v48, v13, s0
	v_cvt_pk_bf16_f32 v49, v6, s0
	v_cvt_pk_bf16_f32 v50, v7, s0
	v_cvt_pk_bf16_f32 v51, v8, s0
	v_cvt_pk_bf16_f32 v52, v9, s0
	s_lshr_b32 s0, s0, 25
	s_add_i32 s1, s6, s0
	s_ashr_i32 s0, s1, 7
	s_and_b32 s1, s1, 0xffffff80
	s_sub_i32 s1, s6, s1
	s_ashr_i32 s7, s1, 31
	s_lshr_b32 s7, s7, 28
	s_add_i32 s1, s1, s7
	s_add_i32 s5, s6, s90
	s_ashr_i32 s14, s1, 4
	s_cmpk_lt_u32 s5, 0x80
	s_cselect_b32 s1, s5, s6
	s_ashr_i32 s6, s1, 31
	s_lshr_b32 s6, s6, 25
	s_add_i32 s7, s1, s6
	s_ashr_i32 s6, s7, 7
	s_and_b32 s7, s7, 0xffffff80
	s_sub_i32 s1, s1, s7
	s_ashr_i32 s8, s1, 31
	s_lshr_b32 s8, s8, 28
	s_ashr_i32 s7, s6, 31
	s_add_i32 s8, s1, s8
	s_lshl_b64 s[6:7], s[6:7], 21
	s_ashr_i32 s8, s8, 4
	s_add_u32 s9, s52, s6
	s_addc_u32 s15, s53, s7
	s_lshl_b32 s6, s8, 6
	s_ashr_i32 s7, s6, 31
	s_lshl_b64 s[6:7], s[6:7], 12
	s_add_u32 s9, s9, s6
	s_addc_u32 s15, s15, s7
	s_lshl_b32 s6, s8, 10
	s_lshl_b32 s1, s1, 6
	s_sub_i32 s6, s1, s6
	s_ashr_i32 s7, s6, 31
	s_lshl_b64 s[6:7], s[6:7], 2
	s_add_u32 s6, s9, s6
	s_addc_u32 s7, s15, s7
	v_lshl_add_u64 v[6:7], s[6:7], 0, v[18:19]
	v_lshl_add_u64 v[8:9], v[20:21], 2, v[6:7]
	v_lshl_add_u64 v[10:11], v[22:23], 2, v[6:7]
	v_lshl_add_u64 v[38:39], v[24:25], 2, v[6:7]
	v_lshl_add_u64 v[40:41], v[26:27], 2, v[6:7]
	global_load_dwordx4 v[14:17], v[8:9], off nt
	s_nop 0
	global_load_dwordx4 v[10:13], v[10:11], off nt
	s_nop 0
	global_load_dwordx4 v[6:9], v[38:39], off nt
	s_nop 0
	global_load_dwordx4 v[38:41], v[40:41], off nt
	s_ashr_i32 s1, s0, 31
	s_lshl_b64 s[8:9], s[0:1], 20
	s_add_u32 s1, s10, s8
	s_addc_u32 s7, s11, s9
	s_lshl_b32 s8, s14, 6
	s_ashr_i32 s9, s8, 31
	s_lshl_b32 s15, s14, 10
	s_lshl_b64 s[8:9], s[8:9], 1
	s_add_u32 s8, s1, s8
	s_addc_u32 s9, s7, s9
	s_lshl_b32 s7, s0, 13
	v_cvt_pk_bf16_f32 v2, v2, s0
	v_cvt_pk_bf16_f32 v3, v3, s0
	v_cvt_pk_bf16_f32 v4, v4, s0
	v_cvt_pk_bf16_f32 v5, v5, s0
	v_add_u32_e32 v53, s2, v34
	s_add_i32 s0, s15, s7
	v_add_u32_e32 v54, s2, v29
	s_waitcnt lgkmcnt(0)
	s_barrier
	ds_write_b16 v1, v37
	ds_write_b16 v1, v42 offset:144
	ds_write_b16 v1, v43 offset:288
	ds_write_b16 v1, v44 offset:432
	ds_write_b16 v1, v45 offset:32
	ds_write_b16 v1, v46 offset:176
	ds_write_b16 v1, v47 offset:320
	ds_write_b16 v1, v48 offset:464
	ds_write_b16 v1, v49 offset:64
	ds_write_b16 v1, v50 offset:208
	ds_write_b16 v1, v51 offset:352
	ds_write_b16 v1, v52 offset:496
	ds_write_b16 v1, v2 offset:96
	ds_write_b16 v1, v3 offset:240
	ds_write_b16 v1, v4 offset:384
	ds_write_b16 v1, v5 offset:528
	v_subrev_u32_e32 v37, s0, v53
	v_subrev_u32_e32 v48, s0, v54
	v_cmp_gt_i32_e32 vcc, s4, v37
	v_cmp_gt_i32_e64 s[0:1], s4, v48
	s_waitcnt lgkmcnt(0)
	v_cndmask_b32_e64 v37, v36, 0, vcc
	v_cndmask_b32_e64 v48, v36, 0, s[0:1]
	v_subrev_u32_e32 v37, s15, v37
	v_subrev_u32_e32 v48, s15, v48
	v_subrev_u32_e32 v37, s7, v37
	v_subrev_u32_e32 v48, s7, v48
	v_add_lshl_u32 v37, v53, v37, 1
	s_barrier
	ds_read_b128 v[2:5], v28
	ds_read_b128 v[42:45], v30
	v_cndmask_b32_e64 v49, 32, 0, vcc
	v_add_lshl_u32 v48, v54, v48, 1
	v_and_b32_e32 v37, 0xffffffc0, v37
	v_cndmask_b32_e64 v50, 32, 0, s[0:1]
	v_and_b32_e32 v51, 0xffffffc0, v48
	v_or3_b32 v48, v49, v31, v37
	v_or3_b32 v50, v50, v35, v51
	v_ashrrev_i32_e32 v49, 31, v48
	v_lshl_add_u64 v[46:47], s[8:9], 0, v[32:33]
	v_ashrrev_i32_e32 v51, 31, v50
	v_lshlrev_b64 v[48:49], 10, v[48:49]
	s_add_i32 s2, s2, s3
	v_lshlrev_b64 v[50:51], 10, v[50:51]
	v_lshl_add_u64 v[48:49], v[46:47], 0, v[48:49]
	s_mov_b32 s6, s5
	s_cmpk_lt_i32 s5, 0x80
	v_lshl_add_u64 v[46:47], v[46:47], 0, v[50:51]
	s_waitcnt lgkmcnt(1)
	global_store_dwordx4 v[48:49], v[2:5], off sc0 sc1
	s_waitcnt lgkmcnt(0)
	global_store_dwordx4 v[46:47], v[42:45], off sc0 sc1
	s_waitcnt vmcnt(2)
	v_mov_b64_e32 v[2:3], v[38:39]
	v_mov_b64_e32 v[4:5], v[40:41]
	s_cbranch_scc1 .LBB0_27
.LBB0_28:
	s_add_u32 s8, s88, 0x600000
	s_addc_u32 s9, s89, 0
	s_cmpk_lt_i32 s24, 0x100
	v_mov_b32_e32 v30, v128
	s_cselect_b64 s[0:1], -1, 0
	s_cmpk_gt_i32 s24, 0xff
	s_cbranch_scc1 .LBB0_31
	s_ashr_i32 s2, s24, 31
	s_lshr_b32 s2, s2, 24
	s_add_i32 s4, s24, s2
	s_ashr_i32 s2, s4, 8
	v_readlane_b32 s44, v237, 5
	s_ashr_i32 s3, s2, 31
	v_readlane_b32 s54, v237, 15
	v_readlane_b32 s55, v237, 16
	s_lshl_b64 s[2:3], s[2:3], 22
	s_mov_b64 s[26:27], s[54:55]
	s_add_u32 s5, s26, s2
	s_addc_u32 s6, s27, s3
	s_and_b32 s2, s4, 0xffffff00
	s_sub_i32 s4, s24, s2
	s_ashr_i32 s2, s4, 31
	s_lshr_b32 s2, s2, 28
	s_add_i32 s2, s4, s2
	s_ashr_i32 s7, s2, 4
	s_lshl_b32 s2, s7, 6
	s_ashr_i32 s3, s2, 31
	s_lshl_b64 s[2:3], s[2:3], 12
	s_add_u32 s5, s5, s2
	s_addc_u32 s6, s6, s3
	s_lshl_b32 s2, s7, 10
	s_lshl_b32 s3, s4, 6
	s_sub_i32 s2, s3, s2
	s_ashr_i32 s3, s2, 31
	v_ashrrev_i32_e32 v28, 4, v30
	s_lshl_b64 s[2:3], s[2:3], 2
	v_and_b32_e32 v1, 15, v30
	v_add_u32_e32 v22, 16, v28
	v_add_u32_e32 v24, 32, v28
	v_add_u32_e32 v26, 48, v28
	s_add_u32 s2, s5, s2
	v_mov_b32_e32 v19, 0
	v_ashrrev_i32_e32 v29, 31, v28
	v_ashrrev_i32_e32 v23, 31, v22
	v_ashrrev_i32_e32 v25, 31, v24
	v_ashrrev_i32_e32 v27, 31, v26
	s_addc_u32 s3, s6, s3
	v_lshlrev_b32_e32 v18, 4, v1
	v_lshl_add_u64 v[10:11], s[2:3], 0, v[18:19]
	v_lshlrev_b64 v[2:3], 12, v[26:27]
	v_lshlrev_b64 v[4:5], 12, v[24:25]
	v_lshlrev_b64 v[12:13], 12, v[22:23]
	v_lshlrev_b64 v[14:15], 12, v[28:29]
	v_lshl_add_u64 v[2:3], v[10:11], 0, v[2:3]
	v_lshl_add_u64 v[6:7], v[10:11], 0, v[4:5]
	v_lshl_add_u64 v[12:13], v[10:11], 0, v[12:13]
	v_lshl_add_u64 v[14:15], v[10:11], 0, v[14:15]
	global_load_dwordx4 v[2:5], v[2:3], off nt
	s_nop 0
	global_load_dwordx4 v[6:9], v[6:7], off nt
	s_nop 0
	global_load_dwordx4 v[10:13], v[12:13], off nt
	s_nop 0
	global_load_dwordx4 v[14:17], v[14:15], off nt
	v_lshlrev_b32_e32 v18, 2, v1
	v_mul_u32_u24_e32 v1, 0x120, v1
	v_lshlrev_b32_e32 v1, 1, v1
	v_lshlrev_b64 v[20:21], 10, v[28:29]
	v_lshl_add_u32 v1, v28, 1, v1
	v_lshlrev_b32_e32 v28, 3, v30
	v_and_b32_e32 v32, 56, v28
	v_lshlrev_b32_e32 v36, 1, v32
	v_ashrrev_i32_e32 v34, 3, v30
	s_movk_i32 s4, 0x90
	v_mad_u64_u32 v[28:29], s[2:3], v34, s4, v[36:37]
	v_add_u32_e32 v29, 0x100, v30
	v_ashrrev_i32_e32 v29, 3, v29
	v_lshlrev_b64 v[22:23], 10, v[22:23]
	v_lshlrev_b64 v[24:25], 10, v[24:25]
	v_lshlrev_b64 v[26:27], 10, v[26:27]
	v_mad_u64_u32 v[30:31], s[2:3], v29, s4, v[36:37]
	s_lshl_b32 s4, s24, 6
	s_lshl_b32 s5, s90, 6
	v_lshlrev_b32_e32 v18, 2, v18
	v_lshlrev_b32_e32 v32, 1, v32
	v_mov_b32_e32 v33, v19
	s_mov_b32 s6, s24
	v_readlane_b32 s45, v237, 6
	v_readlane_b32 s46, v237, 7
	v_readlane_b32 s47, v237, 8
	v_readlane_b32 s48, v237, 9
	v_readlane_b32 s49, v237, 10
	v_readlane_b32 s50, v237, 11
	v_readlane_b32 s51, v237, 12
	v_readlane_b32 s52, v237, 13
	v_readlane_b32 s53, v237, 14
	v_readlane_b32 s56, v237, 17
	v_readlane_b32 s57, v237, 18
	v_readlane_b32 s58, v237, 19
	v_readlane_b32 s59, v237, 20
.LBB0_30:
	s_ashr_i32 s2, s6, 31
	s_lshr_b32 s2, s2, 24
	s_add_i32 s3, s6, s2
	s_ashr_i32 s2, s3, 8
	s_and_b32 s3, s3, 0xffffff00
	s_sub_i32 s3, s6, s3
	s_ashr_i32 s7, s3, 31
	s_lshr_b32 s7, s7, 28
	s_add_i32 s3, s3, s7
	s_add_i32 s16, s6, s90
	s_ashr_i32 s17, s3, 4
	s_cmpk_lt_u32 s16, 0x100
	s_cselect_b32 s3, s16, s6
	s_ashr_i32 s6, s3, 31
	s_lshr_b32 s6, s6, 24
	s_add_i32 s7, s3, s6
	s_ashr_i32 s6, s7, 8
	s_and_b32 s7, s7, 0xffffff00
	s_sub_i32 s3, s3, s7
	s_ashr_i32 s14, s3, 31
	s_lshr_b32 s14, s14, 28
	s_ashr_i32 s7, s6, 31
	s_add_i32 s14, s3, s14
	s_lshl_b64 s[6:7], s[6:7], 22
	s_ashr_i32 s14, s14, 4
	s_add_u32 s15, s26, s6
	s_addc_u32 s18, s27, s7
	s_lshl_b32 s6, s14, 6
	s_ashr_i32 s7, s6, 31
	s_lshl_b64 s[6:7], s[6:7], 12
	s_add_u32 s15, s15, s6
	s_addc_u32 s18, s18, s7
	s_lshl_b32 s6, s14, 10
	s_lshl_b32 s3, s3, 6
	s_sub_i32 s6, s3, s6
	s_ashr_i32 s7, s6, 31
	s_lshl_b64 s[6:7], s[6:7], 2
	s_add_u32 s6, s15, s6
	s_addc_u32 s7, s18, s7
	v_lshl_add_u64 v[36:37], s[6:7], 0, v[18:19]
	v_lshl_add_u64 v[38:39], v[20:21], 2, v[36:37]
	v_lshl_add_u64 v[40:41], v[22:23], 2, v[36:37]
	v_lshl_add_u64 v[44:45], v[24:25], 2, v[36:37]
	v_lshl_add_u64 v[48:49], v[26:27], 2, v[36:37]
	global_load_dwordx4 v[36:39], v[38:39], off nt
	s_nop 0
	global_load_dwordx4 v[40:43], v[40:41], off nt
	s_nop 0
	global_load_dwordx4 v[44:47], v[44:45], off nt
	s_nop 0
	global_load_dwordx4 v[48:51], v[48:49], off nt
	s_ashr_i32 s3, s2, 31
	s_lshl_b64 s[14:15], s[2:3], 21
	s_add_u32 s3, s8, s14
	s_addc_u32 s7, s9, s15
	s_lshl_b32 s14, s17, 6
	s_ashr_i32 s15, s14, 31
	s_lshl_b64 s[14:15], s[14:15], 1
	s_add_u32 s14, s3, s14
	s_addc_u32 s15, s7, s15
	s_lshl_b32 s3, s17, 10
	s_lshl_b32 s2, s2, 14
	s_waitcnt vmcnt(4)
	v_cvt_pk_bf16_f32 v14, v14, s0
	v_cvt_pk_bf16_f32 v6, v6, s0
	v_cvt_pk_bf16_f32 v7, v7, s0
	v_cvt_pk_bf16_f32 v8, v8, s0
	v_cvt_pk_bf16_f32 v9, v9, s0
	v_cvt_pk_bf16_f32 v2, v2, s0
	v_cvt_pk_bf16_f32 v3, v3, s0
	v_cvt_pk_bf16_f32 v4, v4, s0
	v_cvt_pk_bf16_f32 v5, v5, s0
	s_add_i32 s3, s3, s2
	v_cvt_pk_bf16_f32 v15, v15, s0
	v_cvt_pk_bf16_f32 v16, v16, s0
	v_cvt_pk_bf16_f32 v17, v17, s0
	v_cvt_pk_bf16_f32 v10, v10, s0
	v_cvt_pk_bf16_f32 v11, v11, s0
	v_cvt_pk_bf16_f32 v12, v12, s0
	v_cvt_pk_bf16_f32 v13, v13, s0
	s_waitcnt lgkmcnt(0)
	s_barrier
	ds_write_b16 v1, v14
	ds_write_b16 v1, v15 offset:144
	ds_write_b16 v1, v16 offset:288
	ds_write_b16 v1, v17 offset:432
	ds_write_b16 v1, v10 offset:32
	ds_write_b16 v1, v11 offset:176
	ds_write_b16 v1, v12 offset:320
	ds_write_b16 v1, v13 offset:464
	ds_write_b16 v1, v6 offset:64
	ds_write_b16 v1, v7 offset:208
	ds_write_b16 v1, v8 offset:352
	ds_write_b16 v1, v9 offset:496
	ds_write_b16 v1, v2 offset:96
	ds_write_b16 v1, v3 offset:240
	ds_write_b16 v1, v4 offset:384
	ds_write_b16 v1, v5 offset:528
	s_waitcnt lgkmcnt(0)
	s_barrier
	ds_read_b128 v[2:5], v28
	ds_read_b128 v[6:9], v30
	s_sub_i32 s2, s4, s3
	v_add_u32_e32 v12, s2, v34
	v_add_u32_e32 v14, s2, v29
	v_ashrrev_i32_e32 v13, 31, v12
	v_ashrrev_i32_e32 v15, 31, v14
	v_lshl_add_u64 v[10:11], s[14:15], 0, v[32:33]
	v_lshlrev_b64 v[12:13], 11, v[12:13]
	v_lshlrev_b64 v[14:15], 11, v[14:15]
	s_add_i32 s4, s4, s5
	v_lshl_add_u64 v[12:13], v[10:11], 0, v[12:13]
	v_lshl_add_u64 v[10:11], v[10:11], 0, v[14:15]
	s_mov_b32 s6, s16
	s_cmpk_lt_i32 s16, 0x100
	s_waitcnt lgkmcnt(1)
	global_store_dwordx4 v[12:13], v[2:5], off sc0 sc1
	s_waitcnt lgkmcnt(0)
	global_store_dwordx4 v[10:11], v[6:9], off sc0 sc1
	s_waitcnt vmcnt(5)
	v_mov_b64_e32 v[14:15], v[36:37]
	v_mov_b64_e32 v[16:17], v[38:39]
	s_waitcnt vmcnt(4)
	v_mov_b64_e32 v[10:11], v[40:41]
	v_mov_b64_e32 v[12:13], v[42:43]
	s_waitcnt vmcnt(3)
	v_mov_b64_e32 v[6:7], v[44:45]
	v_mov_b64_e32 v[8:9], v[46:47]
	s_waitcnt vmcnt(2)
	v_mov_b64_e32 v[2:3], v[48:49]
	v_mov_b64_e32 v[4:5], v[50:51]
	s_cbranch_scc1 .LBB0_30
.LBB0_31:
	s_add_u32 s2, s88, 0x800000
	s_addc_u32 s3, s89, 0
	v_writelane_b32 v237, s2, 21
	v_mov_b32_e32 v30, v128
	s_cmpk_gt_i32 s24, 0x17f
	v_writelane_b32 v237, s3, 22
	s_cbranch_scc1 .LBB0_34
	v_ashrrev_i32_e32 v1, 4, v30
	s_movk_i32 s4, 0x600
	v_add_u32_e32 v2, 16, v1
	v_mad_i64_i32 v[22:23], s[2:3], v2, s4, 0
	v_add_u32_e32 v2, 32, v1
	v_mad_i64_i32 v[24:25], s[2:3], v2, s4, 0
	v_add_u32_e32 v2, 48, v1
	v_mad_i64_i32 v[20:21], s[2:3], v1, s4, 0
	v_mad_i64_i32 v[26:27], s[2:3], v2, s4, 0
	s_mul_hi_i32 s2, s24, 0x2aaaaaab
	s_lshr_b32 s3, s2, 31
	s_ashr_i32 s2, s2, 6
	v_readlane_b32 s44, v237, 5
	s_add_i32 s2, s2, s3
	v_readlane_b32 s56, v237, 17
	v_readlane_b32 s57, v237, 18
	s_mul_i32 s4, s2, 0x600000
	v_readlane_b32 s58, v237, 19
	v_readlane_b32 s59, v237, 20
	s_mov_b64 s[28:29], s[56:57]
	s_mul_hi_i32 s3, s2, 0x600000
	s_add_u32 s4, s28, s4
	s_mulk_i32 s2, 0xfe80
	s_addc_u32 s3, s29, s3
	s_add_i32 s2, s2, s24
	s_mul_hi_i32 s5, s2, 0x2aaaaaab
	s_lshr_b32 s6, s5, 31
	s_ashr_i32 s5, s5, 2
	s_add_i32 s5, s5, s6
	s_lshl_b32 s6, s5, 6
	s_mul_i32 s7, s5, 0x60000
	s_mul_hi_i32 s6, s6, 0x1800
	s_add_u32 s4, s4, s7
	s_addc_u32 s6, s3, s6
	s_mul_i32 s3, s5, 0xffffffe8
	s_add_i32 s3, s3, s2
	s_lshl_b32 s2, s3, 6
	s_ashr_i32 s3, s2, 31
	s_lshl_b64 s[2:3], s[2:3], 2
	v_and_b32_e32 v28, 15, v30
	s_add_u32 s2, s4, s2
	v_mov_b32_e32 v19, 0
	s_addc_u32 s3, s6, s3
	v_lshlrev_b32_e32 v18, 4, v28
	v_lshl_add_u64 v[10:11], s[2:3], 0, v[18:19]
	v_lshl_add_u64 v[2:3], v[26:27], 2, v[10:11]
	v_lshl_add_u64 v[6:7], v[24:25], 2, v[10:11]
	v_lshl_add_u64 v[12:13], v[22:23], 2, v[10:11]
	v_lshl_add_u64 v[14:15], v[20:21], 2, v[10:11]
	global_load_dwordx4 v[2:5], v[2:3], off nt
	s_nop 0
	global_load_dwordx4 v[6:9], v[6:7], off nt
	s_nop 0
	global_load_dwordx4 v[10:13], v[12:13], off nt
	s_nop 0
	global_load_dwordx4 v[14:17], v[14:15], off nt
	v_lshlrev_b32_e32 v18, 2, v28
	v_mul_u32_u24_e32 v28, 0x120, v28
	v_lshlrev_b32_e32 v28, 1, v28
	v_lshl_add_u32 v1, v1, 1, v28
	v_lshlrev_b32_e32 v28, 3, v30
	v_and_b32_e32 v32, 56, v28
	v_lshlrev_b32_e32 v36, 1, v32
	v_ashrrev_i32_e32 v34, 3, v30
	s_movk_i32 s4, 0x90
	v_mad_u64_u32 v[28:29], s[2:3], v34, s4, v[36:37]
	v_add_u32_e32 v29, 0x100, v30
	v_ashrrev_i32_e32 v29, 3, v29
	v_mad_u64_u32 v[30:31], s[2:3], v29, s4, v[36:37]
	v_readlane_b32 s18, v237, 21
	v_lshlrev_b32_e32 v18, 2, v18
	v_lshlrev_b32_e32 v32, 1, v32
	v_mov_b32_e32 v33, v19
	s_mov_b32 s2, s24
	v_readlane_b32 s19, v237, 22
	v_readlane_b32 s45, v237, 6
	v_readlane_b32 s46, v237, 7
	v_readlane_b32 s47, v237, 8
	v_readlane_b32 s48, v237, 9
	v_readlane_b32 s49, v237, 10
	v_readlane_b32 s50, v237, 11
	v_readlane_b32 s51, v237, 12
	v_readlane_b32 s52, v237, 13
	v_readlane_b32 s53, v237, 14
	v_readlane_b32 s54, v237, 15
	v_readlane_b32 s55, v237, 16
	s_mov_b64 s[30:31], s[58:59]
.LBB0_33:
	s_mul_hi_i32 s3, s2, 0x2aaaaaab
	s_lshr_b32 s4, s3, 31
	s_ashr_i32 s3, s3, 6
	s_add_i32 s3, s3, s4
	s_mul_i32 s4, s3, 0xfffffe80
	s_add_i32 s4, s2, s4
	s_mul_hi_i32 s4, s4, 0x2aaaaaab
	s_lshr_b32 s5, s4, 31
	s_ashr_i32 s4, s4, 2
	s_add_i32 s6, s2, s90
	s_add_i32 s7, s4, s5
	s_cmpk_lt_u32 s6, 0x180
	s_cselect_b32 s4, s6, s2
	s_mul_hi_i32 s5, s4, 0x2aaaaaab
	s_lshr_b32 s14, s5, 31
	s_ashr_i32 s5, s5, 6
	s_add_i32 s5, s5, s14
	s_mul_i32 s14, s5, 0xfffffe80
	s_add_i32 s14, s14, s4
	s_mul_hi_i32 s4, s14, 0x2aaaaaab
	s_lshr_b32 s16, s4, 31
	s_ashr_i32 s4, s4, 2
	s_add_i32 s4, s4, s16
	s_mul_i32 s16, s4, 0xffffffe8
	s_mul_hi_i32 s15, s5, 0x600000
	s_mul_i32 s5, s5, 0x600000
	s_add_i32 s16, s16, s14
	s_add_u32 s5, s28, s5
	s_mul_i32 s17, s4, 0x60000
	s_addc_u32 s14, s29, s15
	s_lshl_b32 s4, s4, 6
	s_mul_hi_i32 s4, s4, 0x1800
	s_add_u32 s15, s5, s17
	s_addc_u32 s14, s14, s4
	s_lshl_b32 s4, s16, 6
	s_ashr_i32 s5, s4, 31
	s_lshl_b64 s[4:5], s[4:5], 2
	s_add_u32 s4, s15, s4
	s_addc_u32 s5, s14, s5
	v_lshl_add_u64 v[36:37], s[4:5], 0, v[18:19]
	v_lshl_add_u64 v[38:39], v[20:21], 2, v[36:37]
	v_lshl_add_u64 v[40:41], v[22:23], 2, v[36:37]
	v_lshl_add_u64 v[44:45], v[24:25], 2, v[36:37]
	v_lshl_add_u64 v[48:49], v[26:27], 2, v[36:37]
	global_load_dwordx4 v[36:39], v[38:39], off nt
	s_nop 0
	global_load_dwordx4 v[40:43], v[40:41], off nt
	s_nop 0
	global_load_dwordx4 v[44:47], v[44:45], off nt
	s_nop 0
	global_load_dwordx4 v[48:51], v[48:49], off nt
	s_mul_i32 s4, s3, 0x180
	s_mul_i32 s14, s7, 0xffffffe8
	s_sub_i32 s4, s14, s4
	s_mul_hi_i32 s5, s3, 0x300000
	s_mul_i32 s3, s3, 0x300000
	s_add_i32 s4, s2, s4
	s_add_u32 s3, s18, s3
	s_addc_u32 s14, s19, s5
	s_lshl_b32 s15, s4, 6
	s_lshl_b32 s4, s7, 6
	s_waitcnt vmcnt(4)
	v_cvt_pk_bf16_f32 v14, v14, s0
	v_cvt_pk_bf16_f32 v6, v6, s0
	v_cvt_pk_bf16_f32 v7, v7, s0
	v_cvt_pk_bf16_f32 v8, v8, s0
	v_cvt_pk_bf16_f32 v9, v9, s0
	v_cvt_pk_bf16_f32 v2, v2, s0
	v_cvt_pk_bf16_f32 v3, v3, s0
	v_cvt_pk_bf16_f32 v4, v4, s0
	v_cvt_pk_bf16_f32 v5, v5, s0
	s_ashr_i32 s5, s4, 31
	v_cvt_pk_bf16_f32 v15, v15, s0
	v_cvt_pk_bf16_f32 v16, v16, s0
	v_cvt_pk_bf16_f32 v17, v17, s0
	v_cvt_pk_bf16_f32 v10, v10, s0
	v_cvt_pk_bf16_f32 v11, v11, s0
	v_cvt_pk_bf16_f32 v12, v12, s0
	v_cvt_pk_bf16_f32 v13, v13, s0
	s_waitcnt lgkmcnt(0)
	s_barrier
	ds_write_b16 v1, v14
	ds_write_b16 v1, v15 offset:144
	ds_write_b16 v1, v16 offset:288
	ds_write_b16 v1, v17 offset:432
	ds_write_b16 v1, v10 offset:32
	ds_write_b16 v1, v11 offset:176
	ds_write_b16 v1, v12 offset:320
	ds_write_b16 v1, v13 offset:464
	ds_write_b16 v1, v6 offset:64
	ds_write_b16 v1, v7 offset:208
	ds_write_b16 v1, v8 offset:352
	ds_write_b16 v1, v9 offset:496
	ds_write_b16 v1, v2 offset:96
	ds_write_b16 v1, v3 offset:240
	ds_write_b16 v1, v4 offset:384
	ds_write_b16 v1, v5 offset:528
	s_waitcnt lgkmcnt(0)
	s_barrier
	ds_read_b128 v[2:5], v28
	ds_read_b128 v[6:9], v30
	s_lshl_b64 s[4:5], s[4:5], 1
	v_add_u32_e32 v10, s15, v34
	v_add_u32_e32 v12, s15, v29
	s_add_u32 s4, s3, s4
	v_ashrrev_i32_e32 v11, 31, v10
	v_ashrrev_i32_e32 v13, 31, v12
	s_addc_u32 s5, s14, s5
	v_lshlrev_b64 v[10:11], 11, v[10:11]
	v_lshlrev_b64 v[12:13], 11, v[12:13]
	v_lshl_add_u64 v[14:15], s[4:5], 0, v[32:33]
	v_lshl_add_u64 v[10:11], v[14:15], 0, v[10:11]
	v_lshl_add_u64 v[12:13], v[14:15], 0, v[12:13]
	s_mov_b32 s2, s6
	s_cmpk_lt_i32 s6, 0x180
	s_waitcnt lgkmcnt(1)
	global_store_dwordx4 v[10:11], v[2:5], off sc0 sc1
	s_waitcnt lgkmcnt(0)
	global_store_dwordx4 v[12:13], v[6:9], off sc0 sc1
	s_waitcnt vmcnt(5)
	v_mov_b64_e32 v[14:15], v[36:37]
	v_mov_b64_e32 v[16:17], v[38:39]
	s_waitcnt vmcnt(4)
	v_mov_b64_e32 v[10:11], v[40:41]
	v_mov_b64_e32 v[12:13], v[42:43]
	s_waitcnt vmcnt(3)
	v_mov_b64_e32 v[6:7], v[44:45]
	v_mov_b64_e32 v[8:9], v[46:47]
	s_waitcnt vmcnt(2)
	v_mov_b64_e32 v[2:3], v[48:49]
	v_mov_b64_e32 v[4:5], v[50:51]
	s_cbranch_scc1 .LBB0_33
.LBB0_34:
	s_add_u32 s2, s88, 0xb00000
	s_addc_u32 s3, s89, 0
	v_writelane_b32 v237, s2, 23
	v_mov_b32_e32 v30, v128
	s_andn2_b64 vcc, exec, s[0:1]
	v_writelane_b32 v237, s3, 24
	s_cbranch_vccnz .LBB0_37
	s_ashr_i32 s0, s24, 31
	s_lshr_b32 s0, s0, 24
	s_add_i32 s2, s24, s0
	s_ashr_i32 s0, s2, 8
	s_ashr_i32 s1, s0, 31
	s_lshl_b64 s[0:1], s[0:1], 22
	s_waitcnt lgkmcnt(0)
	s_add_u32 s3, s60, s0
	s_addc_u32 s4, s61, s1
	s_and_b32 s0, s2, 0xffffff00
	s_sub_i32 s2, s24, s0
	s_ashr_i32 s0, s2, 31
	s_lshr_b32 s0, s0, 28
	s_add_i32 s0, s2, s0
	s_ashr_i32 s5, s0, 4
	s_lshl_b32 s0, s5, 6
	s_ashr_i32 s1, s0, 31
	s_lshl_b64 s[0:1], s[0:1], 12
	s_add_u32 s3, s3, s0
	s_addc_u32 s4, s4, s1
	s_lshl_b32 s0, s5, 10
	s_lshl_b32 s1, s2, 6
	s_sub_i32 s0, s1, s0
	s_ashr_i32 s1, s0, 31
	v_ashrrev_i32_e32 v28, 4, v30
	s_lshl_b64 s[0:1], s[0:1], 2
	v_and_b32_e32 v1, 15, v30
	v_add_u32_e32 v22, 16, v28
	v_add_u32_e32 v24, 32, v28
	v_add_u32_e32 v26, 48, v28
	s_add_u32 s0, s3, s0
	v_mov_b32_e32 v19, 0
	v_ashrrev_i32_e32 v29, 31, v28
	v_ashrrev_i32_e32 v23, 31, v22
	v_ashrrev_i32_e32 v25, 31, v24
	v_ashrrev_i32_e32 v27, 31, v26
	s_addc_u32 s1, s4, s1
	v_lshlrev_b32_e32 v18, 4, v1
	v_lshl_add_u64 v[10:11], s[0:1], 0, v[18:19]
	v_lshlrev_b64 v[2:3], 12, v[26:27]
	v_lshlrev_b64 v[4:5], 12, v[24:25]
	v_lshlrev_b64 v[12:13], 12, v[22:23]
	v_lshlrev_b64 v[14:15], 12, v[28:29]
	v_lshl_add_u64 v[2:3], v[10:11], 0, v[2:3]
	v_lshl_add_u64 v[6:7], v[10:11], 0, v[4:5]
	v_lshl_add_u64 v[12:13], v[10:11], 0, v[12:13]
	v_lshl_add_u64 v[14:15], v[10:11], 0, v[14:15]
	global_load_dwordx4 v[2:5], v[2:3], off nt
	s_nop 0
	global_load_dwordx4 v[6:9], v[6:7], off nt
	s_nop 0
	global_load_dwordx4 v[10:13], v[12:13], off nt
	s_nop 0
	global_load_dwordx4 v[14:17], v[14:15], off nt
	v_lshlrev_b32_e32 v18, 2, v1
	v_mul_u32_u24_e32 v1, 0x120, v1
	v_lshlrev_b32_e32 v1, 1, v1
	v_lshlrev_b64 v[20:21], 10, v[28:29]
	v_lshl_add_u32 v1, v28, 1, v1
	v_lshlrev_b32_e32 v28, 3, v30
	v_and_b32_e32 v32, 56, v28
	v_lshlrev_b32_e32 v36, 1, v32
	v_ashrrev_i32_e32 v34, 3, v30
	s_movk_i32 s2, 0x90
	v_mad_u64_u32 v[28:29], s[0:1], v34, s2, v[36:37]
	v_add_u32_e32 v29, 0x100, v30
	v_ashrrev_i32_e32 v29, 3, v29
	v_readlane_b32 s18, v237, 23
	v_lshlrev_b64 v[22:23], 10, v[22:23]
	v_lshlrev_b64 v[24:25], 10, v[24:25]
	v_lshlrev_b64 v[26:27], 10, v[26:27]
	v_mad_u64_u32 v[30:31], s[0:1], v29, s2, v[36:37]
	s_lshl_b32 s2, s24, 6
	s_lshl_b32 s3, s90, 6
	v_lshlrev_b32_e32 v18, 2, v18
	v_lshlrev_b32_e32 v32, 1, v32
	v_mov_b32_e32 v33, v19
	s_mov_b32 s4, s24
	v_readlane_b32 s19, v237, 24
.LBB0_36:
	s_ashr_i32 s0, s4, 31
	s_lshr_b32 s0, s0, 24
	s_add_i32 s1, s4, s0
	s_ashr_i32 s0, s1, 8
	s_and_b32 s1, s1, 0xffffff00
	s_sub_i32 s1, s4, s1
	s_ashr_i32 s5, s1, 31
	s_lshr_b32 s5, s5, 28
	s_add_i32 s1, s1, s5
	s_add_i32 s14, s4, s90
	s_ashr_i32 s15, s1, 4
	s_cmpk_lt_u32 s14, 0x100
	s_cselect_b32 s1, s14, s4
	s_ashr_i32 s4, s1, 31
	s_lshr_b32 s4, s4, 24
	s_add_i32 s5, s1, s4
	s_ashr_i32 s4, s5, 8
	s_and_b32 s5, s5, 0xffffff00
	s_sub_i32 s1, s1, s5
	s_ashr_i32 s6, s1, 31
	s_lshr_b32 s6, s6, 28
	s_ashr_i32 s5, s4, 31
	s_add_i32 s6, s1, s6
	s_lshl_b64 s[4:5], s[4:5], 22
	s_ashr_i32 s6, s6, 4
	s_add_u32 s7, s60, s4
	s_addc_u32 s16, s61, s5
	s_lshl_b32 s4, s6, 6
	s_ashr_i32 s5, s4, 31
	s_lshl_b64 s[4:5], s[4:5], 12
	s_add_u32 s7, s7, s4
	s_addc_u32 s16, s16, s5
	s_lshl_b32 s4, s6, 10
	s_lshl_b32 s1, s1, 6
	s_sub_i32 s4, s1, s4
	s_ashr_i32 s5, s4, 31
	s_lshl_b64 s[4:5], s[4:5], 2
	s_add_u32 s4, s7, s4
	s_addc_u32 s5, s16, s5
	v_lshl_add_u64 v[36:37], s[4:5], 0, v[18:19]
	v_lshl_add_u64 v[38:39], v[20:21], 2, v[36:37]
	v_lshl_add_u64 v[40:41], v[22:23], 2, v[36:37]
	v_lshl_add_u64 v[44:45], v[24:25], 2, v[36:37]
	v_lshl_add_u64 v[48:49], v[26:27], 2, v[36:37]
	global_load_dwordx4 v[36:39], v[38:39], off nt
	s_nop 0
	global_load_dwordx4 v[40:43], v[40:41], off nt
	s_nop 0
	global_load_dwordx4 v[44:47], v[44:45], off nt
	s_nop 0
	global_load_dwordx4 v[48:51], v[48:49], off nt
	s_ashr_i32 s1, s0, 31
	s_lshl_b64 s[6:7], s[0:1], 21
	s_add_u32 s1, s18, s6
	s_addc_u32 s5, s19, s7
	s_lshl_b32 s6, s15, 6
	s_ashr_i32 s7, s6, 31
	s_lshl_b64 s[6:7], s[6:7], 1
	s_add_u32 s6, s1, s6
	s_waitcnt vmcnt(4)
	v_cvt_pk_bf16_f32 v14, v14, s0
	v_cvt_pk_bf16_f32 v15, v15, s0
	v_cvt_pk_bf16_f32 v16, v16, s0
	v_cvt_pk_bf16_f32 v17, v17, s0
	v_cvt_pk_bf16_f32 v10, v10, s0
	v_cvt_pk_bf16_f32 v11, v11, s0
	v_cvt_pk_bf16_f32 v12, v12, s0
	v_cvt_pk_bf16_f32 v13, v13, s0
	v_cvt_pk_bf16_f32 v6, v6, s0
	v_cvt_pk_bf16_f32 v7, v7, s0
	v_cvt_pk_bf16_f32 v8, v8, s0
	v_cvt_pk_bf16_f32 v9, v9, s0
	v_cvt_pk_bf16_f32 v2, v2, s0
	v_cvt_pk_bf16_f32 v3, v3, s0
	v_cvt_pk_bf16_f32 v4, v4, s0
	v_cvt_pk_bf16_f32 v5, v5, s0
	s_addc_u32 s7, s5, s7
	s_lshl_b32 s1, s15, 10
	s_lshl_b32 s0, s0, 14
	s_add_i32 s1, s1, s0
	s_barrier
	ds_write_b16 v1, v14
	ds_write_b16 v1, v15 offset:144
	ds_write_b16 v1, v16 offset:288
	ds_write_b16 v1, v17 offset:432
	ds_write_b16 v1, v10 offset:32
	ds_write_b16 v1, v11 offset:176
	ds_write_b16 v1, v12 offset:320
	ds_write_b16 v1, v13 offset:464
	ds_write_b16 v1, v6 offset:64
	ds_write_b16 v1, v7 offset:208
	ds_write_b16 v1, v8 offset:352
	ds_write_b16 v1, v9 offset:496
	ds_write_b16 v1, v2 offset:96
	ds_write_b16 v1, v3 offset:240
	ds_write_b16 v1, v4 offset:384
	ds_write_b16 v1, v5 offset:528
	s_waitcnt lgkmcnt(0)
	s_barrier
	ds_read_b128 v[2:5], v28
	ds_read_b128 v[6:9], v30
	s_sub_i32 s0, s2, s1
	v_add_u32_e32 v12, s0, v34
	v_add_u32_e32 v14, s0, v29
	v_ashrrev_i32_e32 v13, 31, v12
	v_ashrrev_i32_e32 v15, 31, v14
	v_lshl_add_u64 v[10:11], s[6:7], 0, v[32:33]
	v_lshlrev_b64 v[12:13], 11, v[12:13]
	v_lshlrev_b64 v[14:15], 11, v[14:15]
	s_add_i32 s2, s2, s3
	v_lshl_add_u64 v[12:13], v[10:11], 0, v[12:13]
	v_lshl_add_u64 v[10:11], v[10:11], 0, v[14:15]
	s_mov_b32 s4, s14
	s_cmpk_lt_i32 s14, 0x100
	s_waitcnt lgkmcnt(1)
	global_store_dwordx4 v[12:13], v[2:5], off sc0 sc1
	s_waitcnt lgkmcnt(0)
	global_store_dwordx4 v[10:11], v[6:9], off sc0 sc1
	s_waitcnt vmcnt(5)
	v_mov_b64_e32 v[14:15], v[36:37]
	v_mov_b64_e32 v[16:17], v[38:39]
	s_waitcnt vmcnt(4)
	v_mov_b64_e32 v[10:11], v[40:41]
	v_mov_b64_e32 v[12:13], v[42:43]
	s_waitcnt vmcnt(3)
	v_mov_b64_e32 v[6:7], v[44:45]
	v_mov_b64_e32 v[8:9], v[46:47]
	s_waitcnt vmcnt(2)
	v_mov_b64_e32 v[2:3], v[48:49]
	v_mov_b64_e32 v[4:5], v[50:51]
	s_cbranch_scc1 .LBB0_36
.LBB0_37:
	s_add_u32 s20, s88, 0xd00000
	s_addc_u32 s21, s89, 0
	s_cmpk_lt_i32 s24, 0x1000
	v_mov_b32_e32 v30, v128
	s_cselect_b64 s[2:3], -1, 0
	s_cmpk_gt_i32 s24, 0xfff
	s_cbranch_scc1 .LBB0_40
	s_ashr_i32 s0, s24, 31
	s_lshr_b32 s0, s0, 25
	s_add_i32 s4, s24, s0
	s_ashr_i32 s0, s4, 7
	s_ashr_i32 s1, s0, 31
	s_lshl_b64 s[0:1], s[0:1], 21
	s_waitcnt lgkmcnt(0)
	s_add_u32 s5, s74, s0
	s_addc_u32 s6, s75, s1
	s_and_b32 s0, s4, 0xffffff80
	s_sub_i32 s4, s24, s0
	s_ashr_i32 s0, s4, 31
	s_lshr_b32 s0, s0, 29
	s_add_i32 s0, s4, s0
	s_ashr_i32 s7, s0, 3
	s_lshl_b32 s0, s7, 6
	s_ashr_i32 s1, s0, 31
	s_lshl_b64 s[0:1], s[0:1], 11
	s_add_u32 s5, s5, s0
	s_addc_u32 s6, s6, s1
	s_lshl_b32 s0, s7, 9
	s_lshl_b32 s1, s4, 6
	s_sub_i32 s0, s1, s0
	s_ashr_i32 s1, s0, 31
	v_ashrrev_i32_e32 v28, 4, v30
	s_lshl_b64 s[0:1], s[0:1], 2
	v_and_b32_e32 v1, 15, v30
	v_add_u32_e32 v22, 16, v28
	v_add_u32_e32 v24, 32, v28
	v_add_u32_e32 v26, 48, v28
	s_add_u32 s0, s5, s0
	v_mov_b32_e32 v19, 0
	v_ashrrev_i32_e32 v29, 31, v28
	v_ashrrev_i32_e32 v23, 31, v22
	v_ashrrev_i32_e32 v25, 31, v24
	v_ashrrev_i32_e32 v27, 31, v26
	s_addc_u32 s1, s6, s1
	v_lshlrev_b32_e32 v18, 4, v1
	v_lshl_add_u64 v[10:11], s[0:1], 0, v[18:19]
	v_lshlrev_b64 v[2:3], 11, v[26:27]
	v_lshlrev_b64 v[4:5], 11, v[24:25]
	v_lshlrev_b64 v[12:13], 11, v[22:23]
	v_lshlrev_b64 v[14:15], 11, v[28:29]
	v_lshl_add_u64 v[2:3], v[10:11], 0, v[2:3]
	v_lshl_add_u64 v[6:7], v[10:11], 0, v[4:5]
	v_lshl_add_u64 v[12:13], v[10:11], 0, v[12:13]
	v_lshl_add_u64 v[14:15], v[10:11], 0, v[14:15]
	global_load_dwordx4 v[2:5], v[2:3], off nt
	s_nop 0
	global_load_dwordx4 v[6:9], v[6:7], off nt
	s_nop 0
	global_load_dwordx4 v[10:13], v[12:13], off nt
	s_nop 0
	global_load_dwordx4 v[14:17], v[14:15], off nt
	v_lshlrev_b32_e32 v18, 2, v1
	v_mul_u32_u24_e32 v1, 0x120, v1
	v_lshlrev_b32_e32 v1, 1, v1
	v_lshlrev_b64 v[20:21], 9, v[28:29]
	v_lshl_add_u32 v1, v28, 1, v1
	v_lshlrev_b32_e32 v28, 3, v30
	v_and_b32_e32 v32, 56, v28
	v_lshlrev_b32_e32 v36, 1, v32
	v_ashrrev_i32_e32 v34, 3, v30
	s_movk_i32 s5, 0x90
	v_mad_u64_u32 v[28:29], s[0:1], v34, s5, v[36:37]
	v_add_u32_e32 v29, 0x100, v30
	v_ashrrev_i32_e32 v29, 3, v29
	v_mad_u64_u32 v[30:31], s[0:1], v29, s5, v[36:37]
	v_lshlrev_b64 v[22:23], 9, v[22:23]
	v_lshlrev_b64 v[24:25], 9, v[24:25]
	v_lshlrev_b64 v[26:27], 9, v[26:27]
	s_movk_i32 s4, 0x100
	v_and_b32_e32 v31, 31, v34
	v_and_b32_e32 v35, 31, v29
	s_lshl_b32 s5, s24, 6
	s_lshl_b32 s6, s90, 6
	v_lshlrev_b32_e32 v18, 2, v18
	v_lshlrev_b32_e32 v32, 1, v32
	v_mov_b32_e32 v33, v19
	v_mov_b32_e32 v36, 0xffffff00
	s_mov_b32 s14, s24
.LBB0_39:
	s_ashr_i32 s0, s14, 31
	s_waitcnt vmcnt(0)
	v_cvt_pk_bf16_f32 v37, v14, s0
	v_cvt_pk_bf16_f32 v42, v15, s0
	v_cvt_pk_bf16_f32 v43, v16, s0
	v_cvt_pk_bf16_f32 v44, v17, s0
	v_cvt_pk_bf16_f32 v45, v10, s0
	v_cvt_pk_bf16_f32 v46, v11, s0
	v_cvt_pk_bf16_f32 v47, v12, s0
	v_cvt_pk_bf16_f32 v48, v13, s0
	v_cvt_pk_bf16_f32 v49, v6, s0
	v_cvt_pk_bf16_f32 v50, v7, s0
	v_cvt_pk_bf16_f32 v51, v8, s0
	v_cvt_pk_bf16_f32 v52, v9, s0
	s_lshr_b32 s0, s0, 25
	s_add_i32 s1, s14, s0
	s_ashr_i32 s0, s1, 7
	s_and_b32 s1, s1, 0xffffff80
	s_sub_i32 s1, s14, s1
	s_ashr_i32 s15, s1, 31
	s_lshr_b32 s15, s15, 29
	s_add_i32 s1, s1, s15
	s_add_i32 s7, s14, s90
	s_ashr_i32 s18, s1, 3
	s_cmpk_lt_u32 s7, 0x1000
	s_cselect_b32 s1, s7, s14
	s_ashr_i32 s14, s1, 31
	s_lshr_b32 s14, s14, 25
	s_add_i32 s15, s1, s14
	s_ashr_i32 s14, s15, 7
	s_and_b32 s15, s15, 0xffffff80
	s_sub_i32 s1, s1, s15
	s_ashr_i32 s16, s1, 31
	s_lshr_b32 s16, s16, 29
	s_ashr_i32 s15, s14, 31
	s_add_i32 s16, s1, s16
	s_lshl_b64 s[14:15], s[14:15], 21
	s_ashr_i32 s16, s16, 3
	s_add_u32 s17, s74, s14
	s_addc_u32 s19, s75, s15
	s_lshl_b32 s14, s16, 6
	s_ashr_i32 s15, s14, 31
	s_lshl_b64 s[14:15], s[14:15], 11
	s_add_u32 s17, s17, s14
	s_addc_u32 s19, s19, s15
	s_lshl_b32 s14, s16, 9
	s_lshl_b32 s1, s1, 6
	s_sub_i32 s14, s1, s14
	s_ashr_i32 s15, s14, 31
	s_lshl_b64 s[14:15], s[14:15], 2
	s_add_u32 s14, s17, s14
	s_addc_u32 s15, s19, s15
	v_lshl_add_u64 v[6:7], s[14:15], 0, v[18:19]
	v_lshl_add_u64 v[8:9], v[20:21], 2, v[6:7]
	v_lshl_add_u64 v[10:11], v[22:23], 2, v[6:7]
	v_lshl_add_u64 v[38:39], v[24:25], 2, v[6:7]
	v_lshl_add_u64 v[40:41], v[26:27], 2, v[6:7]
	global_load_dwordx4 v[14:17], v[8:9], off nt
	s_nop 0
	global_load_dwordx4 v[10:13], v[10:11], off nt
	s_nop 0
	global_load_dwordx4 v[6:9], v[38:39], off nt
	s_nop 0
	global_load_dwordx4 v[38:41], v[40:41], off nt
	s_ashr_i32 s1, s0, 31
	s_lshl_b64 s[16:17], s[0:1], 20
	s_add_u32 s1, s20, s16
	s_addc_u32 s15, s21, s17
	s_lshl_b32 s16, s18, 6
	s_ashr_i32 s17, s16, 31
	s_lshl_b32 s19, s18, 9
	s_lshl_b64 s[16:17], s[16:17], 1
	s_add_u32 s16, s1, s16
	s_addc_u32 s17, s15, s17
	s_lshl_b32 s15, s0, 13
	v_cvt_pk_bf16_f32 v2, v2, s0
	v_cvt_pk_bf16_f32 v3, v3, s0
	v_cvt_pk_bf16_f32 v4, v4, s0
	v_cvt_pk_bf16_f32 v5, v5, s0
	v_add_u32_e32 v53, s5, v34
	s_add_i32 s0, s19, s15
	v_add_u32_e32 v54, s5, v29
	s_barrier
	ds_write_b16 v1, v37
	ds_write_b16 v1, v42 offset:144
	ds_write_b16 v1, v43 offset:288
	ds_write_b16 v1, v44 offset:432
	ds_write_b16 v1, v45 offset:32
	ds_write_b16 v1, v46 offset:176
	ds_write_b16 v1, v47 offset:320
	ds_write_b16 v1, v48 offset:464
	ds_write_b16 v1, v49 offset:64
	ds_write_b16 v1, v50 offset:208
	ds_write_b16 v1, v51 offset:352
	ds_write_b16 v1, v52 offset:496
	ds_write_b16 v1, v2 offset:96
	ds_write_b16 v1, v3 offset:240
	ds_write_b16 v1, v4 offset:384
	ds_write_b16 v1, v5 offset:528
	v_subrev_u32_e32 v37, s0, v53
	v_subrev_u32_e32 v48, s0, v54
	v_cmp_gt_i32_e32 vcc, s4, v37
	v_cmp_gt_i32_e64 s[0:1], s4, v48
	s_waitcnt lgkmcnt(0)
	v_cndmask_b32_e64 v37, v36, 0, vcc
	v_cndmask_b32_e64 v48, v36, 0, s[0:1]
	v_subrev_u32_e32 v37, s19, v37
	v_subrev_u32_e32 v48, s19, v48
	v_subrev_u32_e32 v37, s15, v37
	v_subrev_u32_e32 v48, s15, v48
	v_add_lshl_u32 v37, v53, v37, 1
	s_barrier
	ds_read_b128 v[2:5], v28
	ds_read_b128 v[42:45], v30
	v_cndmask_b32_e64 v49, 32, 0, vcc
	v_add_lshl_u32 v48, v54, v48, 1
	v_and_b32_e32 v37, 0xffffffc0, v37
	v_cndmask_b32_e64 v50, 32, 0, s[0:1]
	v_and_b32_e32 v51, 0xffffffc0, v48
	v_or3_b32 v48, v49, v31, v37
	v_or3_b32 v50, v50, v35, v51
	v_ashrrev_i32_e32 v49, 31, v48
	v_lshl_add_u64 v[46:47], s[16:17], 0, v[32:33]
	v_ashrrev_i32_e32 v51, 31, v50
	v_lshlrev_b64 v[48:49], 11, v[48:49]
	s_add_i32 s5, s5, s6
	v_lshlrev_b64 v[50:51], 11, v[50:51]
	v_lshl_add_u64 v[48:49], v[46:47], 0, v[48:49]
	s_mov_b32 s14, s7
	s_cmpk_lt_i32 s7, 0x1000
	v_lshl_add_u64 v[46:47], v[46:47], 0, v[50:51]
	s_waitcnt lgkmcnt(1)
	global_store_dwordx4 v[48:49], v[2:5], off sc0 sc1
	s_waitcnt lgkmcnt(0)
	global_store_dwordx4 v[46:47], v[42:45], off sc0 sc1
	s_waitcnt vmcnt(2)
	v_mov_b64_e32 v[2:3], v[38:39]
	v_mov_b64_e32 v[4:5], v[40:41]
	s_cbranch_scc1 .LBB0_39
.LBB0_40:
	s_add_u32 s22, s88, 0x2d00000
	s_addc_u32 s23, s89, 0
	s_cmpk_lt_i32 s24, 0x800
	v_writelane_b32 v237, s20, 25
	v_mov_b32_e32 v30, v128
	s_cselect_b64 s[0:1], -1, 0
	s_cmpk_gt_i32 s24, 0x7ff
	v_writelane_b32 v237, s21, 26
	s_cbranch_scc1 .LBB0_43
	s_ashr_i32 s4, s24, 31
	s_lshr_b32 s4, s4, 26
	s_add_i32 s6, s24, s4
	s_ashr_i32 s4, s6, 6
	s_ashr_i32 s5, s4, 31
	s_lshl_b64 s[4:5], s[4:5], 20
	s_add_u32 s7, s80, s4
	s_addc_u32 s14, s81, s5
	s_andn2_b32 s6, s6, 63
	s_sub_i32 s6, s24, s6
	s_ashr_i32 s4, s6, 31
	s_lshr_b32 s4, s4, 28
	s_add_i32 s4, s6, s4
	s_ashr_i32 s15, s4, 4
	s_lshl_b32 s4, s15, 6
	s_ashr_i32 s5, s4, 31
	s_lshl_b64 s[4:5], s[4:5], 12
	s_add_u32 s7, s7, s4
	s_addc_u32 s14, s14, s5
	s_lshl_b32 s4, s15, 10
	s_lshl_b32 s5, s6, 6
	s_sub_i32 s4, s5, s4
	s_ashr_i32 s5, s4, 31
	v_ashrrev_i32_e32 v28, 4, v30
	s_lshl_b64 s[4:5], s[4:5], 2
	v_and_b32_e32 v1, 15, v30
	v_add_u32_e32 v22, 16, v28
	v_add_u32_e32 v24, 32, v28
	v_add_u32_e32 v26, 48, v28
	s_add_u32 s4, s7, s4
	v_mov_b32_e32 v19, 0
	v_ashrrev_i32_e32 v29, 31, v28
	v_ashrrev_i32_e32 v23, 31, v22
	v_ashrrev_i32_e32 v25, 31, v24
	v_ashrrev_i32_e32 v27, 31, v26
	s_addc_u32 s5, s14, s5
	v_lshlrev_b32_e32 v18, 4, v1
	v_lshl_add_u64 v[10:11], s[4:5], 0, v[18:19]
	v_lshlrev_b64 v[2:3], 12, v[26:27]
	v_lshlrev_b64 v[4:5], 12, v[24:25]
	v_lshlrev_b64 v[12:13], 12, v[22:23]
	v_lshlrev_b64 v[14:15], 12, v[28:29]
	v_lshl_add_u64 v[2:3], v[10:11], 0, v[2:3]
	v_lshl_add_u64 v[6:7], v[10:11], 0, v[4:5]
	v_lshl_add_u64 v[12:13], v[10:11], 0, v[12:13]
	v_lshl_add_u64 v[14:15], v[10:11], 0, v[14:15]
	global_load_dwordx4 v[2:5], v[2:3], off nt
	s_nop 0
	global_load_dwordx4 v[6:9], v[6:7], off nt
	s_nop 0
	global_load_dwordx4 v[10:13], v[12:13], off nt
	s_nop 0
	global_load_dwordx4 v[14:17], v[14:15], off nt
	v_lshlrev_b32_e32 v18, 2, v1
	v_mul_u32_u24_e32 v1, 0x120, v1
	v_lshlrev_b32_e32 v1, 1, v1
	v_lshlrev_b64 v[20:21], 10, v[28:29]
	v_lshl_add_u32 v1, v28, 1, v1
	v_lshlrev_b32_e32 v28, 3, v30
	v_and_b32_e32 v32, 56, v28
	v_lshlrev_b32_e32 v36, 1, v32
	v_ashrrev_i32_e32 v34, 3, v30
	s_movk_i32 s6, 0x90
	v_mad_u64_u32 v[28:29], s[4:5], v34, s6, v[36:37]
	v_add_u32_e32 v29, 0x100, v30
	v_ashrrev_i32_e32 v29, 3, v29
	v_mad_u64_u32 v[30:31], s[4:5], v29, s6, v[36:37]
	v_lshlrev_b64 v[22:23], 10, v[22:23]
	v_lshlrev_b64 v[24:25], 10, v[24:25]
	v_lshlrev_b64 v[26:27], 10, v[26:27]
	s_lshl_b32 s4, s24, 6
	s_lshl_b32 s5, s90, 6
	v_lshlrev_b32_e32 v18, 2, v18
	v_lshlrev_b32_e32 v32, 1, v32
	v_mov_b32_e32 v33, v19
	s_mov_b32 s14, s24
.LBB0_42:
	s_ashr_i32 s6, s14, 31
	s_lshr_b32 s6, s6, 26
	s_add_i32 s7, s14, s6
	s_ashr_i32 s6, s7, 6
	s_andn2_b32 s7, s7, 63
	s_sub_i32 s7, s14, s7
	s_ashr_i32 s15, s7, 31
	s_lshr_b32 s15, s15, 28
	s_add_i32 s7, s7, s15
	s_add_i32 s18, s14, s90
	s_ashr_i32 s19, s7, 4
	s_cmpk_lt_u32 s18, 0x800
	s_cselect_b32 s7, s18, s14
	s_ashr_i32 s14, s7, 31
	s_lshr_b32 s14, s14, 26
	s_add_i32 s15, s7, s14
	s_ashr_i32 s14, s15, 6
	s_andn2_b32 s15, s15, 63
	s_sub_i32 s7, s7, s15
	s_ashr_i32 s16, s7, 31
	s_lshr_b32 s16, s16, 28
	s_ashr_i32 s15, s14, 31
	s_add_i32 s16, s7, s16
	s_lshl_b64 s[14:15], s[14:15], 20
	s_ashr_i32 s16, s16, 4
	s_add_u32 s17, s80, s14
	s_addc_u32 s20, s81, s15
	s_lshl_b32 s14, s16, 6
	s_ashr_i32 s15, s14, 31
	s_lshl_b64 s[14:15], s[14:15], 12
	s_add_u32 s17, s17, s14
	s_addc_u32 s20, s20, s15
	s_lshl_b32 s14, s16, 10
	s_lshl_b32 s7, s7, 6
	s_sub_i32 s14, s7, s14
	s_ashr_i32 s15, s14, 31
	s_lshl_b64 s[14:15], s[14:15], 2
	s_add_u32 s14, s17, s14
	s_addc_u32 s15, s20, s15
	v_lshl_add_u64 v[36:37], s[14:15], 0, v[18:19]
	v_lshl_add_u64 v[38:39], v[20:21], 2, v[36:37]
	v_lshl_add_u64 v[40:41], v[22:23], 2, v[36:37]
	v_lshl_add_u64 v[44:45], v[24:25], 2, v[36:37]
	v_lshl_add_u64 v[48:49], v[26:27], 2, v[36:37]
	global_load_dwordx4 v[36:39], v[38:39], off nt
	s_nop 0
	global_load_dwordx4 v[40:43], v[40:41], off nt
	s_nop 0
	global_load_dwordx4 v[44:47], v[44:45], off nt
	s_nop 0
	global_load_dwordx4 v[48:51], v[48:49], off nt
	s_ashr_i32 s7, s6, 31
	s_lshl_b64 s[16:17], s[6:7], 19
	s_add_u32 s7, s22, s16
	s_addc_u32 s15, s23, s17
	s_lshl_b32 s16, s19, 6
	s_ashr_i32 s17, s16, 31
	s_lshl_b64 s[16:17], s[16:17], 1
	s_add_u32 s16, s7, s16
	s_addc_u32 s17, s15, s17
	s_lshl_b32 s7, s19, 10
	s_lshl_b32 s6, s6, 12
	s_waitcnt vmcnt(4)
	v_cvt_pk_bf16_f32 v14, v14, s0
	v_cvt_pk_bf16_f32 v6, v6, s0
	v_cvt_pk_bf16_f32 v7, v7, s0
	v_cvt_pk_bf16_f32 v8, v8, s0
	v_cvt_pk_bf16_f32 v9, v9, s0
	v_cvt_pk_bf16_f32 v2, v2, s0
	v_cvt_pk_bf16_f32 v3, v3, s0
	v_cvt_pk_bf16_f32 v4, v4, s0
	v_cvt_pk_bf16_f32 v5, v5, s0
	s_add_i32 s7, s7, s6
	v_cvt_pk_bf16_f32 v15, v15, s0
	v_cvt_pk_bf16_f32 v16, v16, s0
	v_cvt_pk_bf16_f32 v17, v17, s0
	v_cvt_pk_bf16_f32 v10, v10, s0
	v_cvt_pk_bf16_f32 v11, v11, s0
	v_cvt_pk_bf16_f32 v12, v12, s0
	v_cvt_pk_bf16_f32 v13, v13, s0
	s_waitcnt lgkmcnt(0)
	s_barrier
	ds_write_b16 v1, v14
	ds_write_b16 v1, v15 offset:144
	ds_write_b16 v1, v16 offset:288
	ds_write_b16 v1, v17 offset:432
	ds_write_b16 v1, v10 offset:32
	ds_write_b16 v1, v11 offset:176
	ds_write_b16 v1, v12 offset:320
	ds_write_b16 v1, v13 offset:464
	ds_write_b16 v1, v6 offset:64
	ds_write_b16 v1, v7 offset:208
	ds_write_b16 v1, v8 offset:352
	ds_write_b16 v1, v9 offset:496
	ds_write_b16 v1, v2 offset:96
	ds_write_b16 v1, v3 offset:240
	ds_write_b16 v1, v4 offset:384
	ds_write_b16 v1, v5 offset:528
	s_waitcnt lgkmcnt(0)
	s_barrier
	ds_read_b128 v[2:5], v28
	ds_read_b128 v[6:9], v30
	s_sub_i32 s6, s4, s7
	v_add_u32_e32 v12, s6, v34
	v_add_u32_e32 v14, s6, v29
	v_ashrrev_i32_e32 v13, 31, v12
	v_ashrrev_i32_e32 v15, 31, v14
	v_lshl_add_u64 v[10:11], s[16:17], 0, v[32:33]
	v_lshlrev_b64 v[12:13], 9, v[12:13]
	v_lshlrev_b64 v[14:15], 9, v[14:15]
	s_add_i32 s4, s4, s5
	v_lshl_add_u64 v[12:13], v[10:11], 0, v[12:13]
	v_lshl_add_u64 v[10:11], v[10:11], 0, v[14:15]
	s_mov_b32 s14, s18
	s_cmpk_lt_i32 s18, 0x800
	s_waitcnt lgkmcnt(1)
	global_store_dwordx4 v[12:13], v[2:5], off sc0 sc1
	s_waitcnt lgkmcnt(0)
	global_store_dwordx4 v[10:11], v[6:9], off sc0 sc1
	s_waitcnt vmcnt(5)
	v_mov_b64_e32 v[14:15], v[36:37]
	v_mov_b64_e32 v[16:17], v[38:39]
	s_waitcnt vmcnt(4)
	v_mov_b64_e32 v[10:11], v[40:41]
	v_mov_b64_e32 v[12:13], v[42:43]
	s_waitcnt vmcnt(3)
	v_mov_b64_e32 v[6:7], v[44:45]
	v_mov_b64_e32 v[8:9], v[46:47]
	s_waitcnt vmcnt(2)
	v_mov_b64_e32 v[2:3], v[48:49]
	v_mov_b64_e32 v[4:5], v[50:51]
	s_cbranch_scc1 .LBB0_42

.LBB0_45:
	global_load_dwordx4 v[8:11], v[6:7], off offset:-16 nt
	global_load_dwordx4 v[12:15], v[6:7], off nt
	v_lshl_add_u64 v[2:3], v[2:3], 0, s[14:15]
	v_cmp_lt_u64_e32 vcc, s[22:23], v[2:3]
	v_lshl_add_u64 v[6:7], v[6:7], 0, s[18:19]
	s_or_b64 s[20:21], vcc, s[20:21]
	s_waitcnt vmcnt(1)
	v_cvt_pk_bf16_f32 v8, v8, v9
	v_cvt_pk_bf16_f32 v9, v10, v11
	s_waitcnt vmcnt(0)
	v_cvt_pk_bf16_f32 v10, v12, v13
	v_cvt_pk_bf16_f32 v11, v14, v15
	global_store_dwordx4 v[4:5], v[8:11], off sc0 sc1
	v_lshl_add_u64 v[4:5], v[4:5], 0, s[16:17]
	s_andn2_b64 exec, exec, s[20:21]
	s_cbranch_execnz .LBB0_45

.LBB0_545:
	s_or_b64 exec, exec, s[0:1]
	s_waitcnt vmcnt(1)
	v_mov_b32_e32 v56, v128
	s_waitcnt lgkmcnt(0)
	s_barrier
	s_nop 0
	v_add_u32_e32 v66, 0x100, v56
	v_ashrrev_i32_e32 v57, 31, v56
	v_ashrrev_i32_e32 v67, 31, v66
	v_lshl_add_u64 v[0:1], v[56:57], 4, s[70:71]
	v_lshl_add_u64 v[4:5], v[66:67], 4, s[70:71]
	v_add_u32_e32 v68, 0x200, v56
	v_add_u32_e32 v70, 0x300, v56
	s_barrier
	global_load_dwordx4 v[0:3], v[0:1], off
	s_nop 0
	global_load_dwordx4 v[4:7], v[4:5], off
	v_ashrrev_i32_e32 v69, 31, v68
	v_ashrrev_i32_e32 v71, 31, v70
	v_lshl_add_u64 v[8:9], v[68:69], 4, s[70:71]
	v_lshl_add_u64 v[12:13], v[70:71], 4, s[70:71]
	v_add_u32_e32 v72, 0x400, v56
	global_load_dwordx4 v[8:11], v[8:9], off
	v_ashrrev_i32_e32 v73, 31, v72
	global_load_dwordx4 v[12:15], v[12:13], off nt
	v_lshl_add_u64 v[16:17], v[72:73], 4, s[70:71]
	v_add_u32_e32 v74, 0x500, v56
	global_load_dwordx4 v[16:19], v[16:17], off
	v_ashrrev_i32_e32 v75, 31, v74
	v_lshl_add_u64 v[20:21], v[74:75], 4, s[70:71]
	v_add_u32_e32 v76, 0x600, v56
	global_load_dwordx4 v[20:23], v[20:21], off
	v_ashrrev_i32_e32 v77, 31, v76
	v_lshl_add_u64 v[24:25], v[76:77], 4, s[70:71]
	v_add_u32_e32 v78, 0x700, v56
	global_load_dwordx4 v[24:27], v[24:25], off
	v_ashrrev_i32_e32 v79, 31, v78
	v_lshl_add_u64 v[28:29], v[78:79], 4, s[70:71]
	v_add_u32_e32 v80, 0x800, v56
	global_load_dwordx4 v[28:31], v[28:29], off
	v_ashrrev_i32_e32 v81, 31, v80
	v_lshl_add_u64 v[32:33], v[80:81], 4, s[70:71]
	v_add_u32_e32 v82, 0x900, v56
	global_load_dwordx4 v[32:35], v[32:33], off
	v_ashrrev_i32_e32 v83, 31, v82
	v_lshl_add_u64 v[36:37], v[82:83], 4, s[70:71]
	v_add_u32_e32 v84, 0xa00, v56
	global_load_dwordx4 v[36:39], v[36:37], off
	v_ashrrev_i32_e32 v85, 31, v84
	v_lshl_add_u64 v[40:41], v[84:85], 4, s[70:71]
	v_add_u32_e32 v86, 0xb00, v56
	global_load_dwordx4 v[40:43], v[40:41], off
	v_ashrrev_i32_e32 v87, 31, v86
	v_lshl_add_u64 v[44:45], v[86:87], 4, s[70:71]
	v_add_u32_e32 v88, 0xc00, v56
	global_load_dwordx4 v[44:47], v[44:45], off
	v_ashrrev_i32_e32 v89, 31, v88
	v_lshl_add_u64 v[48:49], v[88:89], 4, s[70:71]
	v_add_u32_e32 v90, 0xd00, v56
	global_load_dwordx4 v[48:51], v[48:49], off
	v_ashrrev_i32_e32 v91, 31, v90
	v_lshl_add_u64 v[52:53], v[90:91], 4, s[70:71]
	v_add_u32_e32 v92, 0xe00, v56
	global_load_dwordx4 v[52:55], v[52:53], off
	v_ashrrev_i32_e32 v93, 31, v92
	v_lshl_add_u64 v[58:59], v[92:93], 4, s[70:71]
	v_add_u32_e32 v94, 0xf00, v56
	global_load_dwordx4 v[58:61], v[58:59], off
	v_ashrrev_i32_e32 v95, 31, v94
	s_waitcnt vmcnt(15)
	v_lshl_add_u64 v[62:63], v[94:95], 4, s[70:71]
	global_load_dwordx4 v[62:65], v[62:63], off
	v_lshlrev_b32_e32 v67, 14, v56
	v_and_b32_e32 v69, -4, v56
	v_and_b32_e32 v67, 0xc000, v67
	v_and_b32_e32 v66, -4, v66
	v_and_b32_e32 v68, -4, v68
	v_add_u32_e32 v69, v67, v69
	v_add_u32_e32 v66, v67, v66
	v_add_u32_e32 v68, v67, v68
	s_add_u32 s0, s88, 0x3e00000
	s_addc_u32 s1, s89, 0
	v_writelane_b32 v237, s0, 42
	s_waitcnt vmcnt(15)
	ds_write2st64_b32 v69, v0, v1 offset1:16
	ds_write2st64_b32 v69, v2, v3 offset0:32 offset1:48
	s_waitcnt vmcnt(14)
	ds_write2st64_b32 v66, v4, v5 offset1:16
	ds_write2st64_b32 v66, v6, v7 offset0:32 offset1:48
	s_waitcnt vmcnt(13)
	ds_write2st64_b32 v68, v8, v9 offset1:16
	ds_write2st64_b32 v68, v10, v11 offset0:32 offset1:48
	v_and_b32_e32 v0, -4, v70
	v_add_u32_e32 v0, v67, v0
	s_waitcnt vmcnt(12)
	ds_write2st64_b32 v0, v12, v13 offset1:16
	ds_write2st64_b32 v0, v14, v15 offset0:32 offset1:48
	v_and_b32_e32 v0, -4, v72
	v_add_u32_e32 v0, v67, v0
	s_waitcnt vmcnt(11)
	ds_write2st64_b32 v0, v16, v17 offset1:16
	ds_write2st64_b32 v0, v18, v19 offset0:32 offset1:48
	v_and_b32_e32 v0, -4, v74
	v_add_u32_e32 v0, v67, v0
	v_writelane_b32 v237, s1, 43
	s_waitcnt vmcnt(10)
	ds_write2st64_b32 v0, v20, v21 offset1:16
	ds_write2st64_b32 v0, v22, v23 offset0:32 offset1:48
	v_and_b32_e32 v0, -4, v76
	s_add_u32 s0, s88, 0x3d80000
	v_add_u32_e32 v0, v67, v0
	s_addc_u32 s1, s89, 0
	s_waitcnt vmcnt(9)
	ds_write2st64_b32 v0, v24, v25 offset1:16
	ds_write2st64_b32 v0, v26, v27 offset0:32 offset1:48
	v_and_b32_e32 v0, -4, v78
	v_writelane_b32 v237, s0, 44
	v_add_u32_e32 v0, v67, v0
	s_waitcnt vmcnt(8)
	ds_write2st64_b32 v0, v28, v29 offset1:16
	ds_write2st64_b32 v0, v30, v31 offset0:32 offset1:48
	v_writelane_b32 v237, s1, 45
	v_and_b32_e32 v0, -4, v80
	v_readlane_b32 s0, v237, 31
	v_add_u32_e32 v0, v67, v0
	s_cmpk_lt_i32 s0, 0x200
	s_waitcnt vmcnt(7)
	ds_write2st64_b32 v0, v32, v33 offset1:16
	ds_write2st64_b32 v0, v34, v35 offset0:32 offset1:48
	v_and_b32_e32 v0, -4, v82
	s_cselect_b64 s[2:3], -1, 0
	v_add_u32_e32 v0, v67, v0
	v_readlane_b32 s1, v237, 32
	v_writelane_b32 v237, s2, 46
	s_waitcnt vmcnt(6)
	ds_write2st64_b32 v0, v36, v37 offset1:16
	ds_write2st64_b32 v0, v38, v39 offset0:32 offset1:48
	v_and_b32_e32 v0, -4, v84
	v_writelane_b32 v237, s3, 47
	v_add_u32_e32 v0, v67, v0
	v_writelane_b32 v237, s80, 48
	s_waitcnt vmcnt(5)
	ds_write2st64_b32 v0, v40, v41 offset1:16
	ds_write2st64_b32 v0, v42, v43 offset0:32 offset1:48
	v_and_b32_e32 v0, -4, v86
	v_writelane_b32 v237, s81, 49
	v_add_u32_e32 v0, v67, v0
	v_writelane_b32 v237, s82, 50
	s_waitcnt vmcnt(4)
	ds_write2st64_b32 v0, v44, v45 offset1:16
	ds_write2st64_b32 v0, v46, v47 offset0:32 offset1:48
	v_and_b32_e32 v0, -4, v88
	v_writelane_b32 v237, s83, 51
	v_add_u32_e32 v0, v67, v0
	v_writelane_b32 v237, s84, 52
	s_waitcnt vmcnt(3)
	ds_write2st64_b32 v0, v48, v49 offset1:16
	ds_write2st64_b32 v0, v50, v51 offset0:32 offset1:48
	v_and_b32_e32 v0, -4, v90
	v_writelane_b32 v237, s85, 53
	v_add_u32_e32 v0, v67, v0
	v_writelane_b32 v237, s86, 54
	s_waitcnt vmcnt(2)
	ds_write2st64_b32 v0, v52, v53 offset1:16
	ds_write2st64_b32 v0, v54, v55 offset0:32 offset1:48
	v_and_b32_e32 v0, -4, v92
	v_writelane_b32 v237, s87, 55
	v_add_u32_e32 v0, v67, v0
	v_writelane_b32 v237, s88, 56
	s_waitcnt vmcnt(1)
	ds_write2st64_b32 v0, v58, v59 offset1:16
	ds_write2st64_b32 v0, v60, v61 offset0:32 offset1:48
	v_and_b32_e32 v0, -4, v94
	v_writelane_b32 v237, s89, 57
	v_add_u32_e32 v0, v67, v0
	s_cmpk_gt_i32 s0, 0x1ff
	v_writelane_b32 v237, s90, 58
	s_waitcnt vmcnt(0)
	ds_write2st64_b32 v0, v62, v63 offset1:16
	ds_write2st64_b32 v0, v64, v65 offset0:32 offset1:48
	s_waitcnt lgkmcnt(0)
	s_barrier
	v_writelane_b32 v237, s91, 59
	s_cbranch_scc1 .LBB0_594
	v_and_b32_e32 v5, 63, v56
	v_mov_b32_e32 v61, 0
	v_readlane_b32 s0, v237, 40
	v_lshlrev_b32_e32 v0, 3, v5
	v_mov_b32_e32 v1, v61
	v_readlane_b32 s1, v237, 41
	v_lshl_add_u64 v[2:3], v[56:57], 2, s[88:89]
	v_ashrrev_i32_e32 v4, 2, v56
	v_lshl_add_u64 v[64:65], s[0:1], 0, v[0:1]
	s_mov_b64 s[0:1], 0x3d00000
	v_lshl_add_u64 v[70:71], v[2:3], 0, s[0:1]
	v_lshlrev_b32_e32 v2, 6, v5
	v_mov_b32_e32 v3, v61
	v_lshl_add_u64 v[72:73], s[66:67], 0, v[2:3]
	s_mov_b64 s[0:1], 0x1000
	v_lshl_add_u64 v[74:75], v[72:73], 0, s[0:1]
	s_mov_b64 s[0:1], 0x2000
	v_lshl_add_u64 v[76:77], v[72:73], 0, s[0:1]
	s_mov_b64 s[0:1], 0x3000
	v_lshl_add_u64 v[78:79], v[72:73], 0, s[0:1]
	v_readlane_b32 s4, v237, 31
	s_lshl_b32 s0, s90, 6
	v_cmp_gt_i32_e64 s[6:7], 24, v56
	v_lshlrev_b32_e32 v6, 2, v56
	v_and_b32_e32 v58, -16, v4
	v_lshlrev_b32_e32 v60, 4, v5
	v_cmp_gt_i32_e64 s[8:9], 64, v56
	v_readlane_b32 s5, v237, 32
	s_lshl_b32 s12, s4, 6
	v_writelane_b32 v237, s0, 60
	v_mov_b32_e32 v2, 0x10000
	v_lshl_add_u64 v[0:1], s[88:89], 0, v[0:1]
	s_mov_b64 s[0:1], 0x4500400
	v_add_u32_e32 v99, 0x10100, v6
	v_ashrrev_i32_e32 v59, 31, v58
	v_lshl_add_u64 v[62:63], s[36:37], 0, v[60:61]
	v_lshl_add_u64 v[66:67], s[62:63], 0, v[60:61]
	v_lshl_add_u64 v[68:69], s[64:65], 0, v[60:61]
	v_lshrrev_b32_e32 v250, 6, v56
	v_lshlrev_b32_e32 v250, 10, v250
	v_mov_b32_e32 v251, 0
	v_lshl_add_u64 v[252:253], v[66:67], 0, v[250:251]
	global_load_dwordx4 v[186:189], v[252:253], off
	v_lshl_add_u64 v[252:253], v[68:69], 0, v[250:251]
	global_load_dwordx4 v[190:193], v[252:253], off
	v_lshlrev_b32_e32 v250, 4, v56
	v_add_u32_e32 v250, 0x10400, v250
	s_waitcnt vmcnt(0)
	ds_write_b128 v250, v[186:189]
	ds_write_b128 v250, v[190:193] offset:4096
	v_add_u32_e32 v234, 0x10400, v60
	s_waitcnt lgkmcnt(0)
	s_mov_b32 s3, 0
	v_cmp_eq_u32_e64 s[10:11], 0, v5
	v_add_u32_e32 v112, 0x10000, v6
	v_add_u32_e32 v113, 0x10200, v6
	v_add_u32_e32 v57, 0x10180, v6
	v_add_u32_e32 v114, s12, v4
	v_lshl_add_u32 v115, v4, 2, v2
	v_lshl_add_u64 v[80:81], v[0:1], 0, s[0:1]
	s_mov_b32 s22, 0x3fb504f3
	v_mov_b32_e32 v116, 0x3727c5ac
	v_mov_b32_e32 v117, 1
	v_mov_b32_e32 v118, 0xff61b1e6
	v_mov_b32_e32 v119, 0x10100
	v_mov_b32_e32 v120, 0x10180
	s_mov_b32 s2, s4
	v_writelane_b32 v237, s6, 62
	v_writelane_b32 v236, s8, 0
	s_nop 0
	v_writelane_b32 v237, s7, 63
	v_writelane_b32 v236, s9, 1
	s_branch .LBB0_548

.LBB0_552:
	s_add_i32 s23, s7, 1
	s_waitcnt vmcnt(0)
	v_mov_b64_e32 v[38:39], v[84:85]
	v_mov_b64_e32 v[32:33], v[92:93]
	v_mov_b64_e32 v[34:35], v[90:91]
	v_mov_b64_e32 v[36:37], v[88:89]
	v_mov_b32_e32 v0, s23
	v_min_u32_e32 v0, 15, v0
	v_mov_b32_e32 v1, 0
	v_lshl_add_u64 v[0:1], v[82:83], 0, v[0:1]
	v_lshlrev_b64 v[2:3], 12, v[0:1]
	v_lshlrev_b64 v[0:1], 11, v[0:1]
	v_lshl_add_u64 v[12:13], v[62:63], 0, v[2:3]
	v_lshl_add_u64 v[92:93], v[64:65], 0, v[0:1]
	global_load_dwordx4 v[0:3], v[12:13], off nt
	global_load_dwordx2 v[84:85], v[92:93], off nt
	global_load_dwordx4 v[4:7], v[12:13], off offset:1024 nt
	global_load_dwordx2 v[88:89], v[92:93], off offset:512 nt
	global_load_dwordx4 v[8:11], v[12:13], off offset:2048 nt
	global_load_dwordx2 v[90:91], v[92:93], off offset:1024 nt
	s_nop 0
	global_load_dwordx4 v[12:15], v[12:13], off offset:3072 nt
	s_nop 0
	global_load_dwordx2 v[92:93], v[92:93], off offset:1536 nt
	v_lshlrev_b32_e32 v40, 16, v38
	v_and_b32_e32 v41, 0xffff0000, v38
	v_lshlrev_b32_e32 v38, 16, v39
	v_and_b32_e32 v39, 0xffff0000, v39
	v_lshlrev_b32_e32 v54, 16, v36
	v_and_b32_e32 v55, 0xffff0000, v36
	v_lshlrev_b32_e32 v94, 16, v37
	v_and_b32_e32 v95, 0xffff0000, v37
	v_lshlrev_b32_e32 v96, 16, v34
	v_and_b32_e32 v97, 0xffff0000, v34
	v_lshlrev_b32_e32 v100, 16, v35
	v_and_b32_e32 v101, 0xffff0000, v35
	v_lshlrev_b32_e32 v102, 16, v32
	v_and_b32_e32 v103, 0xffff0000, v32
	v_lshlrev_b32_e32 v104, 16, v33
	v_and_b32_e32 v105, 0xffff0000, v33
	v_pk_fma_f32 v[106:107], v[30:31], s[22:23], v[38:39] op_sel_hi:[1,0,1]
	ds_read_b128 v[30:33], v234
	ds_read_b128 v[34:37], v234 offset:4096
	v_pk_fma_f32 v[28:29], v[28:29], s[22:23], v[40:41] op_sel_hi:[1,0,1]
	v_pk_fma_f32 v[20:21], v[20:21], s[22:23], v[54:55] op_sel_hi:[1,0,1]
	v_add_f32_e32 v38, v28, v29
	v_add_f32_e32 v38, v38, v106
	v_pk_fma_f32 v[22:23], v[22:23], s[22:23], v[94:95] op_sel_hi:[1,0,1]
	v_add_f32_e32 v54, v20, v21
	v_pk_fma_f32 v[24:25], v[24:25], s[22:23], v[96:97] op_sel_hi:[1,0,1]
	v_add_f32_e32 v38, v107, v38
	v_add_f32_e32 v54, v54, v22
	v_pk_fma_f32 v[26:27], v[26:27], s[22:23], v[100:101] op_sel_hi:[1,0,1]
	v_add_f32_e32 v55, v24, v25
	v_add_f32_e32 v98, 0, v38
	v_add_f32_e32 v54, v23, v54
	v_add_f32_e32 v55, v55, v26
	v_add_f32_e32 v54, v98, v54
	v_add_f32_e32 v55, v27, v55
	v_pk_fma_f32 v[16:17], v[16:17], s[22:23], v[102:103] op_sel_hi:[1,0,1]
	v_add_f32_e32 v54, v54, v55
	v_pk_fma_f32 v[18:19], v[18:19], s[22:23], v[104:105] op_sel_hi:[1,0,1]
	v_add_f32_e32 v55, v16, v17
	v_add_f32_e32 v55, v55, v18
	v_add_f32_e32 v55, v19, v55
	v_add_f32_e32 v54, v54, v55
	ds_read_b128 v[38:41], v60
	ds_read_b128 v[42:45], v60 offset:4096
	ds_read_b128 v[46:49], v60 offset:8192
	ds_read_b128 v[50:53], v60 offset:12288
	ds_read_b128 v[108:111], v60 offset:16384
	ds_read_b128 v[122:125], v60 offset:20480
	ds_read_b128 v[130:133], v60 offset:24576
	ds_read_b128 v[134:137], v60 offset:28672
	ds_read_b128 v[138:141], v60 offset:32768
	ds_read_b128 v[142:145], v60 offset:36864
	ds_read_b128 v[146:149], v60 offset:40960
	ds_read_b128 v[150:153], v60 offset:45056
	ds_read_b128 v[154:157], v60 offset:49152
	v_add_f32_dpp v54, v54, v54 quad_perm:[1,0,3,2] row_mask:0xf bank_mask:0xf bound_ctrl:1
	s_nop 1
	v_add_f32_dpp v54, v54, v54 quad_perm:[2,3,0,1] row_mask:0xf bank_mask:0xf bound_ctrl:1
	s_nop 1
	v_add_f32_dpp v54, v54, v54 row_half_mirror row_mask:0xf bank_mask:0xf bound_ctrl:1
	s_nop 1
	v_add_f32_dpp v54, v54, v54 row_mirror row_mask:0xf bank_mask:0xf bound_ctrl:1
	s_nop 0
	v_readlane_b32 s2, v54, 16
	v_readlane_b32 s4, v54, 48
	v_readlane_b32 s0, v54, 0
	v_readlane_b32 s1, v54, 32
	v_mov_b32_e32 v54, s2
	v_mov_b32_e32 v55, s4
	v_pk_add_f32 v[54:55], s[0:1], v[54:55]
	s_nop 0
	v_add_f32_e32 v54, v54, v55
	v_mul_f32_e32 v54, 0x3a800000, v54
	v_pk_add_f32 v[28:29], v[28:29], v[54:55] op_sel_hi:[1,0] neg_lo:[0,1] neg_hi:[0,1]
	v_pk_add_f32 v[126:127], v[106:107], v[54:55] op_sel_hi:[1,0] neg_lo:[0,1] neg_hi:[0,1]
	v_pk_mul_f32 v[104:105], v[28:29], v[28:29]
	v_pk_mul_f32 v[106:107], v[126:127], v[126:127]
	v_pk_add_f32 v[158:159], v[20:21], v[54:55] op_sel_hi:[1,0] neg_lo:[0,1] neg_hi:[0,1]
	v_pk_add_f32 v[160:161], v[22:23], v[54:55] op_sel_hi:[1,0] neg_lo:[0,1] neg_hi:[0,1]
	v_pk_add_f32 v[100:101], v[24:25], v[54:55] op_sel_hi:[1,0] neg_lo:[0,1] neg_hi:[0,1]
	v_pk_add_f32 v[102:103], v[26:27], v[54:55] op_sel_hi:[1,0] neg_lo:[0,1] neg_hi:[0,1]
	v_pk_add_f32 v[94:95], v[16:17], v[54:55] op_sel_hi:[1,0] neg_lo:[0,1] neg_hi:[0,1]
	v_pk_add_f32 v[96:97], v[18:19], v[54:55] op_sel_hi:[1,0] neg_lo:[0,1] neg_hi:[0,1]
	v_add_f32_e32 v54, v104, v105
	v_add_f32_e32 v54, v106, v54
	v_pk_mul_f32 v[20:21], v[158:159], v[158:159]
	v_add_f32_e32 v54, v107, v54
	v_add_f32_e32 v20, v20, v54
	v_pk_mul_f32 v[22:23], v[160:161], v[160:161]
	v_add_f32_e32 v20, v21, v20
	v_add_f32_e32 v20, v22, v20
	v_pk_mul_f32 v[24:25], v[100:101], v[100:101]
	v_add_f32_e32 v20, v23, v20
	v_add_f32_e32 v20, v24, v20
	v_pk_mul_f32 v[26:27], v[102:103], v[102:103]
	v_add_f32_e32 v20, v25, v20
	v_add_f32_e32 v20, v26, v20
	v_pk_mul_f32 v[16:17], v[94:95], v[94:95]
	v_add_f32_e32 v20, v27, v20
	v_add_f32_e32 v16, v16, v20
	v_pk_mul_f32 v[18:19], v[96:97], v[96:97]
	v_add_f32_e32 v16, v17, v16
	v_add_f32_e32 v16, v18, v16
	v_add_f32_e32 v16, v19, v16
	s_nop 1
	v_add_f32_dpp v16, v16, v16 quad_perm:[1,0,3,2] row_mask:0xf bank_mask:0xf bound_ctrl:1
	s_nop 1
	v_add_f32_dpp v16, v16, v16 quad_perm:[2,3,0,1] row_mask:0xf bank_mask:0xf bound_ctrl:1
	s_nop 1
	v_add_f32_dpp v16, v16, v16 row_half_mirror row_mask:0xf bank_mask:0xf bound_ctrl:1
	s_nop 1
	v_add_f32_dpp v16, v16, v16 row_mirror row_mask:0xf bank_mask:0xf bound_ctrl:1
	s_nop 0
	v_readlane_b32 s2, v16, 16
	v_readlane_b32 s4, v16, 48
	v_readlane_b32 s0, v16, 0
	v_readlane_b32 s1, v16, 32
	v_mov_b32_e32 v16, s2
	v_mov_b32_e32 v17, s4
	v_pk_add_f32 v[16:17], s[0:1], v[16:17]
	s_mov_b32 s0, 0x800000
	v_add_f32_e32 v16, v16, v17
	v_fmamk_f32 v16, v16, 0x3a800000, v116
	v_cmp_gt_f32_e32 vcc, s0, v16
	v_mul_f32_e32 v17, 0x4b800000, v16
	s_nop 0
	v_cndmask_b32_e32 v16, v16, v17, vcc
	v_rsq_f32_e32 v54, v16
	ds_read_b128 v[16:19], v60 offset:53248
	s_waitcnt lgkmcnt(15)
	ds_read_b128 v[20:23], v60 offset:57344
	s_waitcnt lgkmcnt(15)
	ds_read_b128 v[24:27], v60 offset:61440
	s_waitcnt lgkmcnt(15)
	v_mul_f32_e32 v55, 0x45800000, v54
	v_cndmask_b32_e32 v98, v54, v55, vcc
	v_pk_mul_f32 v[28:29], v[28:29], v[98:99] op_sel_hi:[1,0]
	v_pk_fma_f32 v[106:107], v[30:31], v[28:29], v[34:35]
	v_pk_mul_f32 v[28:29], v[126:127], v[98:99] op_sel_hi:[1,0]
	s_waitcnt lgkmcnt(2)
	v_mul_f32_e32 v17, v107, v17
	v_pk_fma_f32 v[104:105], v[32:33], v[28:29], v[36:37]
	v_cvt_pk_bf16_f32 v28, v106, v107
	v_cvt_pk_bf16_f32 v29, v104, v105
	global_store_dwordx2 v[86:87], v[28:29], off offset:-1024
	v_mul_f32_e32 v54, v39, v107
	v_fmac_f32_e32 v54, v38, v106
	ds_read_b128 v[32:35], v234 offset:1024
	ds_read_b128 v[36:39], v234 offset:5120
	v_fmac_f32_e32 v54, v104, v40
	v_fmac_f32_e32 v54, v105, v41
	v_mul_f32_e32 v55, v107, v43
	v_fmac_f32_e32 v55, v106, v42
	v_fmac_f32_e32 v55, v104, v44
	v_fmac_f32_e32 v55, v105, v45
	v_mul_f32_e32 v28, v107, v47
	v_fmac_f32_e32 v28, v106, v46
	v_fmac_f32_e32 v28, v104, v48
	v_fmac_f32_e32 v28, v105, v49
	v_add_f32_e32 v46, 0, v28
	v_mul_f32_e32 v45, v107, v51
	v_fmac_f32_e32 v45, v106, v50
	v_fmac_f32_e32 v45, v104, v52
	v_fmac_f32_e32 v45, v105, v53
	v_mul_f32_e32 v44, v107, v109
	v_fmac_f32_e32 v44, v106, v108
	v_fmac_f32_e32 v44, v104, v110
	v_fmac_f32_e32 v44, v105, v111
	v_mul_f32_e32 v53, v107, v123
	v_fmac_f32_e32 v53, v106, v122
	v_fmac_f32_e32 v53, v104, v124
	v_fmac_f32_e32 v53, v105, v125
	v_mul_f32_e32 v52, v107, v131
	v_fmac_f32_e32 v52, v106, v130
	v_fmac_f32_e32 v52, v104, v132
	v_fmac_f32_e32 v52, v105, v133
	v_mul_f32_e32 v51, v107, v135
	v_fmac_f32_e32 v51, v106, v134
	v_fmac_f32_e32 v51, v104, v136
	v_fmac_f32_e32 v51, v105, v137
	v_mul_f32_e32 v50, v107, v139
	v_fmac_f32_e32 v50, v106, v138
	v_fmac_f32_e32 v50, v104, v140
	v_fmac_f32_e32 v50, v105, v141
	v_mul_f32_e32 v49, v107, v143
	v_fmac_f32_e32 v49, v106, v142
	v_fmac_f32_e32 v49, v104, v144
	v_fmac_f32_e32 v49, v105, v145
	v_mul_f32_e32 v48, v107, v147
	v_fmac_f32_e32 v48, v106, v146
	v_fmac_f32_e32 v48, v104, v148
	v_fmac_f32_e32 v48, v105, v149
	v_mul_f32_e32 v131, v107, v151
	v_fmac_f32_e32 v17, v106, v16
	s_waitcnt lgkmcnt(3)
	v_mul_f32_e32 v122, v107, v21
	v_fmac_f32_e32 v131, v106, v150
	v_fmac_f32_e32 v122, v106, v20
	v_fmac_f32_e32 v131, v104, v152
	v_fmac_f32_e32 v122, v104, v22
	v_fmac_f32_e32 v131, v105, v153
	v_fmac_f32_e32 v122, v105, v23
	v_mul_f32_e32 v125, v107, v155
	s_waitcnt lgkmcnt(2)
	v_mul_f32_e32 v123, v107, v25
	v_fmac_f32_e32 v125, v106, v154
	v_fmac_f32_e32 v123, v106, v24
	v_fmac_f32_e32 v125, v104, v156
	v_fmac_f32_e32 v17, v104, v18
	v_fmac_f32_e32 v123, v104, v26
	v_fmac_f32_e32 v125, v105, v157
	v_fmac_f32_e32 v17, v105, v19
	v_fmac_f32_e32 v123, v105, v27
	v_pk_mul_f32 v[40:41], v[158:159], v[98:99] op_sel_hi:[1,0]
	v_add_f32_e32 v124, 0, v17
	s_waitcnt lgkmcnt(0)
	v_pk_fma_f32 v[108:109], v[40:41], v[32:33], v[36:37]
	ds_read_b128 v[40:43], v60 offset:1024
	ds_read_b128 v[134:137], v60 offset:21504
	v_pk_mul_f32 v[32:33], v[160:161], v[98:99] op_sel_hi:[1,0]
	ds_read_b128 v[142:145], v60 offset:29696
	v_pk_fma_f32 v[110:111], v[32:33], v[34:35], v[38:39]
	s_waitcnt lgkmcnt(2)
	v_fma_f32 v126, v109, v41, v54
	v_cvt_pk_bf16_f32 v32, v108, v109
	v_cvt_pk_bf16_f32 v33, v110, v111
	v_fmac_f32_e32 v126, v108, v40
	global_store_dwordx2 v[86:87], v[32:33], off offset:-512
	ds_read_b128 v[32:35], v60 offset:5120
	v_fmac_f32_e32 v126, v110, v42
	v_fmac_f32_e32 v126, v111, v43
	s_waitcnt lgkmcnt(2)
	v_fma_f32 v133, v109, v135, v53
	s_waitcnt lgkmcnt(1)
	v_fma_f32 v135, v109, v143, v51
	v_fmac_f32_e32 v135, v108, v142
	v_fmac_f32_e32 v135, v110, v144
	v_fmac_f32_e32 v135, v111, v145
	ds_read_b128 v[144:147], v60 offset:50176
	s_waitcnt lgkmcnt(1)
	v_fma_f32 v127, v109, v33, v55
	v_fmac_f32_e32 v127, v108, v32
	v_fmac_f32_e32 v127, v110, v34
	v_fmac_f32_e32 v127, v111, v35
	ds_read_b128 v[36:39], v60 offset:9216
	ds_read_b128 v[32:35], v60 offset:13312
	ds_read_b128 v[40:43], v60 offset:17408
	ds_read_b128 v[138:141], v60 offset:25600
	v_fmac_f32_e32 v133, v108, v134
	v_fmac_f32_e32 v133, v110, v136
	s_waitcnt lgkmcnt(3)
	v_fma_f32 v129, v109, v37, v46
	s_waitcnt lgkmcnt(2)
	v_fma_f32 v130, v109, v33, v45
	v_fmac_f32_e32 v133, v111, v137
	v_fmac_f32_e32 v129, v108, v36
	v_fmac_f32_e32 v130, v108, v32
	s_waitcnt lgkmcnt(0)
	v_fma_f32 v134, v109, v139, v52
	v_fmac_f32_e32 v129, v110, v38
	v_fmac_f32_e32 v130, v110, v34
	v_fma_f32 v132, v109, v41, v44
	v_fmac_f32_e32 v134, v108, v138
	v_fmac_f32_e32 v129, v111, v39
	v_fmac_f32_e32 v130, v111, v35
	v_fmac_f32_e32 v132, v108, v40
	v_fmac_f32_e32 v134, v110, v140
	v_fmac_f32_e32 v132, v110, v42
	v_fmac_f32_e32 v134, v111, v141
	v_fmac_f32_e32 v132, v111, v43
	ds_read_b128 v[52:55], v60 offset:33792
	ds_read_b128 v[138:141], v60 offset:37888
	s_waitcnt lgkmcnt(1)
	v_fma_f32 v136, v109, v53, v50
	v_fmac_f32_e32 v136, v108, v52
	v_fmac_f32_e32 v136, v110, v54
	v_fmac_f32_e32 v136, v111, v55
	ds_read_b128 v[50:53], v60 offset:41984
	s_waitcnt lgkmcnt(1)
	v_fma_f32 v137, v109, v139, v49
	v_fmac_f32_e32 v137, v108, v138
	v_fmac_f32_e32 v137, v110, v140
	v_fmac_f32_e32 v137, v111, v141
	ds_read_b128 v[140:143], v60 offset:46080
	s_waitcnt lgkmcnt(1)
	v_fma_f32 v138, v109, v51, v48
	v_fmac_f32_e32 v138, v108, v50
	v_fmac_f32_e32 v138, v110, v52
	v_fmac_f32_e32 v138, v111, v53
	ds_read_b128 v[48:51], v234 offset:2048
	ds_read_b128 v[52:55], v234 offset:6144
	s_waitcnt lgkmcnt(2)
	v_fma_f32 v131, v109, v141, v131
	v_fmac_f32_e32 v131, v108, v140
	v_fmac_f32_e32 v131, v110, v142
	v_fmac_f32_e32 v131, v111, v143
	ds_read_b128 v[140:143], v60 offset:54272
	v_fma_f32 v139, v109, v145, v125
	v_fmac_f32_e32 v139, v108, v144
	v_fmac_f32_e32 v139, v110, v146
	v_fmac_f32_e32 v139, v111, v147
	ds_read_b128 v[144:147], v60 offset:58368
	s_waitcnt lgkmcnt(1)
	v_fma_f32 v148, v109, v141, v124
	v_fmac_f32_e32 v148, v108, v140
	v_fmac_f32_e32 v148, v110, v142
	v_fmac_f32_e32 v148, v111, v143
	ds_read_b128 v[140:143], v60 offset:62464
	s_waitcnt lgkmcnt(1)
	v_mul_f32_e32 v124, v109, v145
	v_fmac_f32_e32 v124, v108, v144
	v_fmac_f32_e32 v124, v110, v146
	v_fmac_f32_e32 v124, v111, v147
	v_add_f32_e32 v144, v122, v124
	s_waitcnt lgkmcnt(0)
	v_mul_f32_e32 v122, v109, v141
	v_fmac_f32_e32 v122, v108, v140
	v_fmac_f32_e32 v122, v110, v142
	v_fmac_f32_e32 v122, v111, v143
	v_add_f32_e32 v142, v123, v122
	v_mov_b32_e32 v122, v106
	v_mov_b32_e32 v123, v108
	v_mov_b32_e32 v108, v107
	v_mov_b32_e32 v106, v186
	v_mov_b32_e32 v124, v182
	v_mov_b32_e32 v140, v190
	v_mov_b32_e32 v125, v198
	v_mov_b32_e32 v107, v202
	v_pk_mul_f32 v[106:107], v[108:109], v[106:107]
	v_mov_b32_e32 v36, v187
	v_pk_fma_f32 v[106:107], v[122:123], v[124:125], v[106:107]
	v_mov_b32_e32 v124, v104
	v_mov_b32_e32 v125, v110
	v_mov_b32_e32 v110, v105
	v_mov_b32_e32 v104, v194
	v_mov_b32_e32 v141, v206
	v_pk_fma_f32 v[106:107], v[124:125], v[140:141], v[106:107]
	v_mov_b32_e32 v105, v210
	v_mov_b32_e32 v32, v183
	v_mov_b32_e32 v37, v203
	v_pk_mul_f32 v[24:25], v[108:109], v[36:37]
	v_pk_fma_f32 v[104:105], v[110:111], v[104:105], v[106:107]
	v_mov_b32_e32 v33, v199
	v_pk_fma_f32 v[24:25], v[122:123], v[32:33], v[24:25]
	v_mov_b32_e32 v40, v191
	v_add_f32_e32 v16, 0, v104
	v_mov_b32_e32 v41, v207
	v_pk_fma_f32 v[20:21], v[124:125], v[40:41], v[24:25]
	v_mov_b32_e32 v44, v195
	v_add_f32_e32 v107, v16, v105
	v_mov_b32_e32 v45, v211
	v_pk_fma_f32 v[16:17], v[110:111], v[44:45], v[20:21]
	v_mov_b32_e32 v20, v188
	v_add_f32_e32 v16, 0, v16
	v_mov_b32_e32 v21, v204
	v_add_f32_e32 v105, v16, v17
	v_mov_b32_e32 v16, v184
	v_mov_b32_e32 v17, v200
	v_pk_mul_f32 v[20:21], v[108:109], v[20:21]
	v_mov_b32_e32 v38, v189
	v_pk_fma_f32 v[16:17], v[122:123], v[16:17], v[20:21]
	v_mov_b32_e32 v20, v192
	v_mov_b32_e32 v21, v208
	v_pk_fma_f32 v[16:17], v[124:125], v[20:21], v[16:17]
	v_mov_b32_e32 v20, v196
	v_mov_b32_e32 v21, v212
	v_pk_fma_f32 v[16:17], v[110:111], v[20:21], v[16:17]
	v_mov_b32_e32 v34, v185
	v_add_f32_e32 v16, 0, v16
	v_add_f32_e32 v106, v16, v17
	v_mov_b32_e32 v39, v205
	v_pk_mul_f32 v[16:17], v[108:109], v[38:39]
	v_mov_b32_e32 v42, v193
	v_mov_b32_e32 v35, v201
	v_pk_fma_f32 v[16:17], v[122:123], v[34:35], v[16:17]
	v_mov_b32_e32 v46, v197
	v_mov_b32_e32 v43, v209
	v_pk_fma_f32 v[16:17], v[124:125], v[42:43], v[16:17]
	v_pk_mul_f32 v[20:21], v[102:103], v[98:99] op_sel_hi:[1,0]
	v_mov_b32_e32 v47, v213
	v_pk_fma_f32 v[16:17], v[110:111], v[46:47], v[16:17]
	v_pk_fma_f32 v[50:51], v[20:21], v[50:51], v[54:55]
	v_add_f32_e32 v16, 0, v16
	v_add_f32_e32 v104, v16, v17
	v_pk_mul_f32 v[16:17], v[100:101], v[98:99] op_sel_hi:[1,0]
	v_cvt_pk_bf16_f32 v21, v50, v51
	v_pk_fma_f32 v[48:49], v[16:17], v[48:49], v[52:53]
	ds_read_b128 v[16:19], v60 offset:2048
	v_cvt_pk_bf16_f32 v20, v48, v49
	global_store_dwordx2 v[86:87], v[20:21], off
	ds_read_b128 v[20:23], v60 offset:6144
	v_pk_mul_f32 v[46:47], v[94:95], v[98:99] op_sel_hi:[1,0]
	s_waitcnt lgkmcnt(1)
	v_fma_f32 v42, v49, v17, v126
	v_fmac_f32_e32 v42, v48, v16
	v_fmac_f32_e32 v42, v50, v18
	v_fmac_f32_e32 v42, v51, v19
	ds_read_b128 v[16:19], v60 offset:10240
	s_waitcnt lgkmcnt(1)
	v_fma_f32 v41, v49, v21, v127
	v_fmac_f32_e32 v41, v48, v20
	v_fmac_f32_e32 v41, v50, v22
	v_fmac_f32_e32 v41, v51, v23
	ds_read_b128 v[20:23], v60 offset:14336
	s_waitcnt lgkmcnt(1)
	v_fma_f32 v40, v49, v17, v129
	v_fmac_f32_e32 v40, v48, v16
	v_fmac_f32_e32 v40, v50, v18
	v_fmac_f32_e32 v40, v51, v19
	ds_read_b128 v[16:19], v60 offset:18432
	ds_read_b128 v[32:35], v234 offset:3072
	ds_read_b128 v[36:39], v234 offset:7168
	s_waitcnt lgkmcnt(3)
	v_fma_f32 v45, v49, v21, v130
	v_fmac_f32_e32 v45, v48, v20
	v_fmac_f32_e32 v45, v50, v22
	v_fmac_f32_e32 v45, v51, v23
	ds_read_b128 v[20:23], v60 offset:22528
	s_waitcnt lgkmcnt(3)
	v_fma_f32 v44, v49, v17, v132
	v_fmac_f32_e32 v44, v48, v16
	v_fmac_f32_e32 v44, v50, v18
	v_fmac_f32_e32 v44, v51, v19
	ds_read_b128 v[16:19], v60 offset:26624
	s_waitcnt lgkmcnt(1)
	v_fma_f32 v124, v49, v21, v133
	v_fmac_f32_e32 v124, v48, v20
	v_fmac_f32_e32 v124, v50, v22
	v_fmac_f32_e32 v124, v51, v23
	ds_read_b128 v[20:23], v60 offset:30720
	s_waitcnt lgkmcnt(1)
	v_fma_f32 v123, v49, v17, v134
	v_fmac_f32_e32 v123, v48, v16
	v_fmac_f32_e32 v123, v50, v18
	v_fmac_f32_e32 v123, v51, v19
	s_waitcnt lgkmcnt(0)
	v_fma_f32 v122, v49, v21, v135
	v_fmac_f32_e32 v122, v48, v20
	v_fmac_f32_e32 v122, v50, v22
	ds_read_b128 v[16:19], v60 offset:34816
	v_fmac_f32_e32 v122, v51, v23
	ds_read_b128 v[20:23], v60 offset:38912
	s_waitcnt lgkmcnt(1)
	v_fma_f32 v111, v49, v17, v136
	v_fmac_f32_e32 v111, v48, v16
	v_fmac_f32_e32 v111, v50, v18
	s_waitcnt lgkmcnt(0)
	v_fma_f32 v110, v49, v21, v137
	v_fmac_f32_e32 v110, v48, v20
	v_fmac_f32_e32 v111, v51, v19
	v_fmac_f32_e32 v110, v50, v22
	ds_read_b128 v[16:19], v60 offset:43008
	v_fmac_f32_e32 v110, v51, v23
	ds_read_b128 v[20:23], v60 offset:47104
	s_waitcnt lgkmcnt(1)
	v_fma_f32 v109, v49, v17, v138
	v_fmac_f32_e32 v109, v48, v16
	v_fmac_f32_e32 v109, v50, v18
	s_waitcnt lgkmcnt(0)
	v_fma_f32 v108, v49, v21, v131
	v_fmac_f32_e32 v108, v48, v20
	v_fmac_f32_e32 v109, v51, v19
	v_fmac_f32_e32 v108, v50, v22
	ds_read_b128 v[16:19], v60 offset:51200
	v_fmac_f32_e32 v108, v51, v23
	ds_read_b128 v[20:23], v60 offset:55296
	s_waitcnt lgkmcnt(1)
	v_fma_f32 v103, v49, v17, v139
	v_fmac_f32_e32 v103, v48, v16
	v_fmac_f32_e32 v103, v50, v18
	s_waitcnt lgkmcnt(0)
	v_fma_f32 v102, v49, v21, v148
	v_fmac_f32_e32 v102, v48, v20
	v_fmac_f32_e32 v103, v51, v19
	v_fmac_f32_e32 v102, v50, v22
	ds_read_b128 v[16:19], v60 offset:59392
	v_fmac_f32_e32 v102, v51, v23
	ds_read_b128 v[20:23], v60 offset:63488
	s_waitcnt lgkmcnt(1)
	v_fma_f32 v100, v49, v17, v144
	v_fmac_f32_e32 v100, v48, v16
	v_fmac_f32_e32 v100, v50, v18
	s_waitcnt lgkmcnt(0)
	v_fma_f32 v101, v49, v21, v142
	v_fmac_f32_e32 v101, v48, v20
	v_fmac_f32_e32 v101, v50, v22
	v_fmac_f32_e32 v100, v51, v19
	v_fmac_f32_e32 v101, v51, v23
	v_pk_fma_f32 v[52:53], v[46:47], v[32:33], v[36:37]
	v_pk_mul_f32 v[32:33], v[96:97], v[98:99] op_sel_hi:[1,0]
	ds_read_b128 v[94:97], v60 offset:3072
	v_pk_fma_f32 v[54:55], v[32:33], v[34:35], v[38:39]
	v_cvt_pk_bf16_f32 v32, v52, v53
	v_cvt_pk_bf16_f32 v33, v54, v55
	global_store_dwordx2 v[86:87], v[32:33], off offset:512
	ds_read_b128 v[32:35], v60 offset:7168
	s_waitcnt lgkmcnt(1)
	v_mul_f32_e32 v36, v53, v95
	v_fmac_f32_e32 v36, v52, v94
	v_fmac_f32_e32 v36, v54, v96
	v_fmac_f32_e32 v36, v55, v97
	v_add_f32_e32 v94, v42, v36
	ds_read_b128 v[36:39], v60 offset:11264
	ds_read_b128 v[130:133], v60 offset:15360
	s_waitcnt lgkmcnt(2)
	v_fma_f32 v95, v53, v33, v41
	v_fmac_f32_e32 v95, v52, v32
	v_fmac_f32_e32 v95, v54, v34
	s_waitcnt lgkmcnt(1)
	v_fma_f32 v96, v53, v37, v40
	v_fmac_f32_e32 v96, v52, v36
	v_fmac_f32_e32 v96, v54, v38
	v_fmac_f32_e32 v95, v55, v35
	v_fmac_f32_e32 v96, v55, v39
	ds_read_b128 v[40:43], v60 offset:19456
	s_waitcnt lgkmcnt(1)
	v_fma_f32 v97, v53, v131, v45
	v_fmac_f32_e32 v97, v52, v130
	v_fmac_f32_e32 v97, v54, v132
	v_fmac_f32_e32 v97, v55, v133
	ds_read_b128 v[130:133], v60 offset:23552
	s_waitcnt lgkmcnt(1)
	v_fma_f32 v125, v53, v41, v44
	v_fmac_f32_e32 v125, v52, v40
	v_fmac_f32_e32 v125, v54, v42
	v_fmac_f32_e32 v125, v55, v43
	ds_read_b128 v[134:137], v60 offset:27648
	s_waitcnt lgkmcnt(1)
	v_fma_f32 v124, v53, v131, v124
	v_fmac_f32_e32 v124, v52, v130
	v_fmac_f32_e32 v124, v54, v132
	v_fmac_f32_e32 v124, v55, v133
	ds_read_b128 v[130:133], v60 offset:31744
	s_waitcnt lgkmcnt(1)
	v_fma_f32 v98, v53, v135, v123
	v_fmac_f32_e32 v98, v52, v134
	v_fmac_f32_e32 v98, v54, v136
	v_fmac_f32_e32 v98, v55, v137
	ds_read_b128 v[134:137], v60 offset:35840
	s_waitcnt lgkmcnt(1)
	v_fma_f32 v122, v53, v131, v122
	v_fmac_f32_e32 v122, v52, v130
	v_fmac_f32_e32 v122, v54, v132
	v_fmac_f32_e32 v122, v55, v133
	ds_read_b128 v[130:133], v60 offset:39936
	s_waitcnt lgkmcnt(1)
	v_fma_f32 v111, v53, v135, v111
	v_fmac_f32_e32 v111, v52, v134
	v_fmac_f32_e32 v111, v54, v136
	v_fmac_f32_e32 v111, v55, v137
	ds_read_b128 v[134:137], v60 offset:44032
	s_waitcnt lgkmcnt(1)
	v_fma_f32 v110, v53, v131, v110
	v_fmac_f32_e32 v110, v52, v130
	v_fmac_f32_e32 v110, v54, v132
	v_fmac_f32_e32 v110, v55, v133
	ds_read_b128 v[130:133], v60 offset:48128
	s_waitcnt lgkmcnt(1)
	v_fma_f32 v109, v53, v135, v109
	v_fmac_f32_e32 v109, v52, v134
	v_fmac_f32_e32 v109, v54, v136
	v_fmac_f32_e32 v109, v55, v137
	ds_read_b128 v[134:137], v60 offset:52224
	s_waitcnt lgkmcnt(1)
	v_fma_f32 v108, v53, v131, v108
	v_fmac_f32_e32 v108, v52, v130
	v_fmac_f32_e32 v108, v54, v132
	v_fmac_f32_e32 v108, v55, v133
	ds_read_b128 v[130:133], v60 offset:56320
	s_waitcnt lgkmcnt(1)
	v_fma_f32 v103, v53, v135, v103
	v_fmac_f32_e32 v103, v52, v134
	v_fmac_f32_e32 v103, v54, v136
	v_fmac_f32_e32 v103, v55, v137
	ds_read_b128 v[134:137], v60 offset:60416
	s_waitcnt lgkmcnt(1)
	v_fma_f32 v102, v53, v131, v102
	v_fmac_f32_e32 v102, v52, v130
	v_fmac_f32_e32 v102, v54, v132
	v_fmac_f32_e32 v102, v55, v133
	ds_read_b128 v[130:133], v60 offset:64512
	s_waitcnt lgkmcnt(1)
	v_fma_f32 v123, v53, v135, v100
	v_fmac_f32_e32 v123, v52, v134
	v_fmac_f32_e32 v123, v54, v136
	v_fmac_f32_e32 v123, v55, v137
	s_waitcnt lgkmcnt(0)
	v_fma_f32 v129, v53, v131, v101
	v_fmac_f32_e32 v129, v52, v130
	v_fmac_f32_e32 v129, v54, v132
	v_fmac_f32_e32 v129, v55, v133
	v_mov_b32_e32 v100, v48
	v_mov_b32_e32 v101, v52
	v_mov_b32_e32 v52, v49
	v_mov_b32_e32 v48, v218
	v_mov_b32_e32 v126, v214
	v_mov_b32_e32 v130, v222
	v_mov_b32_e32 v127, v230
	v_mov_b32_e32 v49, v238
	v_pk_mul_f32 v[48:49], v[52:53], v[48:49]
	v_mov_b32_e32 v36, v219
	v_pk_fma_f32 v[48:49], v[100:101], v[126:127], v[48:49]
	v_mov_b32_e32 v126, v50
	v_mov_b32_e32 v127, v54
	v_mov_b32_e32 v131, v242
	v_pk_fma_f32 v[48:49], v[126:127], v[130:131], v[48:49]
	v_mov_b32_e32 v54, v51
	v_mov_b32_e32 v50, v226
	v_mov_b32_e32 v51, v246
	v_mov_b32_e32 v32, v215
	v_mov_b32_e32 v37, v239
	v_pk_mul_f32 v[24:25], v[52:53], v[36:37]
	v_pk_fma_f32 v[48:49], v[54:55], v[50:51], v[48:49]
	v_mov_b32_e32 v33, v231
	v_pk_fma_f32 v[24:25], v[100:101], v[32:33], v[24:25]
	v_mov_b32_e32 v40, v223
	v_add_f32_e32 v16, v107, v48
	v_mov_b32_e32 v41, v243
	v_pk_fma_f32 v[20:21], v[126:127], v[40:41], v[24:25]
	v_mov_b32_e32 v44, v227
	v_add_f32_e32 v28, v16, v49
	v_mov_b32_e32 v45, v247
	v_pk_fma_f32 v[16:17], v[54:55], v[44:45], v[20:21]
	v_mov_b32_e32 v20, v220
	v_add_f32_e32 v16, v105, v16
	v_mov_b32_e32 v21, v240
	v_add_f32_e32 v24, v16, v17
	v_mov_b32_e32 v16, v216
	v_mov_b32_e32 v17, v232
	v_pk_mul_f32 v[20:21], v[52:53], v[20:21]
	v_mov_b32_e32 v38, v221
	v_pk_fma_f32 v[16:17], v[100:101], v[16:17], v[20:21]
	v_mov_b32_e32 v20, v224
	v_mov_b32_e32 v21, v244
	v_pk_fma_f32 v[16:17], v[126:127], v[20:21], v[16:17]
	v_mov_b32_e32 v20, v228
	v_mov_b32_e32 v21, v248
	v_pk_fma_f32 v[16:17], v[54:55], v[20:21], v[16:17]
	v_mov_b32_e32 v34, v217
	v_add_f32_e32 v16, v106, v16
	v_add_f32_e32 v20, v16, v17
	v_mov_b32_e32 v39, v241
	v_pk_mul_f32 v[16:17], v[52:53], v[38:39]
	v_mov_b32_e32 v42, v225
	v_mov_b32_e32 v35, v233
	v_pk_fma_f32 v[16:17], v[100:101], v[34:35], v[16:17]
	v_mov_b32_e32 v46, v229
	v_mov_b32_e32 v43, v245
	v_pk_fma_f32 v[16:17], v[126:127], v[42:43], v[16:17]
	v_mov_b32_e32 v47, v249
	v_pk_fma_f32 v[16:17], v[54:55], v[46:47], v[16:17]
	v_add_f32_e32 v16, v104, v16
	v_add_f32_e32 v22, v16, v17
	v_add_f32_dpp v250, v24, v24 row_mirror row_mask:0xf bank_mask:0xf bound_ctrl:1
	v_add_f32_dpp v94, v94, v94 row_mirror row_mask:0xf bank_mask:0xf bound_ctrl:1
	v_add_f32_dpp v125, v125, v125 row_mirror row_mask:0xf bank_mask:0xf bound_ctrl:1
	v_add_f32_dpp v111, v111, v111 row_mirror row_mask:0xf bank_mask:0xf bound_ctrl:1
	v_add_f32_dpp v103, v103, v103 row_mirror row_mask:0xf bank_mask:0xf bound_ctrl:1
	v_add_f32_dpp v250, v20, v20 row_mirror row_mask:0xf bank_mask:0xc bound_ctrl:1
	v_add_f32_dpp v94, v95, v95 row_mirror row_mask:0xf bank_mask:0xc bound_ctrl:1
	v_add_f32_dpp v125, v124, v124 row_mirror row_mask:0xf bank_mask:0xc bound_ctrl:1
	v_add_f32_dpp v111, v110, v110 row_mirror row_mask:0xf bank_mask:0xc bound_ctrl:1
	v_add_f32_dpp v103, v102, v102 row_mirror row_mask:0xf bank_mask:0xc bound_ctrl:1
	v_add_f32_dpp v251, v28, v28 row_mirror row_mask:0xf bank_mask:0xf bound_ctrl:1
	v_add_f32_dpp v96, v96, v96 row_mirror row_mask:0xf bank_mask:0xf bound_ctrl:1
	v_add_f32_dpp v98, v98, v98 row_mirror row_mask:0xf bank_mask:0xf bound_ctrl:1
	v_add_f32_dpp v109, v109, v109 row_mirror row_mask:0xf bank_mask:0xf bound_ctrl:1
	v_add_f32_dpp v123, v123, v123 row_mirror row_mask:0xf bank_mask:0xf bound_ctrl:1
	v_add_f32_dpp v251, v22, v22 row_mirror row_mask:0xf bank_mask:0xc bound_ctrl:1
	v_add_f32_dpp v96, v97, v97 row_mirror row_mask:0xf bank_mask:0xc bound_ctrl:1
	v_add_f32_dpp v98, v122, v122 row_mirror row_mask:0xf bank_mask:0xc bound_ctrl:1
	v_add_f32_dpp v109, v108, v108 row_mirror row_mask:0xf bank_mask:0xc bound_ctrl:1
	v_add_f32_dpp v123, v129, v129 row_mirror row_mask:0xf bank_mask:0xc bound_ctrl:1
	v_add_f32_dpp v250, v250, v250 row_half_mirror row_mask:0xf bank_mask:0xf bound_ctrl:1
	v_add_f32_dpp v94, v94, v94 row_half_mirror row_mask:0xf bank_mask:0xf bound_ctrl:1
	v_add_f32_dpp v125, v125, v125 row_half_mirror row_mask:0xf bank_mask:0xf bound_ctrl:1
	v_add_f32_dpp v111, v111, v111 row_half_mirror row_mask:0xf bank_mask:0xf bound_ctrl:1
	v_add_f32_dpp v103, v103, v103 row_half_mirror row_mask:0xf bank_mask:0xf bound_ctrl:1
	v_add_f32_dpp v250, v251, v251 row_half_mirror row_mask:0xf bank_mask:0xa bound_ctrl:1
	v_add_f32_dpp v94, v96, v96 row_half_mirror row_mask:0xf bank_mask:0xa bound_ctrl:1
	v_add_f32_dpp v125, v98, v98 row_half_mirror row_mask:0xf bank_mask:0xa bound_ctrl:1
	v_add_f32_dpp v111, v109, v109 row_half_mirror row_mask:0xf bank_mask:0xa bound_ctrl:1
	v_add_f32_dpp v103, v123, v123 row_half_mirror row_mask:0xf bank_mask:0xa bound_ctrl:1
	v_add_f32_dpp v250, v250, v250 quad_perm:[1,0,3,2] row_mask:0xf bank_mask:0xf bound_ctrl:1
	v_add_f32_dpp v94, v94, v94 quad_perm:[1,0,3,2] row_mask:0xf bank_mask:0xf bound_ctrl:1
	v_add_f32_dpp v125, v125, v125 quad_perm:[1,0,3,2] row_mask:0xf bank_mask:0xf bound_ctrl:1
	v_add_f32_dpp v111, v111, v111 quad_perm:[1,0,3,2] row_mask:0xf bank_mask:0xf bound_ctrl:1
	v_add_f32_dpp v103, v103, v103 quad_perm:[1,0,3,2] row_mask:0xf bank_mask:0xf bound_ctrl:1
	v_add_f32_dpp v250, v250, v250 quad_perm:[2,3,0,1] row_mask:0xf bank_mask:0xf bound_ctrl:1
	v_add_f32_dpp v94, v94, v94 quad_perm:[2,3,0,1] row_mask:0xf bank_mask:0xf bound_ctrl:1
	v_add_f32_dpp v125, v125, v125 quad_perm:[2,3,0,1] row_mask:0xf bank_mask:0xf bound_ctrl:1
	v_add_f32_dpp v111, v111, v111 quad_perm:[2,3,0,1] row_mask:0xf bank_mask:0xf bound_ctrl:1
	v_add_f32_dpp v103, v103, v103 quad_perm:[2,3,0,1] row_mask:0xf bank_mask:0xf bound_ctrl:1
	v_readlane_b32 s2, v250, 20
	v_readlane_b32 s4, v250, 52
	v_readlane_b32 s0, v250, 4
	v_readlane_b32 s1, v250, 36
	v_mov_b32_e32 v16, s2
	v_mov_b32_e32 v17, s4
	v_readlane_b32 s2, v250, 16
	v_readlane_b32 s4, v250, 48
	v_pk_add_f32 v[16:17], s[0:1], v[16:17]
	v_readlane_b32 s0, v250, 0
	v_readlane_b32 s1, v250, 32
	v_mov_b32_e32 v18, s2
	v_mov_b32_e32 v19, s4
	v_readlane_b32 s2, v250, 24
	v_readlane_b32 s4, v250, 56
	v_pk_add_f32 v[18:19], s[0:1], v[18:19]
	v_readlane_b32 s0, v250, 8
	v_readlane_b32 s1, v250, 40
	v_mov_b32_e32 v20, s2
	v_mov_b32_e32 v21, s4
	v_pk_add_f32 v[20:21], s[0:1], v[20:21]
	v_mov_b32_e32 v25, v18
	v_add_f32_e32 v26, v20, v21
	v_mov_b32_e32 v18, v17
	v_readlane_b32 s2, v250, 28
	v_readlane_b32 s4, v250, 60
	v_readlane_b32 s0, v250, 12
	v_readlane_b32 s1, v250, 44
	v_mov_b32_e32 v20, s2
	v_mov_b32_e32 v21, s4
	v_pk_add_f32 v[20:21], s[0:1], v[20:21]
	v_add_f32_e32 v27, v20, v21
	v_readlane_b32 s20, v94, 0
	v_readlane_b32 s4, v94, 16
	v_readlane_b32 s21, v94, 32
	v_readlane_b32 s5, v94, 48
	v_readlane_b32 s91, v94, 8
	v_readlane_b32 s95, v94, 24
	v_readlane_b32 s94, v94, 40
	v_readlane_b32 s92, v94, 56
	v_readlane_b32 s6, v94, 4
	v_readlane_b32 s75, v94, 20
	v_readlane_b32 s74, v94, 36
	v_readlane_b32 s84, v94, 52
	v_readlane_b32 s97, v94, 12
	v_readlane_b32 s9, v94, 28
	v_readlane_b32 s8, v94, 44
	v_readlane_b32 s12, v94, 60
	v_readlane_b32 s59, v125, 0
	v_readlane_b32 s61, v125, 16
	v_readlane_b32 s60, v125, 32
	v_readlane_b32 s82, v125, 48
	v_readlane_b32 s52, v125, 8
	v_readlane_b32 s54, v125, 24
	v_readlane_b32 s53, v125, 40
	v_readlane_b32 s93, v125, 56
	v_readlane_b32 s85, v125, 4
	v_readlane_b32 s87, v125, 20
	v_readlane_b32 s86, v125, 36
	v_readlane_b32 s90, v125, 52
	v_readlane_b32 s13, v125, 12
	v_readlane_b32 s24, v125, 28
	v_readlane_b32 s16, v125, 44
	v_readlane_b32 s17, v125, 60
	v_readlane_b32 s83, v111, 0
	v_readlane_b32 s89, v111, 16
	v_readlane_b32 s88, v111, 32
	v_readlane_b32 s96, v111, 48
	v_readlane_b32 s55, v111, 8
	v_readlane_b32 s57, v111, 24
	v_readlane_b32 s56, v111, 40
	v_readlane_b32 s58, v111, 56
	v_readlane_b32 s46, v111, 4
	v_readlane_b32 s48, v111, 20
	v_readlane_b32 s47, v111, 36
	v_readlane_b32 s49, v111, 52
	v_readlane_b32 s38, v111, 12
	v_readlane_b32 s40, v111, 28
	v_readlane_b32 s39, v111, 44
	v_readlane_b32 s41, v111, 60
	v_readlane_b32 s34, v103, 0
	v_readlane_b32 s36, v103, 16
	v_readlane_b32 s35, v103, 32
	v_readlane_b32 s37, v103, 48
	v_readlane_b32 s29, v103, 8
	v_readlane_b32 s31, v103, 24
	v_readlane_b32 s30, v103, 40
	v_readlane_b32 s33, v103, 56
	v_readlane_b32 s25, v103, 4
	v_readlane_b32 s28, v103, 20
	v_readlane_b32 s50, v103, 36
	v_readlane_b32 s51, v103, 52
	v_mov_b32_e32 v24, v16
	v_pk_add_f32 v[16:17], v[24:25], v[18:19]
	v_mov_b32_e32 v20, v178
	v_mov_b32_e32 v21, v179
	v_mov_b32_e32 v22, v180
	v_mov_b32_e32 v23, v181
	v_add_f32_e32 v19, v26, v22
	v_pk_add_f32 v[16:17], v[16:17], v[20:21]
	v_add_f32_e32 v18, v27, v23
	v_cmp_gt_f32_e32 vcc, v17, v16
	v_mov_b32_e32 v22, 0
	v_readlane_b32 s42, v103, 12
	v_cndmask_b32_e32 v20, v16, v17, vcc
	v_cmp_gt_f32_e64 s[18:19], v19, v20
	v_cndmask_b32_e64 v21, 0, 1, vcc
	s_and_b64 s[14:15], s[18:19], exec
	v_cndmask_b32_e64 v20, v20, v19, s[18:19]
	v_cmp_ngt_f32_e64 s[0:1], v18, v20
	v_readfirstlane_b32 s2, v21
	s_cselect_b32 s2, 2, s2
	s_and_b64 s[14:15], s[0:1], exec
	s_cselect_b32 s2, s2, 3
	s_cmp_eq_u32 s2, 0
	s_cselect_b64 s[26:27], -1, 0
	s_cmp_lg_u32 s2, 0
	v_mov_b32_e32 v21, 0
	v_readlane_b32 s44, v103, 28
	v_readlane_b32 s43, v103, 44
	v_readlane_b32 s45, v103, 60
	v_cmp_gt_f32_e64 s[14:15], v18, v20
	s_waitcnt lgkmcnt(0)
	s_cbranch_scc0 .LBB0_560
	v_cndmask_b32_e64 v23, 0, 1, s[26:27]
	v_cmp_ne_u32_e64 s[20:21], 1, v23
	s_andn2_b64 vcc, exec, s[26:27]
	s_cbranch_vccz .LBB0_561

.LBB0_1669:
	s_or_b64 exec, exec, s[0:1]
	s_add_u32 s0, s70, 0x10000
	s_waitcnt vmcnt(17)
	v_mov_b32_e32 v56, v128
	s_waitcnt lgkmcnt(0)
	s_barrier
	s_addc_u32 s1, s71, 0
	s_nop 0
	v_ashrrev_i32_e32 v57, 31, v56
	v_add_u32_e32 v66, 0x100, v56
	v_lshl_add_u64 v[8:9], v[56:57], 4, s[0:1]
	v_ashrrev_i32_e32 v67, 31, v66
	v_add_u32_e32 v68, 0x200, v56
	v_add_u32_e32 v70, 0x300, v56
	s_barrier
	v_lshl_add_u64 v[10:11], v[66:67], 4, s[0:1]
	global_load_dwordx4 v[0:3], v[8:9], off
	global_load_dwordx4 v[4:7], v[10:11], off
	v_ashrrev_i32_e32 v69, 31, v68
	v_ashrrev_i32_e32 v71, 31, v70
	v_lshl_add_u64 v[8:9], v[68:69], 4, s[0:1]
	v_lshl_add_u64 v[12:13], v[70:71], 4, s[0:1]
	v_add_u32_e32 v72, 0x400, v56
	global_load_dwordx4 v[8:11], v[8:9], off
	v_ashrrev_i32_e32 v73, 31, v72
	global_load_dwordx4 v[12:15], v[12:13], off nt
	v_lshl_add_u64 v[16:17], v[72:73], 4, s[0:1]
	v_add_u32_e32 v74, 0x500, v56
	global_load_dwordx4 v[16:19], v[16:17], off
	v_ashrrev_i32_e32 v75, 31, v74
	v_lshl_add_u64 v[20:21], v[74:75], 4, s[0:1]
	v_add_u32_e32 v76, 0x600, v56
	global_load_dwordx4 v[20:23], v[20:21], off
	v_ashrrev_i32_e32 v77, 31, v76
	v_lshl_add_u64 v[24:25], v[76:77], 4, s[0:1]
	v_add_u32_e32 v78, 0x700, v56
	global_load_dwordx4 v[24:27], v[24:25], off
	v_ashrrev_i32_e32 v79, 31, v78
	v_lshl_add_u64 v[28:29], v[78:79], 4, s[0:1]
	v_add_u32_e32 v80, 0x800, v56
	global_load_dwordx4 v[28:31], v[28:29], off
	v_ashrrev_i32_e32 v81, 31, v80
	v_lshl_add_u64 v[32:33], v[80:81], 4, s[0:1]
	v_add_u32_e32 v82, 0x900, v56
	global_load_dwordx4 v[32:35], v[32:33], off
	v_ashrrev_i32_e32 v83, 31, v82
	v_lshl_add_u64 v[36:37], v[82:83], 4, s[0:1]
	v_add_u32_e32 v84, 0xa00, v56
	global_load_dwordx4 v[36:39], v[36:37], off
	v_ashrrev_i32_e32 v85, 31, v84
	v_lshl_add_u64 v[40:41], v[84:85], 4, s[0:1]
	v_add_u32_e32 v86, 0xb00, v56
	global_load_dwordx4 v[40:43], v[40:41], off
	v_ashrrev_i32_e32 v87, 31, v86
	v_lshl_add_u64 v[44:45], v[86:87], 4, s[0:1]
	v_add_u32_e32 v88, 0xc00, v56
	global_load_dwordx4 v[44:47], v[44:45], off
	v_ashrrev_i32_e32 v89, 31, v88
	v_lshl_add_u64 v[48:49], v[88:89], 4, s[0:1]
	v_add_u32_e32 v90, 0xd00, v56
	global_load_dwordx4 v[48:51], v[48:49], off
	v_ashrrev_i32_e32 v91, 31, v90
	v_lshl_add_u64 v[52:53], v[90:91], 4, s[0:1]
	v_add_u32_e32 v92, 0xe00, v56
	global_load_dwordx4 v[52:55], v[52:53], off
	v_ashrrev_i32_e32 v93, 31, v92
	v_lshl_add_u64 v[58:59], v[92:93], 4, s[0:1]
	v_add_u32_e32 v94, 0xf00, v56
	global_load_dwordx4 v[58:61], v[58:59], off
	v_ashrrev_i32_e32 v95, 31, v94
	s_waitcnt vmcnt(31)
	v_lshl_add_u64 v[62:63], v[94:95], 4, s[0:1]
	global_load_dwordx4 v[62:65], v[62:63], off
	v_lshlrev_b32_e32 v67, 14, v56
	v_and_b32_e32 v69, -4, v56
	v_and_b32_e32 v67, 0xc000, v67
	v_and_b32_e32 v66, -4, v66
	v_and_b32_e32 v68, -4, v68
	v_add_u32_e32 v69, v67, v69
	v_add_u32_e32 v66, v67, v66
	v_add_u32_e32 v68, v67, v68
	v_readlane_b32 s0, v237, 46
	v_readlane_b32 s1, v237, 47
	s_andn2_b64 vcc, exec, s[0:1]
	s_waitcnt vmcnt(15)
	ds_write2st64_b32 v69, v0, v1 offset1:16
	ds_write2st64_b32 v69, v2, v3 offset0:32 offset1:48
	s_waitcnt vmcnt(14)
	ds_write2st64_b32 v66, v4, v5 offset1:16
	ds_write2st64_b32 v66, v6, v7 offset0:32 offset1:48
	s_waitcnt vmcnt(13)
	ds_write2st64_b32 v68, v8, v9 offset1:16
	ds_write2st64_b32 v68, v10, v11 offset0:32 offset1:48
	v_and_b32_e32 v0, -4, v70
	v_add_u32_e32 v0, v67, v0
	s_waitcnt vmcnt(12)
	ds_write2st64_b32 v0, v12, v13 offset1:16
	ds_write2st64_b32 v0, v14, v15 offset0:32 offset1:48
	v_and_b32_e32 v0, -4, v72
	v_add_u32_e32 v0, v67, v0
	s_waitcnt vmcnt(11)
	ds_write2st64_b32 v0, v16, v17 offset1:16
	ds_write2st64_b32 v0, v18, v19 offset0:32 offset1:48
	v_and_b32_e32 v0, -4, v74
	v_add_u32_e32 v0, v67, v0
	s_waitcnt vmcnt(10)
	ds_write2st64_b32 v0, v20, v21 offset1:16
	ds_write2st64_b32 v0, v22, v23 offset0:32 offset1:48
	v_and_b32_e32 v0, -4, v76
	v_add_u32_e32 v0, v67, v0
	s_waitcnt vmcnt(9)
	ds_write2st64_b32 v0, v24, v25 offset1:16
	ds_write2st64_b32 v0, v26, v27 offset0:32 offset1:48
	v_and_b32_e32 v0, -4, v78
	v_add_u32_e32 v0, v67, v0
	s_waitcnt vmcnt(8)
	ds_write2st64_b32 v0, v28, v29 offset1:16
	ds_write2st64_b32 v0, v30, v31 offset0:32 offset1:48
	v_and_b32_e32 v0, -4, v80
	v_add_u32_e32 v0, v67, v0
	s_waitcnt vmcnt(7)
	ds_write2st64_b32 v0, v32, v33 offset1:16
	ds_write2st64_b32 v0, v34, v35 offset0:32 offset1:48
	v_and_b32_e32 v0, -4, v82
	v_add_u32_e32 v0, v67, v0
	s_waitcnt vmcnt(6)
	ds_write2st64_b32 v0, v36, v37 offset1:16
	ds_write2st64_b32 v0, v38, v39 offset0:32 offset1:48
	v_and_b32_e32 v0, -4, v84
	v_add_u32_e32 v0, v67, v0
	s_waitcnt vmcnt(5)
	ds_write2st64_b32 v0, v40, v41 offset1:16
	ds_write2st64_b32 v0, v42, v43 offset0:32 offset1:48
	v_and_b32_e32 v0, -4, v86
	v_add_u32_e32 v0, v67, v0
	s_waitcnt vmcnt(4)
	ds_write2st64_b32 v0, v44, v45 offset1:16
	ds_write2st64_b32 v0, v46, v47 offset0:32 offset1:48
	v_and_b32_e32 v0, -4, v88
	v_add_u32_e32 v0, v67, v0
	s_waitcnt vmcnt(3)
	ds_write2st64_b32 v0, v48, v49 offset1:16
	ds_write2st64_b32 v0, v50, v51 offset0:32 offset1:48
	v_and_b32_e32 v0, -4, v90
	v_add_u32_e32 v0, v67, v0
	s_waitcnt vmcnt(2)
	ds_write2st64_b32 v0, v52, v53 offset1:16
	ds_write2st64_b32 v0, v54, v55 offset0:32 offset1:48
	v_and_b32_e32 v0, -4, v92
	v_add_u32_e32 v0, v67, v0
	s_waitcnt vmcnt(1)
	ds_write2st64_b32 v0, v58, v59 offset1:16
	ds_write2st64_b32 v0, v60, v61 offset0:32 offset1:48
	v_and_b32_e32 v0, -4, v94
	v_add_u32_e32 v0, v67, v0
	s_waitcnt vmcnt(0)
	ds_write2st64_b32 v0, v62, v63 offset1:16
	ds_write2st64_b32 v0, v64, v65 offset0:32 offset1:48
	s_waitcnt lgkmcnt(0)
	s_barrier
	s_cbranch_vccnz .LBB0_1718
	v_and_b32_e32 v5, 63, v56
	v_readlane_b32 s8, v237, 48
	v_lshlrev_b32_e32 v60, 4, v5
	v_mov_b32_e32 v61, 0
	v_readlane_b32 s12, v237, 52
	v_readlane_b32 s13, v237, 53
	v_readlane_b32 s14, v237, 54
	v_readlane_b32 s15, v237, 55
	v_lshl_add_u64 v[2:3], s[62:63], 0, v[60:61]
	s_mov_b64 s[0:1], 0x1000
	v_lshl_add_u64 v[62:63], s[14:15], 0, v[60:61]
	v_readlane_b32 s12, v237, 56
	v_lshl_add_u64 v[66:67], v[2:3], 0, s[0:1]
	v_lshl_add_u64 v[2:3], s[64:65], 0, v[60:61]
	v_readlane_b32 s13, v237, 57
	v_lshl_add_u64 v[68:69], v[2:3], 0, s[0:1]
	v_lshrrev_b32_e32 v250, 6, v56
	v_lshlrev_b32_e32 v250, 10, v250
	v_mov_b32_e32 v251, 0
	v_lshl_add_u64 v[252:253], v[66:67], 0, v[250:251]
	global_load_dwordx4 v[186:189], v[252:253], off
	v_lshl_add_u64 v[252:253], v[68:69], 0, v[250:251]
	global_load_dwordx4 v[190:193], v[252:253], off
	v_lshlrev_b32_e32 v250, 4, v56
	v_add_u32_e32 v250, 0x10400, v250
	s_waitcnt vmcnt(0)
	ds_write_b128 v250, v[186:189]
	ds_write_b128 v250, v[190:193] offset:4096
	v_add_u32_e32 v234, 0x10400, v60
	s_waitcnt lgkmcnt(0)
	s_mov_b64 s[0:1], 0x3d00080
	v_lshl_add_u64 v[2:3], v[56:57], 2, s[12:13]
	v_lshl_add_u64 v[70:71], v[2:3], 0, s[0:1]
	v_lshlrev_b32_e32 v2, 6, v5
	v_mov_b32_e32 v3, v61
	v_lshl_add_u64 v[2:3], s[66:67], 0, v[2:3]
	s_mov_b64 s[0:1], 0x4000
	v_lshl_add_u64 v[72:73], v[2:3], 0, s[0:1]
	s_mov_b64 s[0:1], 0x5000
	v_lshl_add_u64 v[74:75], v[2:3], 0, s[0:1]
	s_mov_b64 s[0:1], 0x6000
	v_lshl_add_u64 v[76:77], v[2:3], 0, s[0:1]
	s_mov_b64 s[0:1], 0x7000
	v_lshl_add_u64 v[78:79], v[2:3], 0, s[0:1]
	v_readlane_b32 s0, v237, 31
	v_ashrrev_i32_e32 v4, 2, v56
	v_lshlrev_b32_e32 v0, 3, v5
	v_mov_b32_e32 v1, v61
	v_readlane_b32 s1, v237, 32
	v_lshlrev_b32_e32 v6, 2, v56
	v_and_b32_e32 v58, -16, v4
	v_readlane_b32 s9, v237, 49
	v_lshl_add_u64 v[64:65], s[46:47], 0, v[0:1]
	v_readlane_b32 s14, v237, 58
	s_mov_b32 s2, s0
	s_lshl_b32 s18, s0, 6
	v_mov_b32_e32 v2, 0x10000
	v_lshl_add_u64 v[0:1], s[12:13], 0, v[0:1]
	s_mov_b64 s[0:1], 0x4500400
	v_cmp_gt_i32_e64 s[4:5], 24, v56
	v_add_u32_e32 v99, 0x10100, v6
	v_ashrrev_i32_e32 v59, 31, v58
	s_mov_b32 s3, 0
	v_cmp_eq_u32_e64 s[6:7], 0, v5
	v_cmp_gt_i32_e64 s[8:9], 64, v56
	v_add_u32_e32 v112, 0x10000, v6
	v_add_u32_e32 v113, 0x10200, v6
	v_add_u32_e32 v57, 0x10180, v6
	v_add_u32_e32 v114, s18, v4
	s_lshl_b32 s16, s14, 6
	v_lshl_add_u32 v115, v4, 2, v2
	v_lshl_add_u64 v[80:81], v[0:1], 0, s[0:1]
	s_mov_b32 s20, 0x3fb504f3
	v_mov_b32_e32 v116, 0x3727c5ac
	v_mov_b32_e32 v117, 1
	v_mov_b32_e32 v118, 0xff61b1e6
	v_mov_b32_e32 v119, 0x10100
	v_mov_b32_e32 v120, 0x10180
	s_mov_b32 s17, s2
	v_readlane_b32 s10, v237, 50
	v_readlane_b32 s11, v237, 51
	v_readlane_b32 s15, v237, 59
	s_branch .LBB0_1672

.LBB0_1676:
	s_add_i32 s21, s19, 1
	s_waitcnt vmcnt(0)
	v_mov_b64_e32 v[38:39], v[84:85]
	v_mov_b64_e32 v[32:33], v[92:93]
	v_mov_b64_e32 v[34:35], v[90:91]
	v_mov_b64_e32 v[36:37], v[88:89]
	v_mov_b32_e32 v0, s21
	v_min_u32_e32 v0, 15, v0
	v_mov_b32_e32 v1, 0
	v_lshl_add_u64 v[0:1], v[82:83], 0, v[0:1]
	v_lshlrev_b64 v[2:3], 12, v[0:1]
	v_lshlrev_b64 v[0:1], 11, v[0:1]
	v_lshl_add_u64 v[12:13], v[62:63], 0, v[2:3]
	v_lshl_add_u64 v[92:93], v[64:65], 0, v[0:1]
	global_load_dwordx4 v[0:3], v[12:13], off nt
	global_load_dwordx2 v[84:85], v[92:93], off nt
	global_load_dwordx4 v[4:7], v[12:13], off offset:1024 nt
	global_load_dwordx2 v[88:89], v[92:93], off offset:512 nt
	global_load_dwordx4 v[8:11], v[12:13], off offset:2048 nt
	global_load_dwordx2 v[90:91], v[92:93], off offset:1024 nt
	s_nop 0
	global_load_dwordx4 v[12:15], v[12:13], off offset:3072 nt
	s_nop 0
	global_load_dwordx2 v[92:93], v[92:93], off offset:1536 nt
	v_lshlrev_b32_e32 v40, 16, v38
	v_and_b32_e32 v41, 0xffff0000, v38
	v_lshlrev_b32_e32 v38, 16, v39
	v_and_b32_e32 v39, 0xffff0000, v39
	v_lshlrev_b32_e32 v54, 16, v36
	v_and_b32_e32 v55, 0xffff0000, v36
	v_lshlrev_b32_e32 v94, 16, v37
	v_and_b32_e32 v95, 0xffff0000, v37
	v_lshlrev_b32_e32 v96, 16, v34
	v_and_b32_e32 v97, 0xffff0000, v34
	v_lshlrev_b32_e32 v100, 16, v35
	v_and_b32_e32 v101, 0xffff0000, v35
	v_lshlrev_b32_e32 v102, 16, v32
	v_and_b32_e32 v103, 0xffff0000, v32
	v_lshlrev_b32_e32 v104, 16, v33
	v_and_b32_e32 v105, 0xffff0000, v33
	v_pk_fma_f32 v[106:107], v[30:31], s[20:21], v[38:39] op_sel_hi:[1,0,1]
	ds_read_b128 v[30:33], v234
	ds_read_b128 v[34:37], v234 offset:4096
	v_pk_fma_f32 v[28:29], v[28:29], s[20:21], v[40:41] op_sel_hi:[1,0,1]
	v_pk_fma_f32 v[20:21], v[20:21], s[20:21], v[54:55] op_sel_hi:[1,0,1]
	v_add_f32_e32 v38, v28, v29
	v_add_f32_e32 v38, v38, v106
	v_pk_fma_f32 v[22:23], v[22:23], s[20:21], v[94:95] op_sel_hi:[1,0,1]
	v_add_f32_e32 v54, v20, v21
	v_pk_fma_f32 v[24:25], v[24:25], s[20:21], v[96:97] op_sel_hi:[1,0,1]
	v_add_f32_e32 v38, v107, v38
	v_add_f32_e32 v54, v54, v22
	v_pk_fma_f32 v[26:27], v[26:27], s[20:21], v[100:101] op_sel_hi:[1,0,1]
	v_add_f32_e32 v55, v24, v25
	v_add_f32_e32 v98, 0, v38
	v_add_f32_e32 v54, v23, v54
	v_add_f32_e32 v55, v55, v26
	v_add_f32_e32 v54, v98, v54
	v_add_f32_e32 v55, v27, v55
	v_pk_fma_f32 v[16:17], v[16:17], s[20:21], v[102:103] op_sel_hi:[1,0,1]
	v_add_f32_e32 v54, v54, v55
	v_pk_fma_f32 v[18:19], v[18:19], s[20:21], v[104:105] op_sel_hi:[1,0,1]
	v_add_f32_e32 v55, v16, v17
	v_add_f32_e32 v55, v55, v18
	v_add_f32_e32 v55, v19, v55
	v_add_f32_e32 v54, v54, v55
	ds_read_b128 v[38:41], v60
	ds_read_b128 v[42:45], v60 offset:4096
	ds_read_b128 v[46:49], v60 offset:8192
	ds_read_b128 v[50:53], v60 offset:12288
	ds_read_b128 v[108:111], v60 offset:16384
	ds_read_b128 v[122:125], v60 offset:20480
	ds_read_b128 v[130:133], v60 offset:24576
	ds_read_b128 v[134:137], v60 offset:28672
	ds_read_b128 v[138:141], v60 offset:32768
	ds_read_b128 v[142:145], v60 offset:36864
	ds_read_b128 v[146:149], v60 offset:40960
	ds_read_b128 v[150:153], v60 offset:45056
	ds_read_b128 v[154:157], v60 offset:49152
	v_add_f32_dpp v54, v54, v54 quad_perm:[1,0,3,2] row_mask:0xf bank_mask:0xf bound_ctrl:1
	s_nop 1
	v_add_f32_dpp v54, v54, v54 quad_perm:[2,3,0,1] row_mask:0xf bank_mask:0xf bound_ctrl:1
	s_nop 1
	v_add_f32_dpp v54, v54, v54 row_half_mirror row_mask:0xf bank_mask:0xf bound_ctrl:1
	s_nop 1
	v_add_f32_dpp v54, v54, v54 row_mirror row_mask:0xf bank_mask:0xf bound_ctrl:1
	s_nop 0
	v_readlane_b32 s2, v54, 16
	v_readlane_b32 s10, v54, 48
	v_readlane_b32 s0, v54, 0
	v_readlane_b32 s1, v54, 32
	v_mov_b32_e32 v54, s2
	v_mov_b32_e32 v55, s10
	v_pk_add_f32 v[54:55], s[0:1], v[54:55]
	s_nop 0
	v_add_f32_e32 v54, v54, v55
	v_mul_f32_e32 v54, 0x3a800000, v54
	v_pk_add_f32 v[28:29], v[28:29], v[54:55] op_sel_hi:[1,0] neg_lo:[0,1] neg_hi:[0,1]
	v_pk_add_f32 v[126:127], v[106:107], v[54:55] op_sel_hi:[1,0] neg_lo:[0,1] neg_hi:[0,1]
	v_pk_mul_f32 v[104:105], v[28:29], v[28:29]
	v_pk_mul_f32 v[106:107], v[126:127], v[126:127]
	v_pk_add_f32 v[158:159], v[20:21], v[54:55] op_sel_hi:[1,0] neg_lo:[0,1] neg_hi:[0,1]
	v_pk_add_f32 v[160:161], v[22:23], v[54:55] op_sel_hi:[1,0] neg_lo:[0,1] neg_hi:[0,1]
	v_pk_add_f32 v[100:101], v[24:25], v[54:55] op_sel_hi:[1,0] neg_lo:[0,1] neg_hi:[0,1]
	v_pk_add_f32 v[102:103], v[26:27], v[54:55] op_sel_hi:[1,0] neg_lo:[0,1] neg_hi:[0,1]
	v_pk_add_f32 v[94:95], v[16:17], v[54:55] op_sel_hi:[1,0] neg_lo:[0,1] neg_hi:[0,1]
	v_pk_add_f32 v[96:97], v[18:19], v[54:55] op_sel_hi:[1,0] neg_lo:[0,1] neg_hi:[0,1]
	v_add_f32_e32 v54, v104, v105
	v_add_f32_e32 v54, v106, v54
	v_pk_mul_f32 v[20:21], v[158:159], v[158:159]
	v_add_f32_e32 v54, v107, v54
	v_add_f32_e32 v20, v20, v54
	v_pk_mul_f32 v[22:23], v[160:161], v[160:161]
	v_add_f32_e32 v20, v21, v20
	v_add_f32_e32 v20, v22, v20
	v_pk_mul_f32 v[24:25], v[100:101], v[100:101]
	v_add_f32_e32 v20, v23, v20
	v_add_f32_e32 v20, v24, v20
	v_pk_mul_f32 v[26:27], v[102:103], v[102:103]
	v_add_f32_e32 v20, v25, v20
	v_add_f32_e32 v20, v26, v20
	v_pk_mul_f32 v[16:17], v[94:95], v[94:95]
	v_add_f32_e32 v20, v27, v20
	v_add_f32_e32 v16, v16, v20
	v_pk_mul_f32 v[18:19], v[96:97], v[96:97]
	v_add_f32_e32 v16, v17, v16
	v_add_f32_e32 v16, v18, v16
	v_add_f32_e32 v16, v19, v16
	s_nop 1
	v_add_f32_dpp v16, v16, v16 quad_perm:[1,0,3,2] row_mask:0xf bank_mask:0xf bound_ctrl:1
	s_nop 1
	v_add_f32_dpp v16, v16, v16 quad_perm:[2,3,0,1] row_mask:0xf bank_mask:0xf bound_ctrl:1
	s_nop 1
	v_add_f32_dpp v16, v16, v16 row_half_mirror row_mask:0xf bank_mask:0xf bound_ctrl:1
	s_nop 1
	v_add_f32_dpp v16, v16, v16 row_mirror row_mask:0xf bank_mask:0xf bound_ctrl:1
	s_nop 0
	v_readlane_b32 s2, v16, 16
	v_readlane_b32 s10, v16, 48
	v_readlane_b32 s0, v16, 0
	v_readlane_b32 s1, v16, 32
	v_mov_b32_e32 v16, s2
	v_mov_b32_e32 v17, s10
	v_pk_add_f32 v[16:17], s[0:1], v[16:17]
	s_mov_b32 s0, 0x800000
	v_add_f32_e32 v16, v16, v17
	v_fmamk_f32 v16, v16, 0x3a800000, v116
	v_cmp_gt_f32_e32 vcc, s0, v16
	v_mul_f32_e32 v17, 0x4b800000, v16
	s_nop 0
	v_cndmask_b32_e32 v16, v16, v17, vcc
	v_rsq_f32_e32 v54, v16
	ds_read_b128 v[16:19], v60 offset:53248
	s_waitcnt lgkmcnt(15)
	ds_read_b128 v[20:23], v60 offset:57344
	s_waitcnt lgkmcnt(15)
	ds_read_b128 v[24:27], v60 offset:61440
	s_waitcnt lgkmcnt(15)
	v_mul_f32_e32 v55, 0x45800000, v54
	v_cndmask_b32_e32 v98, v54, v55, vcc
	v_pk_mul_f32 v[28:29], v[28:29], v[98:99] op_sel_hi:[1,0]
	v_pk_fma_f32 v[106:107], v[30:31], v[28:29], v[34:35]
	v_pk_mul_f32 v[28:29], v[126:127], v[98:99] op_sel_hi:[1,0]
	s_waitcnt lgkmcnt(2)
	v_mul_f32_e32 v17, v107, v17
	v_pk_fma_f32 v[104:105], v[32:33], v[28:29], v[36:37]
	v_cvt_pk_bf16_f32 v28, v106, v107
	v_cvt_pk_bf16_f32 v29, v104, v105
	global_store_dwordx2 v[86:87], v[28:29], off offset:-1024
	v_mul_f32_e32 v54, v39, v107
	v_fmac_f32_e32 v54, v38, v106
	ds_read_b128 v[32:35], v234 offset:1024
	ds_read_b128 v[36:39], v234 offset:5120
	v_fmac_f32_e32 v54, v104, v40
	v_fmac_f32_e32 v54, v105, v41
	v_mul_f32_e32 v55, v107, v43
	v_fmac_f32_e32 v55, v106, v42
	v_fmac_f32_e32 v55, v104, v44
	v_fmac_f32_e32 v55, v105, v45
	v_mul_f32_e32 v28, v107, v47
	v_fmac_f32_e32 v28, v106, v46
	v_fmac_f32_e32 v28, v104, v48
	v_fmac_f32_e32 v28, v105, v49
	v_add_f32_e32 v46, 0, v28
	v_mul_f32_e32 v45, v107, v51
	v_fmac_f32_e32 v45, v106, v50
	v_fmac_f32_e32 v45, v104, v52
	v_fmac_f32_e32 v45, v105, v53
	v_mul_f32_e32 v44, v107, v109
	v_fmac_f32_e32 v44, v106, v108
	v_fmac_f32_e32 v44, v104, v110
	v_fmac_f32_e32 v44, v105, v111
	v_mul_f32_e32 v53, v107, v123
	v_fmac_f32_e32 v53, v106, v122
	v_fmac_f32_e32 v53, v104, v124
	v_fmac_f32_e32 v53, v105, v125
	v_mul_f32_e32 v52, v107, v131
	v_fmac_f32_e32 v52, v106, v130
	v_fmac_f32_e32 v52, v104, v132
	v_fmac_f32_e32 v52, v105, v133
	v_mul_f32_e32 v51, v107, v135
	v_fmac_f32_e32 v51, v106, v134
	v_fmac_f32_e32 v51, v104, v136
	v_fmac_f32_e32 v51, v105, v137
	v_mul_f32_e32 v50, v107, v139
	v_fmac_f32_e32 v50, v106, v138
	v_fmac_f32_e32 v50, v104, v140
	v_fmac_f32_e32 v50, v105, v141
	v_mul_f32_e32 v49, v107, v143
	v_fmac_f32_e32 v49, v106, v142
	v_fmac_f32_e32 v49, v104, v144
	v_fmac_f32_e32 v49, v105, v145
	v_mul_f32_e32 v48, v107, v147
	v_fmac_f32_e32 v48, v106, v146
	v_fmac_f32_e32 v48, v104, v148
	v_fmac_f32_e32 v48, v105, v149
	v_mul_f32_e32 v131, v107, v151
	v_fmac_f32_e32 v17, v106, v16
	s_waitcnt lgkmcnt(3)
	v_mul_f32_e32 v122, v107, v21
	v_fmac_f32_e32 v131, v106, v150
	v_fmac_f32_e32 v122, v106, v20
	v_fmac_f32_e32 v131, v104, v152
	v_fmac_f32_e32 v122, v104, v22
	v_fmac_f32_e32 v131, v105, v153
	v_fmac_f32_e32 v122, v105, v23
	v_mul_f32_e32 v125, v107, v155
	s_waitcnt lgkmcnt(2)
	v_mul_f32_e32 v123, v107, v25
	v_fmac_f32_e32 v125, v106, v154
	v_fmac_f32_e32 v123, v106, v24
	v_fmac_f32_e32 v125, v104, v156
	v_fmac_f32_e32 v17, v104, v18
	v_fmac_f32_e32 v123, v104, v26
	v_fmac_f32_e32 v125, v105, v157
	v_fmac_f32_e32 v17, v105, v19
	v_fmac_f32_e32 v123, v105, v27
	v_pk_mul_f32 v[40:41], v[158:159], v[98:99] op_sel_hi:[1,0]
	v_add_f32_e32 v124, 0, v17
	s_waitcnt lgkmcnt(0)
	v_pk_fma_f32 v[108:109], v[40:41], v[32:33], v[36:37]
	ds_read_b128 v[40:43], v60 offset:1024
	ds_read_b128 v[134:137], v60 offset:21504
	v_pk_mul_f32 v[32:33], v[160:161], v[98:99] op_sel_hi:[1,0]
	ds_read_b128 v[142:145], v60 offset:29696
	v_pk_fma_f32 v[110:111], v[32:33], v[34:35], v[38:39]
	s_waitcnt lgkmcnt(2)
	v_fma_f32 v126, v109, v41, v54
	v_cvt_pk_bf16_f32 v32, v108, v109
	v_cvt_pk_bf16_f32 v33, v110, v111
	v_fmac_f32_e32 v126, v108, v40
	global_store_dwordx2 v[86:87], v[32:33], off offset:-512
	ds_read_b128 v[32:35], v60 offset:5120
	v_fmac_f32_e32 v126, v110, v42
	v_fmac_f32_e32 v126, v111, v43
	s_waitcnt lgkmcnt(2)
	v_fma_f32 v133, v109, v135, v53
	s_waitcnt lgkmcnt(1)
	v_fma_f32 v135, v109, v143, v51
	v_fmac_f32_e32 v135, v108, v142
	v_fmac_f32_e32 v135, v110, v144
	v_fmac_f32_e32 v135, v111, v145
	ds_read_b128 v[144:147], v60 offset:50176
	s_waitcnt lgkmcnt(1)
	v_fma_f32 v127, v109, v33, v55
	v_fmac_f32_e32 v127, v108, v32
	v_fmac_f32_e32 v127, v110, v34
	v_fmac_f32_e32 v127, v111, v35
	ds_read_b128 v[36:39], v60 offset:9216
	ds_read_b128 v[32:35], v60 offset:13312
	ds_read_b128 v[40:43], v60 offset:17408
	ds_read_b128 v[138:141], v60 offset:25600
	v_fmac_f32_e32 v133, v108, v134
	v_fmac_f32_e32 v133, v110, v136
	s_waitcnt lgkmcnt(3)
	v_fma_f32 v129, v109, v37, v46
	s_waitcnt lgkmcnt(2)
	v_fma_f32 v130, v109, v33, v45
	v_fmac_f32_e32 v133, v111, v137
	v_fmac_f32_e32 v129, v108, v36
	v_fmac_f32_e32 v130, v108, v32
	s_waitcnt lgkmcnt(0)
	v_fma_f32 v134, v109, v139, v52
	v_fmac_f32_e32 v129, v110, v38
	v_fmac_f32_e32 v130, v110, v34
	v_fma_f32 v132, v109, v41, v44
	v_fmac_f32_e32 v134, v108, v138
	v_fmac_f32_e32 v129, v111, v39
	v_fmac_f32_e32 v130, v111, v35
	v_fmac_f32_e32 v132, v108, v40
	v_fmac_f32_e32 v134, v110, v140
	v_fmac_f32_e32 v132, v110, v42
	v_fmac_f32_e32 v134, v111, v141
	v_fmac_f32_e32 v132, v111, v43
	ds_read_b128 v[52:55], v60 offset:33792
	ds_read_b128 v[138:141], v60 offset:37888
	s_waitcnt lgkmcnt(1)
	v_fma_f32 v136, v109, v53, v50
	v_fmac_f32_e32 v136, v108, v52
	v_fmac_f32_e32 v136, v110, v54
	v_fmac_f32_e32 v136, v111, v55
	ds_read_b128 v[50:53], v60 offset:41984
	s_waitcnt lgkmcnt(1)
	v_fma_f32 v137, v109, v139, v49
	v_fmac_f32_e32 v137, v108, v138
	v_fmac_f32_e32 v137, v110, v140
	v_fmac_f32_e32 v137, v111, v141
	ds_read_b128 v[140:143], v60 offset:46080
	s_waitcnt lgkmcnt(1)
	v_fma_f32 v138, v109, v51, v48
	v_fmac_f32_e32 v138, v108, v50
	v_fmac_f32_e32 v138, v110, v52
	v_fmac_f32_e32 v138, v111, v53
	ds_read_b128 v[48:51], v234 offset:2048
	ds_read_b128 v[52:55], v234 offset:6144
	s_waitcnt lgkmcnt(2)
	v_fma_f32 v131, v109, v141, v131
	v_fmac_f32_e32 v131, v108, v140
	v_fmac_f32_e32 v131, v110, v142
	v_fmac_f32_e32 v131, v111, v143
	ds_read_b128 v[140:143], v60 offset:54272
	v_fma_f32 v139, v109, v145, v125
	v_fmac_f32_e32 v139, v108, v144
	v_fmac_f32_e32 v139, v110, v146
	v_fmac_f32_e32 v139, v111, v147
	ds_read_b128 v[144:147], v60 offset:58368
	s_waitcnt lgkmcnt(1)
	v_fma_f32 v148, v109, v141, v124
	v_fmac_f32_e32 v148, v108, v140
	v_fmac_f32_e32 v148, v110, v142
	v_fmac_f32_e32 v148, v111, v143
	ds_read_b128 v[140:143], v60 offset:62464
	s_waitcnt lgkmcnt(1)
	v_mul_f32_e32 v124, v109, v145
	v_fmac_f32_e32 v124, v108, v144
	v_fmac_f32_e32 v124, v110, v146
	v_fmac_f32_e32 v124, v111, v147
	v_add_f32_e32 v144, v122, v124
	s_waitcnt lgkmcnt(0)
	v_mul_f32_e32 v122, v109, v141
	v_fmac_f32_e32 v122, v108, v140
	v_fmac_f32_e32 v122, v110, v142
	v_fmac_f32_e32 v122, v111, v143
	v_add_f32_e32 v142, v123, v122
	v_mov_b32_e32 v122, v106
	v_mov_b32_e32 v123, v108
	v_mov_b32_e32 v108, v107
	v_mov_b32_e32 v106, v186
	v_mov_b32_e32 v124, v182
	v_mov_b32_e32 v140, v190
	v_mov_b32_e32 v125, v198
	v_mov_b32_e32 v107, v202
	v_pk_mul_f32 v[106:107], v[108:109], v[106:107]
	v_mov_b32_e32 v36, v187
	v_pk_fma_f32 v[106:107], v[122:123], v[124:125], v[106:107]
	v_mov_b32_e32 v124, v104
	v_mov_b32_e32 v125, v110
	v_mov_b32_e32 v110, v105
	v_mov_b32_e32 v104, v194
	v_mov_b32_e32 v141, v206
	v_pk_fma_f32 v[106:107], v[124:125], v[140:141], v[106:107]
	v_mov_b32_e32 v105, v210
	v_mov_b32_e32 v32, v183
	v_mov_b32_e32 v37, v203
	v_pk_mul_f32 v[24:25], v[108:109], v[36:37]
	v_pk_fma_f32 v[104:105], v[110:111], v[104:105], v[106:107]
	v_mov_b32_e32 v33, v199
	v_pk_fma_f32 v[24:25], v[122:123], v[32:33], v[24:25]
	v_mov_b32_e32 v40, v191
	v_add_f32_e32 v16, 0, v104
	v_mov_b32_e32 v41, v207
	v_pk_fma_f32 v[20:21], v[124:125], v[40:41], v[24:25]
	v_mov_b32_e32 v44, v195
	v_add_f32_e32 v107, v16, v105
	v_mov_b32_e32 v45, v211
	v_pk_fma_f32 v[16:17], v[110:111], v[44:45], v[20:21]
	v_mov_b32_e32 v20, v188
	v_add_f32_e32 v16, 0, v16
	v_mov_b32_e32 v21, v204
	v_add_f32_e32 v105, v16, v17
	v_mov_b32_e32 v16, v184
	v_mov_b32_e32 v17, v200
	v_pk_mul_f32 v[20:21], v[108:109], v[20:21]
	v_mov_b32_e32 v38, v189
	v_pk_fma_f32 v[16:17], v[122:123], v[16:17], v[20:21]
	v_mov_b32_e32 v20, v192
	v_mov_b32_e32 v21, v208
	v_pk_fma_f32 v[16:17], v[124:125], v[20:21], v[16:17]
	v_mov_b32_e32 v20, v196
	v_mov_b32_e32 v21, v212
	v_pk_fma_f32 v[16:17], v[110:111], v[20:21], v[16:17]
	v_mov_b32_e32 v34, v185
	v_add_f32_e32 v16, 0, v16
	v_add_f32_e32 v106, v16, v17
	v_mov_b32_e32 v39, v205
	v_pk_mul_f32 v[16:17], v[108:109], v[38:39]
	v_mov_b32_e32 v42, v193
	v_mov_b32_e32 v35, v201
	v_pk_fma_f32 v[16:17], v[122:123], v[34:35], v[16:17]
	v_mov_b32_e32 v46, v197
	v_mov_b32_e32 v43, v209
	v_pk_fma_f32 v[16:17], v[124:125], v[42:43], v[16:17]
	v_pk_mul_f32 v[20:21], v[102:103], v[98:99] op_sel_hi:[1,0]
	v_mov_b32_e32 v47, v213
	v_pk_fma_f32 v[16:17], v[110:111], v[46:47], v[16:17]
	v_pk_fma_f32 v[50:51], v[20:21], v[50:51], v[54:55]
	v_add_f32_e32 v16, 0, v16
	v_add_f32_e32 v104, v16, v17
	v_pk_mul_f32 v[16:17], v[100:101], v[98:99] op_sel_hi:[1,0]
	v_cvt_pk_bf16_f32 v21, v50, v51
	v_pk_fma_f32 v[48:49], v[16:17], v[48:49], v[52:53]
	ds_read_b128 v[16:19], v60 offset:2048
	v_cvt_pk_bf16_f32 v20, v48, v49
	global_store_dwordx2 v[86:87], v[20:21], off
	ds_read_b128 v[20:23], v60 offset:6144
	v_pk_mul_f32 v[46:47], v[94:95], v[98:99] op_sel_hi:[1,0]
	s_waitcnt lgkmcnt(1)
	v_fma_f32 v42, v49, v17, v126
	v_fmac_f32_e32 v42, v48, v16
	v_fmac_f32_e32 v42, v50, v18
	v_fmac_f32_e32 v42, v51, v19
	ds_read_b128 v[16:19], v60 offset:10240
	s_waitcnt lgkmcnt(1)
	v_fma_f32 v41, v49, v21, v127
	v_fmac_f32_e32 v41, v48, v20
	v_fmac_f32_e32 v41, v50, v22
	v_fmac_f32_e32 v41, v51, v23
	ds_read_b128 v[20:23], v60 offset:14336
	s_waitcnt lgkmcnt(1)
	v_fma_f32 v40, v49, v17, v129
	v_fmac_f32_e32 v40, v48, v16
	v_fmac_f32_e32 v40, v50, v18
	v_fmac_f32_e32 v40, v51, v19
	ds_read_b128 v[16:19], v60 offset:18432
	ds_read_b128 v[32:35], v234 offset:3072
	ds_read_b128 v[36:39], v234 offset:7168
	s_waitcnt lgkmcnt(3)
	v_fma_f32 v45, v49, v21, v130
	v_fmac_f32_e32 v45, v48, v20
	v_fmac_f32_e32 v45, v50, v22
	v_fmac_f32_e32 v45, v51, v23
	ds_read_b128 v[20:23], v60 offset:22528
	s_waitcnt lgkmcnt(3)
	v_fma_f32 v44, v49, v17, v132
	v_fmac_f32_e32 v44, v48, v16
	v_fmac_f32_e32 v44, v50, v18
	v_fmac_f32_e32 v44, v51, v19
	ds_read_b128 v[16:19], v60 offset:26624
	s_waitcnt lgkmcnt(1)
	v_fma_f32 v124, v49, v21, v133
	v_fmac_f32_e32 v124, v48, v20
	v_fmac_f32_e32 v124, v50, v22
	v_fmac_f32_e32 v124, v51, v23
	ds_read_b128 v[20:23], v60 offset:30720
	s_waitcnt lgkmcnt(1)
	v_fma_f32 v123, v49, v17, v134
	v_fmac_f32_e32 v123, v48, v16
	v_fmac_f32_e32 v123, v50, v18
	v_fmac_f32_e32 v123, v51, v19
	s_waitcnt lgkmcnt(0)
	v_fma_f32 v122, v49, v21, v135
	v_fmac_f32_e32 v122, v48, v20
	v_fmac_f32_e32 v122, v50, v22
	ds_read_b128 v[16:19], v60 offset:34816
	v_fmac_f32_e32 v122, v51, v23
	ds_read_b128 v[20:23], v60 offset:38912
	s_waitcnt lgkmcnt(1)
	v_fma_f32 v111, v49, v17, v136
	v_fmac_f32_e32 v111, v48, v16
	v_fmac_f32_e32 v111, v50, v18
	s_waitcnt lgkmcnt(0)
	v_fma_f32 v110, v49, v21, v137
	v_fmac_f32_e32 v110, v48, v20
	v_fmac_f32_e32 v111, v51, v19
	v_fmac_f32_e32 v110, v50, v22
	ds_read_b128 v[16:19], v60 offset:43008
	v_fmac_f32_e32 v110, v51, v23
	ds_read_b128 v[20:23], v60 offset:47104
	s_waitcnt lgkmcnt(1)
	v_fma_f32 v109, v49, v17, v138
	v_fmac_f32_e32 v109, v48, v16
	v_fmac_f32_e32 v109, v50, v18
	s_waitcnt lgkmcnt(0)
	v_fma_f32 v108, v49, v21, v131
	v_fmac_f32_e32 v108, v48, v20
	v_fmac_f32_e32 v109, v51, v19
	v_fmac_f32_e32 v108, v50, v22
	ds_read_b128 v[16:19], v60 offset:51200
	v_fmac_f32_e32 v108, v51, v23
	ds_read_b128 v[20:23], v60 offset:55296
	s_waitcnt lgkmcnt(1)
	v_fma_f32 v103, v49, v17, v139
	v_fmac_f32_e32 v103, v48, v16
	v_fmac_f32_e32 v103, v50, v18
	s_waitcnt lgkmcnt(0)
	v_fma_f32 v102, v49, v21, v148
	v_fmac_f32_e32 v102, v48, v20
	v_fmac_f32_e32 v103, v51, v19
	v_fmac_f32_e32 v102, v50, v22
	ds_read_b128 v[16:19], v60 offset:59392
	v_fmac_f32_e32 v102, v51, v23
	ds_read_b128 v[20:23], v60 offset:63488
	s_waitcnt lgkmcnt(1)
	v_fma_f32 v100, v49, v17, v144
	v_fmac_f32_e32 v100, v48, v16
	v_fmac_f32_e32 v100, v50, v18
	s_waitcnt lgkmcnt(0)
	v_fma_f32 v101, v49, v21, v142
	v_fmac_f32_e32 v101, v48, v20
	v_fmac_f32_e32 v101, v50, v22
	v_fmac_f32_e32 v100, v51, v19
	v_fmac_f32_e32 v101, v51, v23
	v_pk_fma_f32 v[52:53], v[46:47], v[32:33], v[36:37]
	v_pk_mul_f32 v[32:33], v[96:97], v[98:99] op_sel_hi:[1,0]
	ds_read_b128 v[94:97], v60 offset:3072
	v_pk_fma_f32 v[54:55], v[32:33], v[34:35], v[38:39]
	v_cvt_pk_bf16_f32 v32, v52, v53
	v_cvt_pk_bf16_f32 v33, v54, v55
	global_store_dwordx2 v[86:87], v[32:33], off offset:512
	ds_read_b128 v[32:35], v60 offset:7168
	s_waitcnt lgkmcnt(1)
	v_mul_f32_e32 v36, v53, v95
	v_fmac_f32_e32 v36, v52, v94
	v_fmac_f32_e32 v36, v54, v96
	v_fmac_f32_e32 v36, v55, v97
	v_add_f32_e32 v94, v42, v36
	ds_read_b128 v[36:39], v60 offset:11264
	ds_read_b128 v[130:133], v60 offset:15360
	s_waitcnt lgkmcnt(2)
	v_fma_f32 v95, v53, v33, v41
	v_fmac_f32_e32 v95, v52, v32
	v_fmac_f32_e32 v95, v54, v34
	s_waitcnt lgkmcnt(1)
	v_fma_f32 v96, v53, v37, v40
	v_fmac_f32_e32 v96, v52, v36
	v_fmac_f32_e32 v96, v54, v38
	v_fmac_f32_e32 v95, v55, v35
	v_fmac_f32_e32 v96, v55, v39
	ds_read_b128 v[40:43], v60 offset:19456
	s_waitcnt lgkmcnt(1)
	v_fma_f32 v97, v53, v131, v45
	v_fmac_f32_e32 v97, v52, v130
	v_fmac_f32_e32 v97, v54, v132
	v_fmac_f32_e32 v97, v55, v133
	ds_read_b128 v[130:133], v60 offset:23552
	s_waitcnt lgkmcnt(1)
	v_fma_f32 v125, v53, v41, v44
	v_fmac_f32_e32 v125, v52, v40
	v_fmac_f32_e32 v125, v54, v42
	v_fmac_f32_e32 v125, v55, v43
	ds_read_b128 v[134:137], v60 offset:27648
	s_waitcnt lgkmcnt(1)
	v_fma_f32 v124, v53, v131, v124
	v_fmac_f32_e32 v124, v52, v130
	v_fmac_f32_e32 v124, v54, v132
	v_fmac_f32_e32 v124, v55, v133
	ds_read_b128 v[130:133], v60 offset:31744
	s_waitcnt lgkmcnt(1)
	v_fma_f32 v98, v53, v135, v123
	v_fmac_f32_e32 v98, v52, v134
	v_fmac_f32_e32 v98, v54, v136
	v_fmac_f32_e32 v98, v55, v137
	ds_read_b128 v[134:137], v60 offset:35840
	s_waitcnt lgkmcnt(1)
	v_fma_f32 v122, v53, v131, v122
	v_fmac_f32_e32 v122, v52, v130
	v_fmac_f32_e32 v122, v54, v132
	v_fmac_f32_e32 v122, v55, v133
	ds_read_b128 v[130:133], v60 offset:39936
	s_waitcnt lgkmcnt(1)
	v_fma_f32 v111, v53, v135, v111
	v_fmac_f32_e32 v111, v52, v134
	v_fmac_f32_e32 v111, v54, v136
	v_fmac_f32_e32 v111, v55, v137
	ds_read_b128 v[134:137], v60 offset:44032
	s_waitcnt lgkmcnt(1)
	v_fma_f32 v110, v53, v131, v110
	v_fmac_f32_e32 v110, v52, v130
	v_fmac_f32_e32 v110, v54, v132
	v_fmac_f32_e32 v110, v55, v133
	ds_read_b128 v[130:133], v60 offset:48128
	s_waitcnt lgkmcnt(1)
	v_fma_f32 v109, v53, v135, v109
	v_fmac_f32_e32 v109, v52, v134
	v_fmac_f32_e32 v109, v54, v136
	v_fmac_f32_e32 v109, v55, v137
	ds_read_b128 v[134:137], v60 offset:52224
	s_waitcnt lgkmcnt(1)
	v_fma_f32 v108, v53, v131, v108
	v_fmac_f32_e32 v108, v52, v130
	v_fmac_f32_e32 v108, v54, v132
	v_fmac_f32_e32 v108, v55, v133
	ds_read_b128 v[130:133], v60 offset:56320
	s_waitcnt lgkmcnt(1)
	v_fma_f32 v103, v53, v135, v103
	v_fmac_f32_e32 v103, v52, v134
	v_fmac_f32_e32 v103, v54, v136
	v_fmac_f32_e32 v103, v55, v137
	ds_read_b128 v[134:137], v60 offset:60416
	s_waitcnt lgkmcnt(1)
	v_fma_f32 v102, v53, v131, v102
	v_fmac_f32_e32 v102, v52, v130
	v_fmac_f32_e32 v102, v54, v132
	v_fmac_f32_e32 v102, v55, v133
	ds_read_b128 v[130:133], v60 offset:64512
	s_waitcnt lgkmcnt(1)
	v_fma_f32 v123, v53, v135, v100
	v_fmac_f32_e32 v123, v52, v134
	v_fmac_f32_e32 v123, v54, v136
	v_fmac_f32_e32 v123, v55, v137
	s_waitcnt lgkmcnt(0)
	v_fma_f32 v129, v53, v131, v101
	v_fmac_f32_e32 v129, v52, v130
	v_fmac_f32_e32 v129, v54, v132
	v_fmac_f32_e32 v129, v55, v133
	v_mov_b32_e32 v100, v48
	v_mov_b32_e32 v101, v52
	v_mov_b32_e32 v52, v49
	v_mov_b32_e32 v48, v218
	v_mov_b32_e32 v126, v214
	v_mov_b32_e32 v130, v222
	v_mov_b32_e32 v127, v230
	v_mov_b32_e32 v49, v238
	v_pk_mul_f32 v[48:49], v[52:53], v[48:49]
	v_mov_b32_e32 v36, v219
	v_pk_fma_f32 v[48:49], v[100:101], v[126:127], v[48:49]
	v_mov_b32_e32 v126, v50
	v_mov_b32_e32 v127, v54
	v_mov_b32_e32 v131, v242
	v_pk_fma_f32 v[48:49], v[126:127], v[130:131], v[48:49]
	v_mov_b32_e32 v54, v51
	v_mov_b32_e32 v50, v226
	v_mov_b32_e32 v51, v246
	v_mov_b32_e32 v32, v215
	v_mov_b32_e32 v37, v239
	v_pk_mul_f32 v[24:25], v[52:53], v[36:37]
	v_pk_fma_f32 v[48:49], v[54:55], v[50:51], v[48:49]
	v_mov_b32_e32 v33, v231
	v_pk_fma_f32 v[24:25], v[100:101], v[32:33], v[24:25]
	v_mov_b32_e32 v40, v223
	v_add_f32_e32 v16, v107, v48
	v_mov_b32_e32 v41, v243
	v_pk_fma_f32 v[20:21], v[126:127], v[40:41], v[24:25]
	v_mov_b32_e32 v44, v227
	v_add_f32_e32 v28, v16, v49
	v_mov_b32_e32 v45, v247
	v_pk_fma_f32 v[16:17], v[54:55], v[44:45], v[20:21]
	v_mov_b32_e32 v20, v220
	v_add_f32_e32 v16, v105, v16
	v_mov_b32_e32 v21, v240
	v_add_f32_e32 v24, v16, v17
	v_mov_b32_e32 v16, v216
	v_mov_b32_e32 v17, v232
	v_pk_mul_f32 v[20:21], v[52:53], v[20:21]
	v_mov_b32_e32 v38, v221
	v_pk_fma_f32 v[16:17], v[100:101], v[16:17], v[20:21]
	v_mov_b32_e32 v20, v224
	v_mov_b32_e32 v21, v244
	v_pk_fma_f32 v[16:17], v[126:127], v[20:21], v[16:17]
	v_mov_b32_e32 v20, v228
	v_mov_b32_e32 v21, v248
	v_pk_fma_f32 v[16:17], v[54:55], v[20:21], v[16:17]
	v_mov_b32_e32 v34, v217
	v_add_f32_e32 v16, v106, v16
	v_add_f32_e32 v20, v16, v17
	v_mov_b32_e32 v39, v241
	v_pk_mul_f32 v[16:17], v[52:53], v[38:39]
	v_mov_b32_e32 v42, v225
	v_mov_b32_e32 v35, v233
	v_pk_fma_f32 v[16:17], v[100:101], v[34:35], v[16:17]
	v_mov_b32_e32 v46, v229
	v_mov_b32_e32 v43, v245
	v_pk_fma_f32 v[16:17], v[126:127], v[42:43], v[16:17]
	v_mov_b32_e32 v47, v249
	v_pk_fma_f32 v[16:17], v[54:55], v[46:47], v[16:17]
	v_add_f32_e32 v16, v104, v16
	v_add_f32_e32 v22, v16, v17
	v_add_f32_dpp v250, v24, v24 row_mirror row_mask:0xf bank_mask:0xf bound_ctrl:1
	v_add_f32_dpp v94, v94, v94 row_mirror row_mask:0xf bank_mask:0xf bound_ctrl:1
	v_add_f32_dpp v125, v125, v125 row_mirror row_mask:0xf bank_mask:0xf bound_ctrl:1
	v_add_f32_dpp v111, v111, v111 row_mirror row_mask:0xf bank_mask:0xf bound_ctrl:1
	v_add_f32_dpp v103, v103, v103 row_mirror row_mask:0xf bank_mask:0xf bound_ctrl:1
	v_add_f32_dpp v250, v20, v20 row_mirror row_mask:0xf bank_mask:0xc bound_ctrl:1
	v_add_f32_dpp v94, v95, v95 row_mirror row_mask:0xf bank_mask:0xc bound_ctrl:1
	v_add_f32_dpp v125, v124, v124 row_mirror row_mask:0xf bank_mask:0xc bound_ctrl:1
	v_add_f32_dpp v111, v110, v110 row_mirror row_mask:0xf bank_mask:0xc bound_ctrl:1
	v_add_f32_dpp v103, v102, v102 row_mirror row_mask:0xf bank_mask:0xc bound_ctrl:1
	v_add_f32_dpp v251, v28, v28 row_mirror row_mask:0xf bank_mask:0xf bound_ctrl:1
	v_add_f32_dpp v96, v96, v96 row_mirror row_mask:0xf bank_mask:0xf bound_ctrl:1
	v_add_f32_dpp v98, v98, v98 row_mirror row_mask:0xf bank_mask:0xf bound_ctrl:1
	v_add_f32_dpp v109, v109, v109 row_mirror row_mask:0xf bank_mask:0xf bound_ctrl:1
	v_add_f32_dpp v123, v123, v123 row_mirror row_mask:0xf bank_mask:0xf bound_ctrl:1
	v_add_f32_dpp v251, v22, v22 row_mirror row_mask:0xf bank_mask:0xc bound_ctrl:1
	v_add_f32_dpp v96, v97, v97 row_mirror row_mask:0xf bank_mask:0xc bound_ctrl:1
	v_add_f32_dpp v98, v122, v122 row_mirror row_mask:0xf bank_mask:0xc bound_ctrl:1
	v_add_f32_dpp v109, v108, v108 row_mirror row_mask:0xf bank_mask:0xc bound_ctrl:1
	v_add_f32_dpp v123, v129, v129 row_mirror row_mask:0xf bank_mask:0xc bound_ctrl:1
	v_add_f32_dpp v250, v250, v250 row_half_mirror row_mask:0xf bank_mask:0xf bound_ctrl:1
	v_add_f32_dpp v94, v94, v94 row_half_mirror row_mask:0xf bank_mask:0xf bound_ctrl:1
	v_add_f32_dpp v125, v125, v125 row_half_mirror row_mask:0xf bank_mask:0xf bound_ctrl:1
	v_add_f32_dpp v111, v111, v111 row_half_mirror row_mask:0xf bank_mask:0xf bound_ctrl:1
	v_add_f32_dpp v103, v103, v103 row_half_mirror row_mask:0xf bank_mask:0xf bound_ctrl:1
	v_add_f32_dpp v250, v251, v251 row_half_mirror row_mask:0xf bank_mask:0xa bound_ctrl:1
	v_add_f32_dpp v94, v96, v96 row_half_mirror row_mask:0xf bank_mask:0xa bound_ctrl:1
	v_add_f32_dpp v125, v98, v98 row_half_mirror row_mask:0xf bank_mask:0xa bound_ctrl:1
	v_add_f32_dpp v111, v109, v109 row_half_mirror row_mask:0xf bank_mask:0xa bound_ctrl:1
	v_add_f32_dpp v103, v123, v123 row_half_mirror row_mask:0xf bank_mask:0xa bound_ctrl:1
	v_add_f32_dpp v250, v250, v250 quad_perm:[1,0,3,2] row_mask:0xf bank_mask:0xf bound_ctrl:1
	v_add_f32_dpp v94, v94, v94 quad_perm:[1,0,3,2] row_mask:0xf bank_mask:0xf bound_ctrl:1
	v_add_f32_dpp v125, v125, v125 quad_perm:[1,0,3,2] row_mask:0xf bank_mask:0xf bound_ctrl:1
	v_add_f32_dpp v111, v111, v111 quad_perm:[1,0,3,2] row_mask:0xf bank_mask:0xf bound_ctrl:1
	v_add_f32_dpp v103, v103, v103 quad_perm:[1,0,3,2] row_mask:0xf bank_mask:0xf bound_ctrl:1
	v_add_f32_dpp v250, v250, v250 quad_perm:[2,3,0,1] row_mask:0xf bank_mask:0xf bound_ctrl:1
	v_add_f32_dpp v94, v94, v94 quad_perm:[2,3,0,1] row_mask:0xf bank_mask:0xf bound_ctrl:1
	v_add_f32_dpp v125, v125, v125 quad_perm:[2,3,0,1] row_mask:0xf bank_mask:0xf bound_ctrl:1
	v_add_f32_dpp v111, v111, v111 quad_perm:[2,3,0,1] row_mask:0xf bank_mask:0xf bound_ctrl:1
	v_add_f32_dpp v103, v103, v103 quad_perm:[2,3,0,1] row_mask:0xf bank_mask:0xf bound_ctrl:1
	v_readlane_b32 s2, v250, 20
	v_readlane_b32 s10, v250, 52
	v_readlane_b32 s0, v250, 4
	v_readlane_b32 s1, v250, 36
	v_mov_b32_e32 v16, s2
	v_mov_b32_e32 v17, s10
	v_readlane_b32 s2, v250, 16
	v_readlane_b32 s10, v250, 48
	v_pk_add_f32 v[16:17], s[0:1], v[16:17]
	v_readlane_b32 s0, v250, 0
	v_readlane_b32 s1, v250, 32
	v_mov_b32_e32 v18, s2
	v_mov_b32_e32 v19, s10
	v_readlane_b32 s2, v250, 24
	v_readlane_b32 s10, v250, 56
	v_pk_add_f32 v[18:19], s[0:1], v[18:19]
	v_readlane_b32 s0, v250, 8
	v_readlane_b32 s1, v250, 40
	v_mov_b32_e32 v20, s2
	v_mov_b32_e32 v21, s10
	v_pk_add_f32 v[20:21], s[0:1], v[20:21]
	v_mov_b32_e32 v25, v18
	v_add_f32_e32 v26, v20, v21
	v_mov_b32_e32 v18, v17
	v_readlane_b32 s2, v250, 28
	v_readlane_b32 s10, v250, 60
	v_readlane_b32 s0, v250, 12
	v_readlane_b32 s1, v250, 44
	v_mov_b32_e32 v20, s2
	v_mov_b32_e32 v21, s10
	v_pk_add_f32 v[20:21], s[0:1], v[20:21]
	v_add_f32_e32 v27, v20, v21
	v_readlane_b32 s14, v94, 0
	v_readlane_b32 s94, v94, 16
	v_readlane_b32 s15, v94, 32
	v_readlane_b32 s95, v94, 48
	v_readlane_b32 s87, v94, 8
	v_readlane_b32 s91, v94, 24
	v_readlane_b32 s90, v94, 40
	v_readlane_b32 s92, v94, 56
	v_readlane_b32 s65, v94, 4
	v_readlane_b32 s75, v94, 20
	v_readlane_b32 s66, v94, 36
	v_readlane_b32 s78, v94, 52
	v_readlane_b32 s51, v94, 12
	v_readlane_b32 s53, v94, 28
	v_readlane_b32 s52, v94, 44
	v_readlane_b32 s54, v94, 60
	v_readlane_b32 s35, v125, 0
	v_readlane_b32 s37, v125, 16
	v_readlane_b32 s36, v125, 32
	v_readlane_b32 s38, v125, 48
	v_readlane_b32 s23, v125, 8
	v_readlane_b32 s27, v125, 24
	v_readlane_b32 s26, v125, 40
	v_readlane_b32 s93, v125, 56
	v_readlane_b32 s81, v125, 4
	v_readlane_b32 s83, v125, 20
	v_readlane_b32 s82, v125, 36
	v_readlane_b32 s84, v125, 52
	v_readlane_b32 s63, v125, 12
	v_readlane_b32 s67, v125, 28
	v_readlane_b32 s64, v125, 44
	v_readlane_b32 s70, v125, 60
	v_readlane_b32 s59, v111, 0
	v_readlane_b32 s61, v111, 16
	v_readlane_b32 s60, v111, 32
	v_readlane_b32 s62, v111, 48
	v_readlane_b32 s55, v111, 8
	v_readlane_b32 s57, v111, 24
	v_readlane_b32 s56, v111, 40
	v_readlane_b32 s58, v111, 56
	v_readlane_b32 s47, v111, 4
	v_readlane_b32 s49, v111, 20
	v_readlane_b32 s48, v111, 36
	v_readlane_b32 s50, v111, 52
	v_readlane_b32 s43, v111, 12
	v_readlane_b32 s45, v111, 28
	v_readlane_b32 s44, v111, 44
	v_readlane_b32 s46, v111, 60
	v_readlane_b32 s39, v103, 0
	v_readlane_b32 s41, v103, 16
	v_readlane_b32 s40, v103, 32
	v_readlane_b32 s42, v103, 48
	v_readlane_b32 s30, v103, 8
	v_readlane_b32 s33, v103, 24
	v_readlane_b32 s31, v103, 40
	v_readlane_b32 s34, v103, 56
	v_readlane_b32 s28, v103, 4
	v_readlane_b32 s29, v103, 20
	v_readlane_b32 s85, v103, 36
	v_readlane_b32 s86, v103, 52
	v_mov_b32_e32 v24, v16
	v_pk_add_f32 v[16:17], v[24:25], v[18:19]
	v_mov_b32_e32 v20, v178
	v_mov_b32_e32 v21, v179
	v_mov_b32_e32 v22, v180
	v_mov_b32_e32 v23, v181
	v_add_f32_e32 v19, v26, v22
	v_pk_add_f32 v[16:17], v[16:17], v[20:21]
	v_add_f32_e32 v18, v27, v23
	v_cmp_gt_f32_e32 vcc, v17, v16
	v_mov_b32_e32 v22, 0
	v_readlane_b32 s71, v103, 12
	v_cndmask_b32_e32 v20, v16, v17, vcc
	v_cmp_gt_f32_e64 s[12:13], v19, v20
	v_cndmask_b32_e64 v21, 0, 1, vcc
	s_and_b64 s[10:11], s[12:13], exec
	v_cndmask_b32_e64 v20, v20, v19, s[12:13]
	v_cmp_ngt_f32_e64 s[0:1], v18, v20
	v_readfirstlane_b32 s2, v21
	s_cselect_b32 s2, 2, s2
	s_and_b64 s[10:11], s[0:1], exec
	s_cselect_b32 s2, s2, 3
	s_cmp_eq_u32 s2, 0
	s_cselect_b64 s[24:25], -1, 0
	s_cmp_lg_u32 s2, 0
	v_mov_b32_e32 v21, 0
	v_readlane_b32 s79, v103, 28
	v_readlane_b32 s74, v103, 44
	v_readlane_b32 s80, v103, 60
	v_cmp_gt_f32_e64 s[10:11], v18, v20
	s_waitcnt lgkmcnt(0)
	s_cbranch_scc0 .LBB0_1684
	v_cndmask_b32_e64 v23, 0, 1, s[24:25]
	v_cmp_ne_u32_e64 s[14:15], 1, v23
	s_andn2_b64 vcc, exec, s[24:25]
	s_cbranch_vccz .LBB0_1685
